# SiLU / sigmoid quotients in the GEMM epilogues use v_rcp_f32 (denominator >= 1) instead of the scaled division sequence; f32 throughout
# speedup vs baseline: 1.0378x; 1.0062x over previous
;   DI void operator()(const f32x4 (&acc)[2][2][4][2], const pg8::Unit& u, int wr, int wc, int fr, int fq) const {
;     ...
;         if (type == T_SILU) {
; #pragma unroll
;           for (int n = 0; n < 2; ++n)
; #pragma unroll
;             for (int j = 0; j < 4; ++j) { const float a = v1[n][j]; v1[n][j] = a / (1.f + __expf(-a)); const float b = v2[n][j]; v2[n][j] = b / (1.f + __expf(-b)); }
;         }
.LBB0_211:
	s_cmp_eq_u32 s1, 3
	s_cselect_b64 s[14:15], -1, 0
	s_cmp_lg_u32 s1, 3
	s_cbranch_scc1 .LBB0_213
	v_mul_f32_e32 v161, 0xbfb8aa3b, v121
	v_exp_f32_e32 v163, v161
	v_mul_f32_e32 v161, 0xbfb8aa3b, v118
	v_exp_f32_e32 v164, v161
	v_mul_f32_e32 v161, 0xbfb8aa3b, v122
	v_exp_f32_e32 v166, v161
	v_mul_f32_e32 v161, 0xbfb8aa3b, v119
	v_mul_f32_e32 v175, 0xbfb8aa3b, v126
	v_exp_f32_e32 v165, v161
	v_mul_f32_e32 v161, 0xbfb8aa3b, v123
	v_exp_f32_e32 v180, v175
	v_mul_f32_e32 v175, 0xbfb8aa3b, v127
	v_exp_f32_e32 v167, v161
	v_mul_f32_e32 v161, 0xbfb8aa3b, v124
	v_exp_f32_e32 v181, v175
	v_exp_f32_e32 v176, v161
	v_mul_f32_e32 v161, 0xbfb8aa3b, v112
	v_exp_f32_e32 v178, v161
	v_mul_f32_e32 v161, 0xbfb8aa3b, v125
	v_exp_f32_e32 v177, v161
	v_mul_f32_e32 v161, 0xbfb8aa3b, v113
	v_exp_f32_e32 v179, v161
	v_mul_f32_e32 v161, 0xbfb8aa3b, v114
	v_pk_add_f32 v[180:181], v[180:181], 1.0 op_sel_hi:[1,0]
	v_exp_f32_e32 v184, v161
	v_pk_add_f32 v[176:177], v[176:177], 1.0 op_sel_hi:[1,0]
	v_pk_add_f32 v[164:165], v[164:165], 1.0 op_sel_hi:[1,0]
	v_mul_f32_e32 v159, 0xbfb8aa3b, v120
	v_rcp_f32_e32 v161, v181
	s_nop 0
	v_mul_f32_e32 v127, v127, v161
	v_mul_f32_e32 v158, 0xbfb8aa3b, v116
	v_rcp_f32_e32 v161, v180
	s_nop 0
	v_mul_f32_e32 v126, v126, v161
	v_exp_f32_e32 v162, v159
	v_rcp_f32_e32 v161, v177
	s_nop 0
	v_mul_f32_e32 v125, v125, v161
	v_mul_f32_e32 v159, 0xbfb8aa3b, v117
	v_rcp_f32_e32 v161, v176
	s_nop 0
	v_mul_f32_e32 v124, v124, v161
	v_exp_f32_e32 v158, v158
	v_exp_f32_e32 v159, v159
	v_rcp_f32_e32 v161, v165
	s_nop 0
	v_mul_f32_e32 v119, v119, v161
	v_pk_add_f32 v[158:159], v[158:159], 1.0 op_sel_hi:[1,0]
	v_rcp_f32_e32 v161, v164
	s_nop 0
	v_mul_f32_e32 v118, v118, v161
	v_pk_add_f32 v[162:163], v[162:163], 1.0 op_sel_hi:[1,0]
	v_rcp_f32_e32 v161, v159
	s_nop 0
	v_mul_f32_e32 v117, v117, v161
	v_mul_f32_e32 v164, 0xbfb8aa3b, v115
	v_exp_f32_e32 v185, v164
	v_rcp_f32_e32 v159, v158
	s_nop 0
	v_mul_f32_e32 v116, v116, v159
	v_pk_add_f32 v[158:159], v[184:185], 1.0 op_sel_hi:[1,0]
	v_pk_add_f32 v[164:165], v[166:167], 1.0 op_sel_hi:[1,0]
	v_div_scale_f32 v161, s[8:9], v159, v159, v115
	v_rcp_f32_e32 v175, v161
	v_pk_add_f32 v[166:167], v[178:179], 1.0 op_sel_hi:[1,0]
	v_fma_f32 v176, -v161, v175, 1.0
	v_fmac_f32_e32 v175, v176, v175
	v_div_scale_f32 v176, vcc, v115, v159, v115
	v_mul_f32_e32 v177, v176, v175
	v_fma_f32 v178, -v161, v177, v176
	v_fmac_f32_e32 v177, v178, v175
	v_div_scale_f32 v176, s[8:9], v158, v158, v114
	v_rcp_f32_e32 v178, v176
	v_rcp_f32_e32 v161, v159
	s_nop 0
	v_mul_f32_e32 v115, v115, v161
	v_fma_f32 v159, -v176, v178, 1.0
	v_fmac_f32_e32 v178, v159, v178
	v_div_scale_f32 v175, s[8:9], v167, v167, v113
	v_rcp_f32_e32 v176, v175
	v_rcp_f32_e32 v159, v158
	s_nop 0
	v_mul_f32_e32 v114, v114, v159
	v_fma_f32 v158, -v175, v176, 1.0
	v_fmac_f32_e32 v176, v158, v176
	v_div_scale_f32 v161, s[8:9], v166, v166, v112
	v_rcp_f32_e32 v175, v161
	v_rcp_f32_e32 v158, v167
	s_nop 0
	v_mul_f32_e32 v113, v113, v158
	v_fma_f32 v158, -v161, v175, 1.0
	v_fmac_f32_e32 v175, v158, v175
	v_div_scale_f32 v161, s[8:9], v165, v165, v123
	v_rcp_f32_e32 v167, v161
	v_rcp_f32_e32 v158, v166
	s_nop 0
	v_mul_f32_e32 v112, v112, v158
	v_fma_f32 v158, -v161, v167, 1.0
	v_fmac_f32_e32 v167, v158, v167
	v_div_scale_f32 v161, s[8:9], v164, v164, v122
	v_rcp_f32_e32 v166, v161
	v_rcp_f32_e32 v158, v165
	s_nop 0
	v_mul_f32_e32 v123, v123, v158
	v_fma_f32 v158, -v161, v166, 1.0
	v_fmac_f32_e32 v166, v158, v166
	v_div_scale_f32 v161, s[8:9], v163, v163, v121
	v_rcp_f32_e32 v165, v161
	v_rcp_f32_e32 v158, v164
	s_nop 0
	v_mul_f32_e32 v122, v122, v158
	v_fma_f32 v158, -v161, v165, 1.0
	v_fmac_f32_e32 v165, v158, v165
	v_div_scale_f32 v161, s[8:9], v162, v162, v120
	v_rcp_f32_e32 v164, v161
	v_rcp_f32_e32 v158, v163
	s_nop 0
	v_mul_f32_e32 v121, v121, v158
	v_fma_f32 v158, -v161, v164, 1.0
	v_fmac_f32_e32 v164, v158, v164
	v_div_scale_f32 v158, vcc, v120, v162, v120
	v_mul_f32_e32 v159, v158, v164
	v_fma_f32 v163, -v161, v159, v158
	v_rcp_f32_e32 v158, v162
	s_nop 0
	v_mul_f32_e32 v120, v120, v158

;   DI void operator()(const f32x4 (&acc)[2][2][4][2], const pg8::Unit& u, int wr, int wc, int fr, int fq) const {
;     ...
;         if (type == T_SILU) {
; #pragma unroll
;           for (int n = 0; n < 2; ++n)
; #pragma unroll
;             for (int j = 0; j < 4; ++j) { const float a = v1[n][j]; v1[n][j] = a / (1.f + __expf(-a)); const float b = v2[n][j]; v2[n][j] = b / (1.f + __expf(-b)); }
;         }
.LBB0_227:
	v_cndmask_b32_e64 v113, 0, 1, s[14:15]
	v_cmp_ne_u32_e64 s[12:13], 1, v113
	s_andn2_b64 vcc, exec, s[14:15]
	s_cbranch_vccnz .LBB0_229
	v_mul_f32_e32 v113, 0xbfb8aa3b, v100
	v_exp_f32_e32 v114, v113
	v_mul_f32_e32 v113, 0xbfb8aa3b, v104
	v_exp_f32_e32 v116, v113
	v_mul_f32_e32 v113, 0xbfb8aa3b, v101
	v_exp_f32_e32 v115, v113
	v_mul_f32_e32 v113, 0xbfb8aa3b, v105
	v_exp_f32_e32 v117, v113
	v_mul_f32_e32 v113, 0xbfb8aa3b, v102
	v_exp_f32_e32 v118, v113
	v_mul_f32_e32 v113, 0xbfb8aa3b, v106
	v_exp_f32_e32 v120, v113
	v_mul_f32_e32 v113, 0xbfb8aa3b, v103
	v_mul_f32_e32 v125, 0xbfb8aa3b, v110
	v_exp_f32_e32 v119, v113
	v_mul_f32_e32 v113, 0xbfb8aa3b, v107
	v_exp_f32_e32 v126, v125
	v_mul_f32_e32 v125, 0xbfb8aa3b, v111
	v_exp_f32_e32 v121, v113
	v_mul_f32_e32 v113, 0xbfb8aa3b, v108
	v_exp_f32_e32 v127, v125
	v_exp_f32_e32 v122, v113
	v_mul_f32_e32 v113, 0xbfb8aa3b, v96
	v_exp_f32_e32 v124, v113
	v_mul_f32_e32 v113, 0xbfb8aa3b, v109
	v_exp_f32_e32 v123, v113
	v_mul_f32_e32 v113, 0xbfb8aa3b, v97
	v_exp_f32_e32 v125, v113
	v_mul_f32_e32 v113, 0xbfb8aa3b, v98
	v_pk_add_f32 v[126:127], v[126:127], 1.0 op_sel_hi:[1,0]
	v_exp_f32_e32 v160, v113
	v_div_scale_f32 v113, s[2:3], v127, v127, v111
	v_rcp_f32_e32 v161, v113
	v_pk_add_f32 v[122:123], v[122:123], 1.0 op_sel_hi:[1,0]
	v_pk_add_f32 v[118:119], v[118:119], 1.0 op_sel_hi:[1,0]
	v_pk_add_f32 v[114:115], v[114:115], 1.0 op_sel_hi:[1,0]
	v_fma_f32 v162, -v113, v161, 1.0
	v_fmac_f32_e32 v161, v162, v161
	v_div_scale_f32 v162, vcc, v111, v127, v111
	v_mul_f32_e32 v163, v162, v161
	v_fma_f32 v164, -v113, v163, v162
	v_fmac_f32_e32 v163, v164, v161
	v_div_scale_f32 v162, s[2:3], v126, v126, v110
	v_rcp_f32_e32 v164, v162
	v_rcp_f32_e32 v113, v127
	s_nop 0
	v_mul_f32_e32 v111, v111, v113
	v_pk_add_f32 v[116:117], v[116:117], 1.0 op_sel_hi:[1,0]
	v_fma_f32 v113, -v162, v164, 1.0
	v_fmac_f32_e32 v164, v113, v164
	v_div_scale_f32 v161, s[2:3], v123, v123, v109
	v_rcp_f32_e32 v162, v161
	v_rcp_f32_e32 v113, v126
	s_nop 0
	v_mul_f32_e32 v110, v110, v113
	v_fma_f32 v113, -v161, v162, 1.0
	v_fmac_f32_e32 v162, v113, v162
	v_rcp_f32_e32 v113, v123
	s_nop 0
	v_mul_f32_e32 v109, v109, v113
	v_div_scale_f32 v126, s[2:3], v119, v119, v103
	v_rcp_f32_e32 v127, v126
	v_rcp_f32_e32 v113, v122
	s_nop 0
	v_mul_f32_e32 v108, v108, v113
	v_fma_f32 v113, -v126, v127, 1.0
	v_fmac_f32_e32 v127, v113, v127
	v_div_scale_f32 v123, s[2:3], v118, v118, v102
	v_rcp_f32_e32 v126, v123
	v_rcp_f32_e32 v113, v119
	s_nop 0
	v_mul_f32_e32 v103, v103, v113
	v_fma_f32 v113, -v123, v126, 1.0
	v_fmac_f32_e32 v126, v113, v126
	v_rcp_f32_e32 v113, v118
	s_nop 0
	v_mul_f32_e32 v102, v102, v113
	v_rcp_f32_e32 v113, v115
	s_nop 0
	v_mul_f32_e32 v101, v101, v113
	v_mul_f32_e32 v118, 0xbfb8aa3b, v99
	v_exp_f32_e32 v161, v118
	v_rcp_f32_e32 v113, v114
	s_nop 0
	v_mul_f32_e32 v100, v100, v113
	v_pk_add_f32 v[114:115], v[160:161], 1.0 op_sel_hi:[1,0]
	v_pk_add_f32 v[118:119], v[120:121], 1.0 op_sel_hi:[1,0]
	v_div_scale_f32 v113, s[2:3], v115, v115, v99
	v_rcp_f32_e32 v122, v113
	v_pk_add_f32 v[120:121], v[124:125], 1.0 op_sel_hi:[1,0]
	v_fma_f32 v123, -v113, v122, 1.0
	v_fmac_f32_e32 v122, v123, v122
	v_div_scale_f32 v123, vcc, v99, v115, v99
	v_mul_f32_e32 v124, v123, v122
	v_fma_f32 v125, -v113, v124, v123
	v_fmac_f32_e32 v124, v125, v122
	v_div_scale_f32 v123, s[2:3], v114, v114, v98
	v_rcp_f32_e32 v125, v123
	v_rcp_f32_e32 v113, v115
	s_nop 0
	v_mul_f32_e32 v99, v99, v113
	v_fma_f32 v113, -v123, v125, 1.0
	v_fmac_f32_e32 v125, v113, v125
	v_div_scale_f32 v122, s[2:3], v121, v121, v97
	v_rcp_f32_e32 v123, v122
	v_rcp_f32_e32 v113, v114
	s_nop 0
	v_mul_f32_e32 v98, v98, v113
	v_fma_f32 v113, -v122, v123, 1.0
	v_fmac_f32_e32 v123, v113, v123
	v_div_scale_f32 v115, s[2:3], v120, v120, v96
	v_rcp_f32_e32 v122, v115
	v_rcp_f32_e32 v113, v121
	s_nop 0
	v_mul_f32_e32 v97, v97, v113
	v_fma_f32 v113, -v115, v122, 1.0
	v_fmac_f32_e32 v122, v113, v122
	v_div_scale_f32 v115, s[2:3], v119, v119, v107
	v_rcp_f32_e32 v121, v115
	v_rcp_f32_e32 v113, v120
	s_nop 0
	v_mul_f32_e32 v96, v96, v113
	v_fma_f32 v113, -v115, v121, 1.0
	v_fmac_f32_e32 v121, v113, v121
	v_div_scale_f32 v115, s[2:3], v118, v118, v106
	v_rcp_f32_e32 v120, v115
	v_rcp_f32_e32 v113, v119
	s_nop 0
	v_mul_f32_e32 v107, v107, v113
	v_fma_f32 v113, -v115, v120, 1.0
	v_fmac_f32_e32 v120, v113, v120
	v_div_scale_f32 v115, s[2:3], v117, v117, v105
	v_rcp_f32_e32 v119, v115
	v_rcp_f32_e32 v113, v118
	s_nop 0
	v_mul_f32_e32 v106, v106, v113
	v_fma_f32 v113, -v115, v119, 1.0
	v_fmac_f32_e32 v119, v113, v119
	v_div_scale_f32 v115, s[2:3], v116, v116, v104
	v_rcp_f32_e32 v118, v115
	v_rcp_f32_e32 v113, v117
	s_nop 0
	v_mul_f32_e32 v105, v105, v113
	v_fma_f32 v113, -v115, v118, 1.0
	v_fmac_f32_e32 v118, v113, v118
	v_div_scale_f32 v113, vcc, v104, v116, v104
	v_mul_f32_e32 v114, v113, v118
	v_fma_f32 v117, -v115, v114, v113
	v_rcp_f32_e32 v113, v116
	s_nop 0
	v_mul_f32_e32 v104, v104, v113

;   DI void operator()(const f32x4 (&acc)[2][2][4][2], const pg8::Unit& u, int wr, int wc, int fr, int fq) const {
;     ...
;         if (type == T_SILU) {
; #pragma unroll
;           for (int n = 0; n < 2; ++n)
; #pragma unroll
;             for (int j = 0; j < 4; ++j) { const float a = v1[n][j]; v1[n][j] = a / (1.f + __expf(-a)); const float b = v2[n][j]; v2[n][j] = b / (1.f + __expf(-b)); }
;         }
.LBB0_246:
	v_mul_f32_e32 v97, 0xbfb8aa3b, v84
	v_exp_f32_e32 v98, v97
	v_mul_f32_e32 v97, 0xbfb8aa3b, v88
	v_exp_f32_e32 v100, v97
	v_mul_f32_e32 v97, 0xbfb8aa3b, v85
	v_exp_f32_e32 v99, v97
	v_mul_f32_e32 v97, 0xbfb8aa3b, v89
	v_exp_f32_e32 v101, v97
	v_mul_f32_e32 v97, 0xbfb8aa3b, v86
	v_exp_f32_e32 v102, v97
	v_mul_f32_e32 v97, 0xbfb8aa3b, v90
	v_exp_f32_e32 v104, v97
	v_mul_f32_e32 v97, 0xbfb8aa3b, v87
	v_mul_f32_e32 v109, 0xbfb8aa3b, v94
	v_exp_f32_e32 v103, v97
	v_mul_f32_e32 v97, 0xbfb8aa3b, v91
	v_exp_f32_e32 v110, v109
	v_mul_f32_e32 v109, 0xbfb8aa3b, v95
	v_exp_f32_e32 v105, v97
	v_mul_f32_e32 v97, 0xbfb8aa3b, v92
	v_exp_f32_e32 v111, v109
	v_exp_f32_e32 v106, v97
	v_mul_f32_e32 v97, 0xbfb8aa3b, v80
	v_exp_f32_e32 v108, v97
	v_mul_f32_e32 v97, 0xbfb8aa3b, v93
	v_exp_f32_e32 v107, v97
	v_mul_f32_e32 v97, 0xbfb8aa3b, v81
	v_exp_f32_e32 v109, v97
	v_mul_f32_e32 v97, 0xbfb8aa3b, v82
	v_pk_add_f32 v[110:111], v[110:111], 1.0 op_sel_hi:[1,0]
	v_exp_f32_e32 v112, v97
	v_pk_add_f32 v[106:107], v[106:107], 1.0 op_sel_hi:[1,0]
	v_pk_add_f32 v[102:103], v[102:103], 1.0 op_sel_hi:[1,0]
	v_pk_add_f32 v[98:99], v[98:99], 1.0 op_sel_hi:[1,0]
	v_div_scale_f32 v114, s[0:1], v110, v110, v94
	v_rcp_f32_e32 v116, v114
	v_rcp_f32_e32 v97, v111
	s_nop 0
	v_mul_f32_e32 v95, v95, v97
	v_pk_add_f32 v[100:101], v[100:101], 1.0 op_sel_hi:[1,0]
	v_fma_f32 v97, -v114, v116, 1.0
	v_fmac_f32_e32 v116, v97, v116
	v_rcp_f32_e32 v97, v110
	s_nop 0
	v_mul_f32_e32 v94, v94, v97
	v_rcp_f32_e32 v97, v107
	s_nop 0
	v_mul_f32_e32 v93, v93, v97
	v_rcp_f32_e32 v97, v106
	s_nop 0
	v_mul_f32_e32 v92, v92, v97
	v_rcp_f32_e32 v97, v103
	s_nop 0
	v_mul_f32_e32 v87, v87, v97
	v_rcp_f32_e32 v97, v102
	s_nop 0
	v_mul_f32_e32 v86, v86, v97
	v_rcp_f32_e32 v97, v99
	s_nop 0
	v_mul_f32_e32 v85, v85, v97
	v_mul_f32_e32 v102, 0xbfb8aa3b, v83
	v_exp_f32_e32 v113, v102
	v_rcp_f32_e32 v97, v98
	s_nop 0
	v_mul_f32_e32 v84, v84, v97
	v_pk_add_f32 v[98:99], v[112:113], 1.0 op_sel_hi:[1,0]
	v_pk_add_f32 v[102:103], v[104:105], 1.0 op_sel_hi:[1,0]
	v_pk_add_f32 v[104:105], v[108:109], 1.0 op_sel_hi:[1,0]
	v_rcp_f32_e32 v97, v99
	s_nop 0
	v_mul_f32_e32 v83, v83, v97
	v_rcp_f32_e32 v97, v98
	s_nop 0
	v_mul_f32_e32 v82, v82, v97
	v_rcp_f32_e32 v97, v105
	s_nop 0
	v_mul_f32_e32 v81, v81, v97
	v_rcp_f32_e32 v97, v104
	s_nop 0
	v_mul_f32_e32 v80, v80, v97
	v_rcp_f32_e32 v97, v103
	s_nop 0
	v_mul_f32_e32 v91, v91, v97
	v_rcp_f32_e32 v97, v102
	s_nop 0
	v_mul_f32_e32 v90, v90, v97
	v_rcp_f32_e32 v97, v101
	s_nop 0
	v_mul_f32_e32 v89, v89, v97
	v_rcp_f32_e32 v97, v100
	s_nop 0
	v_mul_f32_e32 v88, v88, v97
	s_and_b64 vcc, exec, s[14:15]
	s_mov_b64 s[0:1], -1
	s_cbranch_vccnz .LBB0_243

;   DI void operator()(const f32x4 (&acc)[2][2][4][2], const pg8::Unit& u, int wr, int wc, int fr, int fq) const {
;     ...
;         if (type == T_SILU) {
; #pragma unroll
;           for (int n = 0; n < 2; ++n)
; #pragma unroll
;             for (int j = 0; j < 4; ++j) { const float a = v1[n][j]; v1[n][j] = a / (1.f + __expf(-a)); const float b = v2[n][j]; v2[n][j] = b / (1.f + __expf(-b)); }
;         }
.LBB0_262:
	v_mul_f32_e32 v81, 0xbfb8aa3b, v68
	v_exp_f32_e32 v82, v81
	v_mul_f32_e32 v81, 0xbfb8aa3b, v72
	v_exp_f32_e32 v84, v81
	v_mul_f32_e32 v81, 0xbfb8aa3b, v69
	v_exp_f32_e32 v83, v81
	v_mul_f32_e32 v81, 0xbfb8aa3b, v73
	v_exp_f32_e32 v85, v81
	v_mul_f32_e32 v81, 0xbfb8aa3b, v70
	v_exp_f32_e32 v86, v81
	v_mul_f32_e32 v81, 0xbfb8aa3b, v74
	v_exp_f32_e32 v88, v81
	v_mul_f32_e32 v81, 0xbfb8aa3b, v71
	v_mul_f32_e32 v93, 0xbfb8aa3b, v78
	v_exp_f32_e32 v87, v81
	v_mul_f32_e32 v81, 0xbfb8aa3b, v75
	v_exp_f32_e32 v94, v93
	v_mul_f32_e32 v93, 0xbfb8aa3b, v79
	v_exp_f32_e32 v89, v81
	v_mul_f32_e32 v81, 0xbfb8aa3b, v76
	v_exp_f32_e32 v95, v93
	v_exp_f32_e32 v90, v81
	v_mul_f32_e32 v81, 0xbfb8aa3b, v64
	v_exp_f32_e32 v92, v81
	v_mul_f32_e32 v81, 0xbfb8aa3b, v77
	v_exp_f32_e32 v91, v81
	v_mul_f32_e32 v81, 0xbfb8aa3b, v65
	v_exp_f32_e32 v93, v81
	v_mul_f32_e32 v81, 0xbfb8aa3b, v66
	v_pk_add_f32 v[94:95], v[94:95], 1.0 op_sel_hi:[1,0]
	v_exp_f32_e32 v96, v81
	v_pk_add_f32 v[90:91], v[90:91], 1.0 op_sel_hi:[1,0]
	v_pk_add_f32 v[86:87], v[86:87], 1.0 op_sel_hi:[1,0]
	v_pk_add_f32 v[82:83], v[82:83], 1.0 op_sel_hi:[1,0]
	v_rcp_f32_e32 v81, v95
	s_nop 0
	v_mul_f32_e32 v79, v79, v81
	v_pk_add_f32 v[84:85], v[84:85], 1.0 op_sel_hi:[1,0]
	v_rcp_f32_e32 v81, v94
	s_nop 0
	v_mul_f32_e32 v78, v78, v81
	v_rcp_f32_e32 v81, v91
	s_nop 0
	v_mul_f32_e32 v77, v77, v81
	v_rcp_f32_e32 v81, v90
	s_nop 0
	v_mul_f32_e32 v76, v76, v81
	v_rcp_f32_e32 v81, v87
	s_nop 0
	v_mul_f32_e32 v71, v71, v81
	v_rcp_f32_e32 v81, v86
	s_nop 0
	v_mul_f32_e32 v70, v70, v81
	v_rcp_f32_e32 v81, v83
	s_nop 0
	v_mul_f32_e32 v69, v69, v81
	v_mul_f32_e32 v86, 0xbfb8aa3b, v67
	v_exp_f32_e32 v97, v86
	v_rcp_f32_e32 v81, v82
	s_nop 0
	v_mul_f32_e32 v68, v68, v81
	v_pk_add_f32 v[82:83], v[96:97], 1.0 op_sel_hi:[1,0]
	v_pk_add_f32 v[86:87], v[88:89], 1.0 op_sel_hi:[1,0]
	v_pk_add_f32 v[88:89], v[92:93], 1.0 op_sel_hi:[1,0]
	v_rcp_f32_e32 v81, v83
	s_nop 0
	v_mul_f32_e32 v67, v67, v81
	v_rcp_f32_e32 v81, v82
	s_nop 0
	v_mul_f32_e32 v66, v66, v81
	v_rcp_f32_e32 v81, v89
	s_nop 0
	v_mul_f32_e32 v65, v65, v81
	v_rcp_f32_e32 v81, v88
	s_nop 0
	v_mul_f32_e32 v64, v64, v81
	v_rcp_f32_e32 v81, v87
	s_nop 0
	v_mul_f32_e32 v75, v75, v81
	v_rcp_f32_e32 v81, v86
	s_nop 0
	v_mul_f32_e32 v74, v74, v81
	v_rcp_f32_e32 v81, v85
	s_nop 0
	v_mul_f32_e32 v73, v73, v81
	v_rcp_f32_e32 v81, v84
	s_nop 0
	v_mul_f32_e32 v72, v72, v81
	s_and_b64 vcc, exec, s[14:15]
	s_mov_b64 s[0:1], -1
	s_cbranch_vccnz .LBB0_259

;   DI void operator()(const f32x4 (&acc)[2][2][4][2], const pg8::Unit& u, int wr, int wc, int fr, int fq) const {
;     ...
;         if (type == T_SILU) {
; #pragma unroll
;           for (int n = 0; n < 2; ++n)
; #pragma unroll
;             for (int j = 0; j < 4; ++j) { const float a = v1[n][j]; v1[n][j] = a / (1.f + __expf(-a)); const float b = v2[n][j]; v2[n][j] = b / (1.f + __expf(-b)); }
;         }
.LBB0_278:
	v_mul_f32_e32 v65, 0xbfb8aa3b, v52
	v_exp_f32_e32 v66, v65
	v_mul_f32_e32 v65, 0xbfb8aa3b, v56
	v_exp_f32_e32 v68, v65
	v_mul_f32_e32 v65, 0xbfb8aa3b, v53
	v_exp_f32_e32 v67, v65
	v_mul_f32_e32 v65, 0xbfb8aa3b, v57
	v_exp_f32_e32 v69, v65
	v_mul_f32_e32 v65, 0xbfb8aa3b, v54
	v_exp_f32_e32 v70, v65
	v_mul_f32_e32 v65, 0xbfb8aa3b, v58
	v_exp_f32_e32 v72, v65
	v_mul_f32_e32 v65, 0xbfb8aa3b, v55
	v_mul_f32_e32 v77, 0xbfb8aa3b, v62
	v_exp_f32_e32 v71, v65
	v_mul_f32_e32 v65, 0xbfb8aa3b, v59
	v_exp_f32_e32 v78, v77
	v_mul_f32_e32 v77, 0xbfb8aa3b, v63
	v_exp_f32_e32 v73, v65
	v_mul_f32_e32 v65, 0xbfb8aa3b, v60
	v_exp_f32_e32 v79, v77
	v_exp_f32_e32 v74, v65
	v_mul_f32_e32 v65, 0xbfb8aa3b, v48
	v_exp_f32_e32 v76, v65
	v_mul_f32_e32 v65, 0xbfb8aa3b, v61
	v_exp_f32_e32 v75, v65
	v_mul_f32_e32 v65, 0xbfb8aa3b, v49
	v_exp_f32_e32 v77, v65
	v_mul_f32_e32 v65, 0xbfb8aa3b, v50
	v_pk_add_f32 v[78:79], v[78:79], 1.0 op_sel_hi:[1,0]
	v_exp_f32_e32 v80, v65
	v_pk_add_f32 v[74:75], v[74:75], 1.0 op_sel_hi:[1,0]
	v_pk_add_f32 v[70:71], v[70:71], 1.0 op_sel_hi:[1,0]
	v_pk_add_f32 v[66:67], v[66:67], 1.0 op_sel_hi:[1,0]
	v_rcp_f32_e32 v65, v79
	s_nop 0
	v_mul_f32_e32 v63, v63, v65
	v_pk_add_f32 v[68:69], v[68:69], 1.0 op_sel_hi:[1,0]
	v_rcp_f32_e32 v65, v78
	s_nop 0
	v_mul_f32_e32 v62, v62, v65
	v_rcp_f32_e32 v65, v75
	s_nop 0
	v_mul_f32_e32 v61, v61, v65
	v_rcp_f32_e32 v65, v74
	s_nop 0
	v_mul_f32_e32 v60, v60, v65
	v_rcp_f32_e32 v65, v71
	s_nop 0
	v_mul_f32_e32 v55, v55, v65
	v_rcp_f32_e32 v65, v70
	s_nop 0
	v_mul_f32_e32 v54, v54, v65
	v_rcp_f32_e32 v65, v67
	s_nop 0
	v_mul_f32_e32 v53, v53, v65
	v_mul_f32_e32 v70, 0xbfb8aa3b, v51
	v_exp_f32_e32 v81, v70
	v_rcp_f32_e32 v65, v66
	s_nop 0
	v_mul_f32_e32 v52, v52, v65
	v_pk_add_f32 v[66:67], v[80:81], 1.0 op_sel_hi:[1,0]
	v_pk_add_f32 v[70:71], v[72:73], 1.0 op_sel_hi:[1,0]
	v_pk_add_f32 v[72:73], v[76:77], 1.0 op_sel_hi:[1,0]
	v_rcp_f32_e32 v65, v67
	s_nop 0
	v_mul_f32_e32 v51, v51, v65
	v_rcp_f32_e32 v65, v66
	s_nop 0
	v_mul_f32_e32 v50, v50, v65
	v_rcp_f32_e32 v65, v73
	s_nop 0
	v_mul_f32_e32 v49, v49, v65
	v_rcp_f32_e32 v65, v72
	s_nop 0
	v_mul_f32_e32 v48, v48, v65
	v_rcp_f32_e32 v65, v71
	s_nop 0
	v_mul_f32_e32 v59, v59, v65
	v_rcp_f32_e32 v65, v70
	s_nop 0
	v_mul_f32_e32 v58, v58, v65
	v_rcp_f32_e32 v65, v69
	s_nop 0
	v_mul_f32_e32 v57, v57, v65
	v_rcp_f32_e32 v65, v68
	s_nop 0
	v_mul_f32_e32 v56, v56, v65
	s_and_b64 vcc, exec, s[14:15]
	s_mov_b64 s[0:1], -1
	s_cbranch_vccnz .LBB0_275

;   DI void operator()(const f32x4 (&acc)[2][2][4][2], const pg8::Unit& u, int wr, int wc, int fr, int fq) const {
;     ...
;         if (type == T_SILU) {
; #pragma unroll
;           for (int n = 0; n < 2; ++n)
; #pragma unroll
;             for (int j = 0; j < 4; ++j) { const float a = v1[n][j]; v1[n][j] = a / (1.f + __expf(-a)); const float b = v2[n][j]; v2[n][j] = b / (1.f + __expf(-b)); }
;         }
.LBB0_294:
	v_mul_f32_e32 v49, 0xbfb8aa3b, v36
	v_exp_f32_e32 v50, v49
	v_mul_f32_e32 v49, 0xbfb8aa3b, v40
	v_exp_f32_e32 v52, v49
	v_mul_f32_e32 v49, 0xbfb8aa3b, v37
	v_exp_f32_e32 v51, v49
	v_mul_f32_e32 v49, 0xbfb8aa3b, v41
	v_exp_f32_e32 v53, v49
	v_mul_f32_e32 v49, 0xbfb8aa3b, v38
	v_exp_f32_e32 v54, v49
	v_mul_f32_e32 v49, 0xbfb8aa3b, v42
	v_exp_f32_e32 v56, v49
	v_mul_f32_e32 v49, 0xbfb8aa3b, v39
	v_mul_f32_e32 v61, 0xbfb8aa3b, v46
	v_exp_f32_e32 v55, v49
	v_mul_f32_e32 v49, 0xbfb8aa3b, v43
	v_exp_f32_e32 v62, v61
	v_mul_f32_e32 v61, 0xbfb8aa3b, v47
	v_exp_f32_e32 v57, v49
	v_mul_f32_e32 v49, 0xbfb8aa3b, v44
	v_exp_f32_e32 v63, v61
	v_exp_f32_e32 v58, v49
	v_mul_f32_e32 v49, 0xbfb8aa3b, v32
	v_exp_f32_e32 v60, v49
	v_mul_f32_e32 v49, 0xbfb8aa3b, v45
	v_exp_f32_e32 v59, v49
	v_mul_f32_e32 v49, 0xbfb8aa3b, v33
	v_exp_f32_e32 v61, v49
	v_mul_f32_e32 v49, 0xbfb8aa3b, v34
	v_pk_add_f32 v[62:63], v[62:63], 1.0 op_sel_hi:[1,0]
	v_exp_f32_e32 v64, v49
	v_pk_add_f32 v[58:59], v[58:59], 1.0 op_sel_hi:[1,0]
	v_pk_add_f32 v[54:55], v[54:55], 1.0 op_sel_hi:[1,0]
	v_pk_add_f32 v[50:51], v[50:51], 1.0 op_sel_hi:[1,0]
	v_rcp_f32_e32 v49, v63
	s_nop 0
	v_mul_f32_e32 v47, v47, v49
	v_pk_add_f32 v[52:53], v[52:53], 1.0 op_sel_hi:[1,0]
	v_rcp_f32_e32 v49, v62
	s_nop 0
	v_mul_f32_e32 v46, v46, v49
	v_rcp_f32_e32 v49, v59
	s_nop 0
	v_mul_f32_e32 v45, v45, v49
	v_rcp_f32_e32 v49, v58
	s_nop 0
	v_mul_f32_e32 v44, v44, v49
	v_rcp_f32_e32 v49, v55
	s_nop 0
	v_mul_f32_e32 v39, v39, v49
	v_rcp_f32_e32 v49, v54
	s_nop 0
	v_mul_f32_e32 v38, v38, v49
	v_rcp_f32_e32 v49, v51
	s_nop 0
	v_mul_f32_e32 v37, v37, v49
	v_mul_f32_e32 v54, 0xbfb8aa3b, v35
	v_exp_f32_e32 v65, v54
	v_rcp_f32_e32 v49, v50
	s_nop 0
	v_mul_f32_e32 v36, v36, v49
	v_pk_add_f32 v[50:51], v[64:65], 1.0 op_sel_hi:[1,0]
	v_pk_add_f32 v[54:55], v[56:57], 1.0 op_sel_hi:[1,0]
	v_pk_add_f32 v[56:57], v[60:61], 1.0 op_sel_hi:[1,0]
	v_rcp_f32_e32 v49, v51
	s_nop 0
	v_mul_f32_e32 v35, v35, v49
	v_rcp_f32_e32 v49, v50
	s_nop 0
	v_mul_f32_e32 v34, v34, v49
	v_rcp_f32_e32 v49, v57
	s_nop 0
	v_mul_f32_e32 v33, v33, v49
	v_rcp_f32_e32 v49, v56
	s_nop 0
	v_mul_f32_e32 v32, v32, v49
	v_rcp_f32_e32 v49, v55
	s_nop 0
	v_mul_f32_e32 v43, v43, v49
	v_rcp_f32_e32 v49, v54
	s_nop 0
	v_mul_f32_e32 v42, v42, v49
	v_rcp_f32_e32 v49, v53
	s_nop 0
	v_mul_f32_e32 v41, v41, v49
	v_rcp_f32_e32 v49, v52
	s_nop 0
	v_mul_f32_e32 v40, v40, v49
	s_and_b64 vcc, exec, s[14:15]
	s_mov_b64 s[0:1], -1
	s_cbranch_vccnz .LBB0_291

;   DI void operator()(const f32x4 (&acc)[2][2][4][2], const pg8::Unit& u, int wr, int wc, int fr, int fq) const {
;     ...
;         if (type == T_SILU) {
; #pragma unroll
;           for (int n = 0; n < 2; ++n)
; #pragma unroll
;             for (int j = 0; j < 4; ++j) { const float a = v1[n][j]; v1[n][j] = a / (1.f + __expf(-a)); const float b = v2[n][j]; v2[n][j] = b / (1.f + __expf(-b)); }
;         }
.LBB0_310:
	v_mul_f32_e32 v33, 0xbfb8aa3b, v20
	v_exp_f32_e32 v34, v33
	v_mul_f32_e32 v33, 0xbfb8aa3b, v24
	v_exp_f32_e32 v36, v33
	v_mul_f32_e32 v33, 0xbfb8aa3b, v21
	v_exp_f32_e32 v35, v33
	v_mul_f32_e32 v33, 0xbfb8aa3b, v25
	v_exp_f32_e32 v37, v33
	v_mul_f32_e32 v33, 0xbfb8aa3b, v22
	v_exp_f32_e32 v38, v33
	v_mul_f32_e32 v33, 0xbfb8aa3b, v26
	v_exp_f32_e32 v40, v33
	v_mul_f32_e32 v33, 0xbfb8aa3b, v23
	v_mul_f32_e32 v45, 0xbfb8aa3b, v30
	v_exp_f32_e32 v39, v33
	v_mul_f32_e32 v33, 0xbfb8aa3b, v27
	v_exp_f32_e32 v46, v45
	v_mul_f32_e32 v45, 0xbfb8aa3b, v31
	v_exp_f32_e32 v41, v33
	v_mul_f32_e32 v33, 0xbfb8aa3b, v28
	v_exp_f32_e32 v47, v45
	v_exp_f32_e32 v42, v33
	v_mul_f32_e32 v33, 0xbfb8aa3b, v16
	v_exp_f32_e32 v44, v33
	v_mul_f32_e32 v33, 0xbfb8aa3b, v29
	v_exp_f32_e32 v43, v33
	v_mul_f32_e32 v33, 0xbfb8aa3b, v17
	v_exp_f32_e32 v45, v33
	v_mul_f32_e32 v33, 0xbfb8aa3b, v18
	v_pk_add_f32 v[46:47], v[46:47], 1.0 op_sel_hi:[1,0]
	v_exp_f32_e32 v48, v33
	v_pk_add_f32 v[42:43], v[42:43], 1.0 op_sel_hi:[1,0]
	v_pk_add_f32 v[38:39], v[38:39], 1.0 op_sel_hi:[1,0]
	v_pk_add_f32 v[34:35], v[34:35], 1.0 op_sel_hi:[1,0]
	v_rcp_f32_e32 v33, v47
	s_nop 0
	v_mul_f32_e32 v31, v31, v33
	v_pk_add_f32 v[36:37], v[36:37], 1.0 op_sel_hi:[1,0]
	v_rcp_f32_e32 v33, v46
	s_nop 0
	v_mul_f32_e32 v30, v30, v33
	v_rcp_f32_e32 v33, v43
	s_nop 0
	v_mul_f32_e32 v29, v29, v33
	v_rcp_f32_e32 v33, v42
	s_nop 0
	v_mul_f32_e32 v28, v28, v33
	v_rcp_f32_e32 v33, v39
	s_nop 0
	v_mul_f32_e32 v23, v23, v33
	v_rcp_f32_e32 v33, v38
	s_nop 0
	v_mul_f32_e32 v22, v22, v33
	v_rcp_f32_e32 v33, v35
	s_nop 0
	v_mul_f32_e32 v21, v21, v33
	v_mul_f32_e32 v38, 0xbfb8aa3b, v19
	v_exp_f32_e32 v49, v38
	v_rcp_f32_e32 v33, v34
	s_nop 0
	v_mul_f32_e32 v20, v20, v33
	v_pk_add_f32 v[34:35], v[48:49], 1.0 op_sel_hi:[1,0]
	v_pk_add_f32 v[38:39], v[40:41], 1.0 op_sel_hi:[1,0]
	v_pk_add_f32 v[40:41], v[44:45], 1.0 op_sel_hi:[1,0]
	v_rcp_f32_e32 v33, v35
	s_nop 0
	v_mul_f32_e32 v19, v19, v33
	v_rcp_f32_e32 v33, v34
	s_nop 0
	v_mul_f32_e32 v18, v18, v33
	v_rcp_f32_e32 v33, v41
	s_nop 0
	v_mul_f32_e32 v17, v17, v33
	v_rcp_f32_e32 v33, v40
	s_nop 0
	v_mul_f32_e32 v16, v16, v33
	v_rcp_f32_e32 v33, v39
	s_nop 0
	v_mul_f32_e32 v27, v27, v33
	v_rcp_f32_e32 v33, v38
	s_nop 0
	v_mul_f32_e32 v26, v26, v33
	v_rcp_f32_e32 v33, v37
	s_nop 0
	v_mul_f32_e32 v25, v25, v33
	v_rcp_f32_e32 v33, v36
	s_nop 0
	v_mul_f32_e32 v24, v24, v33
	s_and_b64 vcc, exec, s[14:15]
	s_mov_b64 s[0:1], -1
	s_cbranch_vccnz .LBB0_307

;   DI void operator()(const f32x4 (&acc)[2][2][4][2], const pg8::Unit& u, int wr, int wc, int fr, int fq) const {
;     ...
;         if (type == T_SILU) {
; #pragma unroll
;           for (int n = 0; n < 2; ++n)
; #pragma unroll
;             for (int j = 0; j < 4; ++j) { const float a = v1[n][j]; v1[n][j] = a / (1.f + __expf(-a)); const float b = v2[n][j]; v2[n][j] = b / (1.f + __expf(-b)); }
;         }
.LBB0_326:
	v_mul_f32_e32 v17, 0xbfb8aa3b, v4
	v_exp_f32_e32 v18, v17
	v_mul_f32_e32 v17, 0xbfb8aa3b, v8
	v_exp_f32_e32 v20, v17
	v_mul_f32_e32 v17, 0xbfb8aa3b, v5
	v_exp_f32_e32 v19, v17
	v_mul_f32_e32 v17, 0xbfb8aa3b, v9
	v_exp_f32_e32 v21, v17
	v_mul_f32_e32 v17, 0xbfb8aa3b, v6
	v_exp_f32_e32 v22, v17
	v_mul_f32_e32 v17, 0xbfb8aa3b, v10
	v_exp_f32_e32 v24, v17
	v_mul_f32_e32 v17, 0xbfb8aa3b, v7
	v_mul_f32_e32 v29, 0xbfb8aa3b, v14
	v_exp_f32_e32 v23, v17
	v_mul_f32_e32 v17, 0xbfb8aa3b, v11
	v_exp_f32_e32 v30, v29
	v_mul_f32_e32 v29, 0xbfb8aa3b, v15
	v_exp_f32_e32 v25, v17
	v_mul_f32_e32 v17, 0xbfb8aa3b, v12
	v_exp_f32_e32 v31, v29
	v_exp_f32_e32 v26, v17
	v_mul_f32_e32 v17, 0xbfb8aa3b, v0
	v_exp_f32_e32 v28, v17
	v_mul_f32_e32 v17, 0xbfb8aa3b, v13
	v_exp_f32_e32 v27, v17
	v_mul_f32_e32 v17, 0xbfb8aa3b, v1
	v_exp_f32_e32 v29, v17
	v_mul_f32_e32 v17, 0xbfb8aa3b, v2
	v_pk_add_f32 v[30:31], v[30:31], 1.0 op_sel_hi:[1,0]
	v_exp_f32_e32 v32, v17
	v_pk_add_f32 v[26:27], v[26:27], 1.0 op_sel_hi:[1,0]
	v_pk_add_f32 v[22:23], v[22:23], 1.0 op_sel_hi:[1,0]
	v_pk_add_f32 v[18:19], v[18:19], 1.0 op_sel_hi:[1,0]
	v_rcp_f32_e32 v17, v31
	s_nop 0
	v_mul_f32_e32 v15, v15, v17
	v_pk_add_f32 v[20:21], v[20:21], 1.0 op_sel_hi:[1,0]
	v_rcp_f32_e32 v17, v30
	s_nop 0
	v_mul_f32_e32 v14, v14, v17
	v_rcp_f32_e32 v17, v27
	s_nop 0
	v_mul_f32_e32 v13, v13, v17
	v_div_scale_f32 v30, s[0:1], v23, v23, v7
	v_rcp_f32_e32 v31, v30
	v_rcp_f32_e32 v17, v26
	s_nop 0
	v_mul_f32_e32 v12, v12, v17
	v_fma_f32 v17, -v30, v31, 1.0
	v_fmac_f32_e32 v31, v17, v31
	v_div_scale_f32 v27, s[0:1], v22, v22, v6
	v_rcp_f32_e32 v30, v27
	v_rcp_f32_e32 v17, v23
	s_nop 0
	v_mul_f32_e32 v7, v7, v17
	v_fma_f32 v17, -v27, v30, 1.0
	v_fmac_f32_e32 v30, v17, v30
	v_rcp_f32_e32 v17, v22
	s_nop 0
	v_mul_f32_e32 v6, v6, v17
	v_rcp_f32_e32 v17, v19
	s_nop 0
	v_mul_f32_e32 v5, v5, v17
	v_mul_f32_e32 v22, 0xbfb8aa3b, v3
	v_exp_f32_e32 v33, v22
	v_rcp_f32_e32 v17, v18
	s_nop 0
	v_mul_f32_e32 v4, v4, v17
	v_pk_add_f32 v[18:19], v[32:33], 1.0 op_sel_hi:[1,0]
	v_pk_add_f32 v[22:23], v[24:25], 1.0 op_sel_hi:[1,0]
	v_div_scale_f32 v17, s[0:1], v19, v19, v3
	v_rcp_f32_e32 v26, v17
	v_pk_add_f32 v[24:25], v[28:29], 1.0 op_sel_hi:[1,0]
	v_fma_f32 v27, -v17, v26, 1.0
	v_fmac_f32_e32 v26, v27, v26
	v_div_scale_f32 v27, vcc, v3, v19, v3
	v_mul_f32_e32 v28, v27, v26
	v_fma_f32 v29, -v17, v28, v27
	v_fmac_f32_e32 v28, v29, v26
	v_div_scale_f32 v27, s[0:1], v18, v18, v2
	v_rcp_f32_e32 v29, v27
	v_rcp_f32_e32 v17, v19
	s_nop 0
	v_mul_f32_e32 v3, v3, v17
	v_fma_f32 v17, -v27, v29, 1.0
	v_fmac_f32_e32 v29, v17, v29
	v_div_scale_f32 v26, s[0:1], v25, v25, v1
	v_rcp_f32_e32 v27, v26
	v_rcp_f32_e32 v17, v18
	s_nop 0
	v_mul_f32_e32 v2, v2, v17
	v_fma_f32 v17, -v26, v27, 1.0
	v_fmac_f32_e32 v27, v17, v27
	v_div_scale_f32 v19, s[0:1], v24, v24, v0
	v_rcp_f32_e32 v26, v19
	v_rcp_f32_e32 v17, v25
	s_nop 0
	v_mul_f32_e32 v1, v1, v17
	v_fma_f32 v17, -v19, v26, 1.0
	v_fmac_f32_e32 v26, v17, v26
	v_div_scale_f32 v19, s[0:1], v23, v23, v11
	v_rcp_f32_e32 v25, v19
	v_rcp_f32_e32 v17, v24
	s_nop 0
	v_mul_f32_e32 v0, v0, v17
	v_fma_f32 v17, -v19, v25, 1.0
	v_fmac_f32_e32 v25, v17, v25
	v_div_scale_f32 v19, s[0:1], v22, v22, v10
	v_rcp_f32_e32 v24, v19
	v_rcp_f32_e32 v17, v23
	s_nop 0
	v_mul_f32_e32 v11, v11, v17
	v_fma_f32 v17, -v19, v24, 1.0
	v_fmac_f32_e32 v24, v17, v24
	v_div_scale_f32 v19, s[0:1], v21, v21, v9
	v_rcp_f32_e32 v23, v19
	v_rcp_f32_e32 v17, v22
	s_nop 0
	v_mul_f32_e32 v10, v10, v17
	v_fma_f32 v17, -v19, v23, 1.0
	v_fmac_f32_e32 v23, v17, v23
	v_div_scale_f32 v19, s[0:1], v20, v20, v8
	v_rcp_f32_e32 v22, v19
	v_rcp_f32_e32 v17, v21
	s_nop 0
	v_mul_f32_e32 v9, v9, v17
	v_fma_f32 v17, -v19, v22, 1.0
	v_fmac_f32_e32 v22, v17, v22
	v_div_scale_f32 v17, vcc, v8, v20, v8
	v_mul_f32_e32 v18, v17, v22
	v_fma_f32 v21, -v19, v18, v17
	v_rcp_f32_e32 v17, v20
	s_nop 0
	v_mul_f32_e32 v8, v8, v17
	s_and_b64 vcc, exec, s[14:15]
	s_mov_b64 s[0:1], -1
	s_cbranch_vccnz .LBB0_323

; DI unsigned cvtpk(float lo, float hi) { f32x2_t v = {lo, hi}; bf16x2_t b = __builtin_convertvector(v, bf16x2_t); return __builtin_bit_cast(unsigned, b); }
;   DI void operator()(const f32x4 (&acc)[2][2][4][2], const pg8::Unit& u, int wr, int wc, int fr, int fq) const {
;     ...
;         const int row = u.pm * 256 + ai * 128 + wr * 64 + m * 16 + fr; float rs = 0.f;
;         const float rstd = rsqrtf(ssx[row] * (1.f / DM) + EPS);
; #pragma unroll
;         for (int bj = 0; bj < 2; ++bj)
; #pragma unroll
;           for (int n = 0; n < 2; ++n) {
;             const int col = u.pn * 256 + bj * 128 + wc * 32 + n * 16 + fq * 4; const size_t off = (size_t)row * DM + col;
;             f32x4 g;
; #pragma unroll
;             for (int j = 0; j < 4; ++j) g[j] = 1.f / (1.f + __expf(-rstd * acc[ai][bj][m][n][j]));
;             const u32x2 pw = *(const u32x2*)(PT + off); f32x4 pp; pp.x = __uint_as_float(pw.x << 16); pp.y = __uint_as_float(pw.x & 0xffff0000u); pp.z = __uint_as_float(pw.y << 16); pp.w = __uint_as_float(pw.y & 0xffff0000u);
;             const u32x2 xw = *(const u32x2*)(X1B + off); f32x4 x1; x1.x = __uint_as_float(xw.x << 16); x1.y = __uint_as_float(xw.x & 0xffff0000u); x1.z = __uint_as_float(xw.y << 16); x1.w = __uint_as_float(xw.y & 0xffff0000u);
;             const f32x4 xn = x1 + pp * g;
;             if (layer != 0) *(f32x4*)(out + off) = xn;
;             if (layer == 0) {
;               rs += xn.x * xn.x + xn.y * xn.y + xn.z * xn.z + xn.w * xn.w;
;               u32x2 w; w.x = cvtpk(xn.x, xn.y); w.y = cvtpk(xn.z, xn.w); *(u32x2*)(H + off) = w;
.LBB0_2372:
	v_lshl_add_u32 v146, s0, 8, v152
	v_ashrrev_i32_e32 v147, 31, v146
	v_lshl_add_u64 v[142:143], v[146:147], 2, s[24:25]
	global_load_dword v159, v[142:143], off
	v_lshl_or_b32 v140, s2, 8, v154
	v_lshlrev_b64 v[148:149], 10, v[146:147]
	v_ashrrev_i32_e32 v141, 31, v140
	v_lshl_add_u64 v[142:143], v[148:149], 0, v[140:141]
	v_lshlrev_b64 v[160:161], 1, v[142:143]
	v_lshl_add_u64 v[150:151], s[16:17], 0, v[160:161]
	v_lshl_add_u64 v[142:143], s[18:19], 0, v[160:161]
	global_load_dwordx2 v[162:163], v[150:151], off
	global_load_dwordx2 v[170:171], v[150:151], off offset:32
	global_load_dwordx2 v[164:165], v[142:143], off
	v_or_b32_e32 v142, 16, v140
	v_ashrrev_i32_e32 v143, 31, v142
	v_lshl_add_u64 v[166:167], v[148:149], 0, v[142:143]
	v_lshlrev_b64 v[166:167], 1, v[166:167]
	v_lshl_add_u64 v[160:161], s[28:29], 0, v[160:161]
	v_lshl_add_u64 v[168:169], s[18:19], 0, v[166:167]
	v_or_b32_e32 v144, 0x80, v140
	v_ashrrev_i32_e32 v145, 31, v144
	v_lshl_add_u64 v[166:167], s[28:29], 0, v[166:167]
	s_waitcnt vmcnt(0)
	v_fmamk_f32 v159, v159, 0x3a800000, v158
	v_mul_f32_e32 v172, 0x4b800000, v159
	v_cmp_gt_f32_e32 vcc, s54, v159
	v_and_b32_e32 v173, 0xffff0000, v162
	s_nop 0
	v_cndmask_b32_e32 v159, v159, v172, vcc
	v_rsq_f32_e32 v159, v159
	v_lshlrev_b32_e32 v174, 16, v164
	v_and_b32_e32 v175, 0xffff0000, v164
	v_lshlrev_b32_e32 v172, 16, v162
	v_mul_f32_e32 v164, 0x45800000, v159
	v_cndmask_b32_e32 v159, v159, v164, vcc
	v_mul_f32_e64 v124, v124, -v159
	v_mul_f32_e64 v125, v125, -v159
	v_mul_f32_e32 v124, 0x3fb8aa3b, v124
	v_mul_f32_e32 v125, 0x3fb8aa3b, v125
	v_mul_f32_e64 v126, v126, -v159
	v_mul_f32_e64 v127, v127, -v159
	v_exp_f32_e32 v124, v124
	v_exp_f32_e32 v125, v125
	v_mul_f32_e32 v126, 0x3fb8aa3b, v126
	v_mul_f32_e32 v127, 0x3fb8aa3b, v127
	v_exp_f32_e32 v126, v126
	v_exp_f32_e32 v127, v127
	v_pk_add_f32 v[124:125], v[124:125], 1.0 op_sel_hi:[1,0]
	v_lshlrev_b32_e32 v162, 16, v163
	v_pk_add_f32 v[126:127], v[126:127], 1.0 op_sel_hi:[1,0]
	v_div_scale_f32 v179, s[10:11], 1.0, v124, 1.0
	v_div_scale_f32 v181, s[12:13], 1.0, v127, 1.0
	v_div_scale_f32 v185, s[14:15], 1.0, v126, 1.0
	s_mov_b64 vcc, s[10:11]
	v_rcp_f32_e32 v125, v125
	s_mov_b64 vcc, s[12:13]
	v_rcp_f32_e32 v124, v124
	s_mov_b64 vcc, s[14:15]
	v_rcp_f32_e32 v127, v127
	v_and_b32_e32 v163, 0xffff0000, v163
	v_lshlrev_b32_e32 v164, 16, v165
	v_and_b32_e32 v165, 0xffff0000, v165
	v_rcp_f32_e32 v126, v126
	v_pk_fma_f32 v[124:125], v[124:125], v[172:173], v[174:175]
	v_pk_fma_f32 v[126:127], v[126:127], v[162:163], v[164:165]
	v_cvt_pk_bf16_f32 v172, v124, v125
	v_cvt_pk_bf16_f32 v173, v126, v127
	global_store_dwordx2 v[160:161], v[172:173], off
	global_load_dwordx2 v[160:161], v[168:169], off
	v_mul_f32_e64 v120, v120, -v159
	v_mul_f32_e64 v121, v121, -v159
	v_mul_f32_e64 v122, v122, -v159
	v_mul_f32_e64 v116, v116, -v159
	v_mul_f32_e64 v168, v117, -v159
	v_mul_f32_e32 v117, 0x3fb8aa3b, v120
	v_mul_f32_e32 v169, 0x3fb8aa3b, v121
	v_mul_f32_e64 v123, v123, -v159
	v_mul_f32_e32 v120, 0x3fb8aa3b, v122
	v_mul_f32_e32 v122, 0x3fb8aa3b, v116
	v_exp_f32_e32 v116, v117
	v_exp_f32_e32 v117, v169
	v_mul_f32_e32 v121, 0x3fb8aa3b, v123
	v_exp_f32_e32 v120, v120
	v_exp_f32_e32 v121, v121
	v_pk_add_f32 v[116:117], v[116:117], 1.0 op_sel_hi:[1,0]
	v_mul_f32_e32 v123, 0x3fb8aa3b, v168
	v_lshlrev_b32_e32 v162, 16, v170
	v_and_b32_e32 v163, 0xffff0000, v170
	v_pk_add_f32 v[120:121], v[120:121], 1.0 op_sel_hi:[1,0]
	v_lshlrev_b32_e32 v164, 16, v171
	v_and_b32_e32 v165, 0xffff0000, v171
	v_div_scale_f32 v171, s[10:11], 1.0, v116, 1.0
	v_div_scale_f32 v173, s[12:13], 1.0, v121, 1.0
	v_div_scale_f32 v175, s[14:15], 1.0, v120, 1.0
	s_mov_b64 vcc, s[10:11]
	v_rcp_f32_e32 v117, v117
	s_mov_b64 vcc, s[12:13]
	v_rcp_f32_e32 v116, v116
	s_mov_b64 vcc, s[14:15]
	v_rcp_f32_e32 v121, v121
	v_rcp_f32_e32 v120, v120
	v_exp_f32_e32 v122, v122
	v_mul_f32_e64 v118, v118, -v159
	s_waitcnt vmcnt(0)
	v_lshlrev_b32_e32 v168, 16, v160
	v_and_b32_e32 v169, 0xffff0000, v160
	v_lshlrev_b32_e32 v160, 16, v161
	v_and_b32_e32 v161, 0xffff0000, v161
	v_pk_fma_f32 v[120:121], v[120:121], v[164:165], v[160:161]
	v_pk_fma_f32 v[116:117], v[116:117], v[162:163], v[168:169]
	v_lshl_add_u64 v[162:163], v[148:149], 0, v[144:145]
	v_cvt_pk_bf16_f32 v160, v116, v117
	v_cvt_pk_bf16_f32 v161, v120, v121
	v_lshlrev_b64 v[162:163], 1, v[162:163]
	global_store_dwordx2 v[166:167], v[160:161], off
	v_lshl_add_u64 v[164:165], s[18:19], 0, v[162:163]
	global_load_dwordx2 v[160:161], v[150:151], off offset:256
	v_mul_f32_e64 v119, v119, -v159
	global_load_dwordx2 v[164:165], v[164:165], off
	v_exp_f32_e32 v123, v123
	v_mul_f32_e32 v118, 0x3fb8aa3b, v118
	v_mul_f32_e32 v119, 0x3fb8aa3b, v119
	v_exp_f32_e32 v118, v118
	v_exp_f32_e32 v119, v119
	v_pk_add_f32 v[122:123], v[122:123], 1.0 op_sel_hi:[1,0]
	v_mul_f32_e32 v125, v125, v125
	v_pk_add_f32 v[118:119], v[118:119], 1.0 op_sel_hi:[1,0]
	v_div_scale_f32 v169, s[10:11], 1.0, v122, 1.0
	v_div_scale_f32 v171, s[12:13], 1.0, v119, 1.0
	v_div_scale_f32 v173, s[14:15], 1.0, v118, 1.0
	v_fmac_f32_e32 v125, v124, v124
	s_mov_b64 vcc, s[10:11]
	v_mul_f32_e32 v117, v117, v117
	v_rcp_f32_e32 v123, v123
	s_mov_b64 vcc, s[12:13]
	v_fmac_f32_e32 v117, v116, v116
	v_fmac_f32_e32 v125, v126, v126
	v_rcp_f32_e32 v122, v122
	s_mov_b64 vcc, s[14:15]
	v_fmac_f32_e32 v117, v120, v120
	v_fmac_f32_e32 v125, v127, v127
	v_rcp_f32_e32 v119, v119
	v_fmac_f32_e32 v117, v121, v121
	v_rcp_f32_e32 v118, v118
	v_add_f32_e32 v166, v125, v117
	v_mul_f32_e64 v112, v112, -v159
	v_mul_f32_e64 v113, v113, -v159
	v_mul_f32_e32 v112, 0x3fb8aa3b, v112
	v_mul_f32_e32 v113, 0x3fb8aa3b, v113
	v_exp_f32_e32 v112, v112
	v_exp_f32_e32 v113, v113
	s_waitcnt vmcnt(1)
; DI unsigned cvtpk(float lo, float hi) { f32x2_t v = {lo, hi}; bf16x2_t b = __builtin_convertvector(v, bf16x2_t); return __builtin_bit_cast(unsigned, b); }
;   DI void operator()(const f32x4 (&acc)[2][2][4][2], const pg8::Unit& u, int wr, int wc, int fr, int fq) const {
;     ...
;         const int row = u.pm * 256 + ai * 128 + wr * 64 + m * 16 + fr; float rs = 0.f;
;         const float rstd = rsqrtf(ssx[row] * (1.f / DM) + EPS);
; #pragma unroll
;         for (int bj = 0; bj < 2; ++bj)
; #pragma unroll
;           for (int n = 0; n < 2; ++n) {
;             const int col = u.pn * 256 + bj * 128 + wc * 32 + n * 16 + fq * 4; const size_t off = (size_t)row * DM + col;
;             f32x4 g;
; #pragma unroll
;             for (int j = 0; j < 4; ++j) g[j] = 1.f / (1.f + __expf(-rstd * acc[ai][bj][m][n][j]));
;             const u32x2 pw = *(const u32x2*)(PT + off); f32x4 pp; pp.x = __uint_as_float(pw.x << 16); pp.y = __uint_as_float(pw.x & 0xffff0000u); pp.z = __uint_as_float(pw.y << 16); pp.w = __uint_as_float(pw.y & 0xffff0000u);
;             const u32x2 xw = *(const u32x2*)(X1B + off); f32x4 x1; x1.x = __uint_as_float(xw.x << 16); x1.y = __uint_as_float(xw.x & 0xffff0000u); x1.z = __uint_as_float(xw.y << 16); x1.w = __uint_as_float(xw.y & 0xffff0000u);
;             const f32x4 xn = x1 + pp * g;
;             if (layer != 0) *(f32x4*)(out + off) = xn;
;             if (layer == 0) {
;               rs += xn.x * xn.x + xn.y * xn.y + xn.z * xn.z + xn.w * xn.w;
;               u32x2 w; w.x = cvtpk(xn.x, xn.y); w.y = cvtpk(xn.z, xn.w); *(u32x2*)(H + off) = w;
;             }
;           }
;         if (layer == 0) { rs += __shfl_xor(rs, 16); rs += __shfl_xor(rs, 32); if (fq == 0) atomicAdd(ss1 + row, rs); }
	v_lshlrev_b32_e32 v116, 16, v160
	v_and_b32_e32 v117, 0xffff0000, v160
	v_lshlrev_b32_e32 v120, 16, v161
	v_and_b32_e32 v121, 0xffff0000, v161
	s_waitcnt vmcnt(0)
	v_lshlrev_b32_e32 v124, 16, v164
	v_and_b32_e32 v125, 0xffff0000, v164
	v_lshlrev_b32_e32 v126, 16, v165
	v_and_b32_e32 v127, 0xffff0000, v165
	v_pk_fma_f32 v[118:119], v[118:119], v[120:121], v[126:127]
	v_pk_fma_f32 v[120:121], v[122:123], v[116:117], v[124:125]
	v_cvt_pk_bf16_f32 v117, v118, v119
	v_cvt_pk_bf16_f32 v116, v120, v121
	v_lshl_add_u64 v[122:123], s[28:29], 0, v[162:163]
	global_store_dwordx2 v[122:123], v[116:117], off
	v_or_b32_e32 v116, 0x90, v140
	v_ashrrev_i32_e32 v117, 31, v116
	v_lshl_add_u64 v[124:125], v[148:149], 0, v[116:117]
	v_lshlrev_b64 v[126:127], 1, v[124:125]
	v_lshl_add_u64 v[124:125], s[18:19], 0, v[126:127]
	global_load_dwordx2 v[122:123], v[150:151], off offset:288
	v_mul_f32_e32 v121, v121, v121
	global_load_dwordx2 v[124:125], v[124:125], off
	v_fmac_f32_e32 v121, v120, v120
	v_pk_add_f32 v[112:113], v[112:113], 1.0 op_sel_hi:[1,0]
	v_fmac_f32_e32 v121, v118, v118
	v_fmac_f32_e32 v121, v119, v119
	v_add_f32_e32 v148, v121, v166
	v_mul_f32_e64 v114, v114, -v159
	v_mul_f32_e64 v115, v115, -v159
	v_mul_f32_e32 v114, 0x3fb8aa3b, v114
	v_mul_f32_e32 v115, 0x3fb8aa3b, v115
	v_exp_f32_e32 v114, v114
	v_exp_f32_e32 v115, v115
	v_rcp_f32_e32 v113, v113
	v_pk_add_f32 v[114:115], v[114:115], 1.0 op_sel_hi:[1,0]
	v_rcp_f32_e32 v112, v112
	v_rcp_f32_e32 v115, v115
	v_rcp_f32_e32 v114, v114
	s_waitcnt vmcnt(1)
	v_lshlrev_b32_e32 v118, 16, v122
	v_and_b32_e32 v119, 0xffff0000, v122
	v_lshlrev_b32_e32 v120, 16, v123
	v_and_b32_e32 v121, 0xffff0000, v123
	s_waitcnt vmcnt(0)
	v_lshlrev_b32_e32 v122, 16, v124
	v_and_b32_e32 v123, 0xffff0000, v124
	v_lshlrev_b32_e32 v124, 16, v125
	v_and_b32_e32 v125, 0xffff0000, v125
	v_pk_fma_f32 v[118:119], v[112:113], v[118:119], v[122:123]
	v_pk_fma_f32 v[114:115], v[114:115], v[120:121], v[124:125]
	v_mul_f32_e32 v112, v119, v119
	v_and_b32_e32 v120, 64, v183
	v_fmac_f32_e32 v112, v118, v118
	v_xor_b32_e32 v113, 16, v183
	v_add_u32_e32 v120, 64, v120
	v_fmac_f32_e32 v112, v114, v114
	v_cmp_lt_i32_e32 vcc, v113, v120
	v_fmac_f32_e32 v112, v115, v115
	v_add_f32_e32 v112, v148, v112
	v_cndmask_b32_e32 v113, v183, v113, vcc
	v_lshlrev_b32_e32 v124, 2, v113
	ds_bpermute_b32 v113, v124, v112
	v_cvt_pk_bf16_f32 v118, v118, v119
	v_cvt_pk_bf16_f32 v119, v114, v115
	v_lshl_add_u64 v[114:115], s[28:29], 0, v[126:127]
	global_store_dwordx2 v[114:115], v[118:119], off
	s_waitcnt lgkmcnt(0)
	v_add_f32_e32 v112, v112, v113
	v_xor_b32_e32 v113, 32, v183
	v_cmp_lt_i32_e32 vcc, v113, v120
	s_nop 1
	v_cndmask_b32_e32 v113, v183, v113, vcc
	v_lshlrev_b32_e32 v125, 2, v113
	ds_bpermute_b32 v113, v125, v112
	s_and_saveexec_b64 s[0:1], s[6:7]
	s_cbranch_execz .LBB0_2374
	s_waitcnt lgkmcnt(0)
	v_add_f32_e32 v114, v112, v113
	v_lshl_add_u64 v[112:113], v[146:147], 2, s[22:23]
	global_atomic_add_f32 v[112:113], v114, off
.LBB0_2374:
	s_or_b64 exec, exec, s[0:1]
	v_or_b32_e32 v112, 16, v146
	s_waitcnt lgkmcnt(0)
	v_ashrrev_i32_e32 v113, 31, v112
	v_lshl_add_u64 v[114:115], v[112:113], 2, s[24:25]
	global_load_dword v147, v[114:115], off
	v_lshlrev_b64 v[114:115], 10, v[112:113]
	v_lshl_add_u64 v[118:119], v[114:115], 0, v[140:141]
	v_lshlrev_b64 v[126:127], 1, v[118:119]
	v_lshl_add_u64 v[120:121], s[18:19], 0, v[126:127]
	global_load_dwordx2 v[122:123], v[120:121], off
	v_lshl_add_u64 v[118:119], s[16:17], 0, v[126:127]
	global_load_dwordx2 v[148:149], v[118:119], off
	global_load_dwordx2 v[162:163], v[118:119], off offset:32
	v_lshl_add_u64 v[120:121], v[114:115], 0, v[142:143]
	v_lshl_add_u64 v[150:151], v[114:115], 0, v[144:145]
	v_lshlrev_b64 v[160:161], 1, v[120:121]
	v_lshl_add_u64 v[126:127], s[28:29], 0, v[126:127]
	v_lshlrev_b64 v[120:121], 1, v[150:151]
	v_lshl_add_u64 v[150:151], s[18:19], 0, v[160:161]
	s_waitcnt vmcnt(3)
	v_fmamk_f32 v147, v147, 0x3a800000, v158
	v_mul_f32_e32 v159, 0x4b800000, v147
	v_cmp_gt_f32_e32 vcc, s54, v147
	s_waitcnt vmcnt(2)
	v_lshlrev_b32_e32 v166, 16, v122
	v_cndmask_b32_e32 v147, v147, v159, vcc
	v_rsq_f32_e32 v147, v147
	v_and_b32_e32 v167, 0xffff0000, v122
	s_waitcnt vmcnt(1)
	v_lshlrev_b32_e32 v164, 16, v148
	v_and_b32_e32 v165, 0xffff0000, v148
	v_mul_f32_e32 v122, 0x45800000, v147
	v_cndmask_b32_e32 v147, v147, v122, vcc
	v_mul_f32_e64 v108, v108, -v147
	v_mul_f32_e64 v109, v109, -v147
	v_mul_f32_e32 v108, 0x3fb8aa3b, v108
	v_mul_f32_e32 v109, 0x3fb8aa3b, v109
	v_mul_f32_e64 v110, v110, -v147
	v_mul_f32_e64 v111, v111, -v147
	v_exp_f32_e32 v108, v108
	v_exp_f32_e32 v109, v109
	v_mul_f32_e32 v110, 0x3fb8aa3b, v110
	v_mul_f32_e32 v111, 0x3fb8aa3b, v111
	v_exp_f32_e32 v110, v110
	v_exp_f32_e32 v111, v111
	v_pk_add_f32 v[108:109], v[108:109], 1.0 op_sel_hi:[1,0]
	v_lshlrev_b32_e32 v148, 16, v149
	v_pk_add_f32 v[110:111], v[110:111], 1.0 op_sel_hi:[1,0]
	v_div_scale_f32 v170, s[10:11], 1.0, v108, 1.0
	v_div_scale_f32 v172, s[12:13], 1.0, v111, 1.0
	v_div_scale_f32 v174, s[14:15], 1.0, v110, 1.0
	s_mov_b64 vcc, s[10:11]
	v_rcp_f32_e32 v109, v109
	s_mov_b64 vcc, s[12:13]
	v_rcp_f32_e32 v108, v108
	s_mov_b64 vcc, s[14:15]
	v_rcp_f32_e32 v111, v111
	v_and_b32_e32 v149, 0xffff0000, v149
	v_lshlrev_b32_e32 v122, 16, v123
	v_and_b32_e32 v123, 0xffff0000, v123
	v_rcp_f32_e32 v110, v110
	v_pk_fma_f32 v[108:109], v[108:109], v[164:165], v[166:167]
	v_pk_fma_f32 v[110:111], v[110:111], v[148:149], v[122:123]
	v_cvt_pk_bf16_f32 v164, v108, v109
	v_cvt_pk_bf16_f32 v165, v110, v111
	global_store_dwordx2 v[126:127], v[164:165], off
	global_load_dwordx2 v[122:123], v[150:151], off
	v_mul_f32_e64 v104, v104, -v147
	v_mul_f32_e64 v105, v105, -v147
	v_mul_f32_e64 v159, v100, -v147
	v_mul_f32_e32 v100, 0x3fb8aa3b, v104
	v_mul_f32_e32 v105, 0x3fb8aa3b, v105
	v_mul_f32_e64 v106, v106, -v147
	v_mul_f32_e64 v107, v107, -v147
	v_exp_f32_e32 v104, v100
	v_exp_f32_e32 v105, v105
	v_mul_f32_e32 v106, 0x3fb8aa3b, v106
	v_mul_f32_e32 v107, 0x3fb8aa3b, v107
	v_exp_f32_e32 v106, v106
	v_exp_f32_e32 v107, v107
	v_pk_add_f32 v[104:105], v[104:105], 1.0 op_sel_hi:[1,0]
	v_lshl_add_u64 v[126:127], s[28:29], 0, v[160:161]
	s_waitcnt vmcnt(2)
; DI unsigned cvtpk(float lo, float hi) { f32x2_t v = {lo, hi}; bf16x2_t b = __builtin_convertvector(v, bf16x2_t); return __builtin_bit_cast(unsigned, b); }
;   DI void operator()(const f32x4 (&acc)[2][2][4][2], const pg8::Unit& u, int wr, int wc, int fr, int fq) const {
;     ...
;         const int row = u.pm * 256 + ai * 128 + wr * 64 + m * 16 + fr; float rs = 0.f;
;         const float rstd = rsqrtf(ssx[row] * (1.f / DM) + EPS);
; #pragma unroll
;         for (int bj = 0; bj < 2; ++bj)
; #pragma unroll
;           for (int n = 0; n < 2; ++n) {
;             const int col = u.pn * 256 + bj * 128 + wc * 32 + n * 16 + fq * 4; const size_t off = (size_t)row * DM + col;
;             f32x4 g;
; #pragma unroll
;             for (int j = 0; j < 4; ++j) g[j] = 1.f / (1.f + __expf(-rstd * acc[ai][bj][m][n][j]));
;             const u32x2 pw = *(const u32x2*)(PT + off); f32x4 pp; pp.x = __uint_as_float(pw.x << 16); pp.y = __uint_as_float(pw.x & 0xffff0000u); pp.z = __uint_as_float(pw.y << 16); pp.w = __uint_as_float(pw.y & 0xffff0000u);
;             const u32x2 xw = *(const u32x2*)(X1B + off); f32x4 x1; x1.x = __uint_as_float(xw.x << 16); x1.y = __uint_as_float(xw.x & 0xffff0000u); x1.z = __uint_as_float(xw.y << 16); x1.w = __uint_as_float(xw.y & 0xffff0000u);
;             const f32x4 xn = x1 + pp * g;
;             if (layer != 0) *(f32x4*)(out + off) = xn;
;             if (layer == 0) {
;               rs += xn.x * xn.x + xn.y * xn.y + xn.z * xn.z + xn.w * xn.w;
;               u32x2 w; w.x = cvtpk(xn.x, xn.y); w.y = cvtpk(xn.z, xn.w); *(u32x2*)(H + off) = w;
	v_lshlrev_b32_e32 v160, 16, v163
	v_and_b32_e32 v161, 0xffff0000, v163
	v_mul_f32_e64 v163, v102, -v147
	v_lshlrev_b32_e32 v150, 16, v162
	v_and_b32_e32 v151, 0xffff0000, v162
	v_mul_f32_e64 v162, v101, -v147
	v_pk_add_f32 v[100:101], v[106:107], 1.0 op_sel_hi:[1,0]
	v_div_scale_f32 v164, s[10:11], 1.0, v104, 1.0
	v_div_scale_f32 v166, s[12:13], 1.0, v101, 1.0
	v_div_scale_f32 v168, s[14:15], 1.0, v100, 1.0
	s_mov_b64 vcc, s[10:11]
	v_rcp_f32_e32 v105, v105
	s_mov_b64 vcc, s[12:13]
	v_rcp_f32_e32 v104, v104
	s_mov_b64 vcc, s[14:15]
	v_rcp_f32_e32 v101, v101
	v_rcp_f32_e32 v100, v100
	v_lshl_add_u64 v[148:149], s[18:19], 0, v[120:121]
	v_mul_f32_e64 v96, v96, -v147
	s_waitcnt vmcnt(0)
	v_lshlrev_b32_e32 v106, 16, v122
	v_and_b32_e32 v107, 0xffff0000, v122
	v_lshlrev_b32_e32 v122, 16, v123
	v_and_b32_e32 v123, 0xffff0000, v123
	v_pk_fma_f32 v[100:101], v[100:101], v[160:161], v[122:123]
	v_pk_fma_f32 v[104:105], v[104:105], v[150:151], v[106:107]
	v_cvt_pk_bf16_f32 v107, v100, v101
	v_cvt_pk_bf16_f32 v106, v104, v105
	global_store_dwordx2 v[126:127], v[106:107], off
	global_load_dwordx2 v[106:107], v[118:119], off offset:256
	v_mul_f32_e64 v122, v103, -v147
	global_load_dwordx2 v[102:103], v[148:149], off
	v_mul_f32_e32 v123, 0x3fb8aa3b, v159
	v_mul_f32_e32 v150, 0x3fb8aa3b, v162
	v_mul_f32_e32 v126, 0x3fb8aa3b, v163
	v_mul_f32_e32 v127, 0x3fb8aa3b, v122
	v_exp_f32_e32 v122, v123
	v_exp_f32_e32 v126, v126
	v_exp_f32_e32 v127, v127
	v_exp_f32_e32 v123, v150
	v_mul_f32_e32 v105, v105, v105
	v_fmac_f32_e32 v105, v104, v104
	v_pk_add_f32 v[126:127], v[126:127], 1.0 op_sel_hi:[1,0]
	v_pk_add_f32 v[122:123], v[122:123], 1.0 op_sel_hi:[1,0]
	v_div_scale_f32 v151, s[10:11], 1.0, v122, 1.0
	v_div_scale_f32 v160, s[12:13], 1.0, v127, 1.0
	v_div_scale_f32 v162, s[14:15], 1.0, v126, 1.0
	v_mul_f32_e32 v159, v109, v109
	v_fmac_f32_e32 v159, v108, v108
	s_mov_b64 vcc, s[10:11]
	v_rcp_f32_e32 v109, v123
	s_mov_b64 vcc, s[12:13]
	v_fmac_f32_e32 v159, v110, v110
	s_mov_b64 vcc, s[14:15]
	v_fmac_f32_e32 v105, v100, v100
	v_fmac_f32_e32 v159, v111, v111
	v_rcp_f32_e32 v111, v127
	v_fmac_f32_e32 v105, v101, v101
	v_rcp_f32_e32 v108, v122
	v_rcp_f32_e32 v110, v126
	v_add_f32_e32 v122, v159, v105
	v_mul_f32_e64 v97, v97, -v147
	v_mul_f32_e32 v96, 0x3fb8aa3b, v96
	v_mul_f32_e32 v97, 0x3fb8aa3b, v97
	s_waitcnt vmcnt(1)
	v_lshlrev_b32_e32 v100, 16, v106
	v_and_b32_e32 v101, 0xffff0000, v106
	v_lshlrev_b32_e32 v104, 16, v107
	v_and_b32_e32 v105, 0xffff0000, v107
	s_waitcnt vmcnt(0)
	v_lshlrev_b32_e32 v106, 16, v102
	v_and_b32_e32 v107, 0xffff0000, v102
	v_lshlrev_b32_e32 v102, 16, v103
	v_and_b32_e32 v103, 0xffff0000, v103
	v_pk_fma_f32 v[102:103], v[110:111], v[104:105], v[102:103]
	v_pk_fma_f32 v[100:101], v[108:109], v[100:101], v[106:107]
	v_cvt_pk_bf16_f32 v105, v102, v103
	v_cvt_pk_bf16_f32 v104, v100, v101
	v_lshl_add_u64 v[106:107], s[28:29], 0, v[120:121]
	global_store_dwordx2 v[106:107], v[104:105], off
	v_lshl_add_u64 v[106:107], v[114:115], 0, v[116:117]
	v_lshlrev_b64 v[106:107], 1, v[106:107]
	v_lshl_add_u64 v[108:109], s[18:19], 0, v[106:107]
	global_load_dwordx2 v[104:105], v[118:119], off offset:288
	v_exp_f32_e32 v96, v96
	global_load_dwordx2 v[108:109], v[108:109], off
	v_exp_f32_e32 v97, v97
	v_mul_f32_e32 v101, v101, v101
	v_fmac_f32_e32 v101, v100, v100
	v_fmac_f32_e32 v101, v102, v102
	v_pk_add_f32 v[96:97], v[96:97], 1.0 op_sel_hi:[1,0]
	v_fmac_f32_e32 v101, v103, v103
	v_add_f32_e32 v110, v101, v122
	v_mul_f32_e64 v98, v98, -v147
	v_mul_f32_e64 v99, v99, -v147
	v_mul_f32_e32 v98, 0x3fb8aa3b, v98
	v_mul_f32_e32 v99, 0x3fb8aa3b, v99
	v_exp_f32_e32 v98, v98
	v_exp_f32_e32 v99, v99
	v_rcp_f32_e32 v97, v97
	v_pk_add_f32 v[98:99], v[98:99], 1.0 op_sel_hi:[1,0]
	v_rcp_f32_e32 v96, v96
	v_rcp_f32_e32 v99, v99
	v_rcp_f32_e32 v98, v98
	s_waitcnt vmcnt(1)
	v_lshlrev_b32_e32 v100, 16, v104
	v_and_b32_e32 v101, 0xffff0000, v104
	v_lshlrev_b32_e32 v102, 16, v105
	v_and_b32_e32 v103, 0xffff0000, v105
	s_waitcnt vmcnt(0)
	v_lshlrev_b32_e32 v104, 16, v108
	v_and_b32_e32 v105, 0xffff0000, v108
	v_pk_fma_f32 v[100:101], v[96:97], v[100:101], v[104:105]
	v_lshlrev_b32_e32 v108, 16, v109
	v_and_b32_e32 v109, 0xffff0000, v109
	v_mul_f32_e32 v96, v101, v101
	v_pk_fma_f32 v[98:99], v[98:99], v[102:103], v[108:109]
	v_fmac_f32_e32 v96, v100, v100
	v_fmac_f32_e32 v96, v98, v98
	v_fmac_f32_e32 v96, v99, v99
	v_add_f32_e32 v96, v110, v96
	ds_bpermute_b32 v97, v124, v96
	v_cvt_pk_bf16_f32 v100, v100, v101
	v_cvt_pk_bf16_f32 v101, v98, v99
	v_lshl_add_u64 v[98:99], s[28:29], 0, v[106:107]
	global_store_dwordx2 v[98:99], v[100:101], off
	s_waitcnt lgkmcnt(0)
	v_add_f32_e32 v96, v96, v97
	ds_bpermute_b32 v97, v125, v96
	s_and_saveexec_b64 s[0:1], s[6:7]
	s_cbranch_execz .LBB0_2376
	s_waitcnt lgkmcnt(0)
	v_add_f32_e32 v98, v96, v97
	v_lshl_add_u64 v[96:97], v[112:113], 2, s[22:23]
	global_atomic_add_f32 v[96:97], v98, off
; DI unsigned cvtpk(float lo, float hi) { f32x2_t v = {lo, hi}; bf16x2_t b = __builtin_convertvector(v, bf16x2_t); return __builtin_bit_cast(unsigned, b); }
;   DI void operator()(const f32x4 (&acc)[2][2][4][2], const pg8::Unit& u, int wr, int wc, int fr, int fq) const {
;     ...
;         const int row = u.pm * 256 + ai * 128 + wr * 64 + m * 16 + fr; float rs = 0.f;
;         const float rstd = rsqrtf(ssx[row] * (1.f / DM) + EPS);
; #pragma unroll
;         for (int bj = 0; bj < 2; ++bj)
; #pragma unroll
;           for (int n = 0; n < 2; ++n) {
;             const int col = u.pn * 256 + bj * 128 + wc * 32 + n * 16 + fq * 4; const size_t off = (size_t)row * DM + col;
;             f32x4 g;
; #pragma unroll
;             for (int j = 0; j < 4; ++j) g[j] = 1.f / (1.f + __expf(-rstd * acc[ai][bj][m][n][j]));
;             const u32x2 pw = *(const u32x2*)(PT + off); f32x4 pp; pp.x = __uint_as_float(pw.x << 16); pp.y = __uint_as_float(pw.x & 0xffff0000u); pp.z = __uint_as_float(pw.y << 16); pp.w = __uint_as_float(pw.y & 0xffff0000u);
;             const u32x2 xw = *(const u32x2*)(X1B + off); f32x4 x1; x1.x = __uint_as_float(xw.x << 16); x1.y = __uint_as_float(xw.x & 0xffff0000u); x1.z = __uint_as_float(xw.y << 16); x1.w = __uint_as_float(xw.y & 0xffff0000u);
;             const f32x4 xn = x1 + pp * g;
;             if (layer != 0) *(f32x4*)(out + off) = xn;
;             if (layer == 0) {
;               rs += xn.x * xn.x + xn.y * xn.y + xn.z * xn.z + xn.w * xn.w;
;               u32x2 w; w.x = cvtpk(xn.x, xn.y); w.y = cvtpk(xn.z, xn.w); *(u32x2*)(H + off) = w;
;             }
;           }
;         if (layer == 0) { rs += __shfl_xor(rs, 16); rs += __shfl_xor(rs, 32); if (fq == 0) atomicAdd(ss1 + row, rs); }
.LBB0_2376:
	s_or_b64 exec, exec, s[0:1]
	v_or_b32_e32 v96, 32, v146
	s_waitcnt lgkmcnt(0)
	v_ashrrev_i32_e32 v97, 31, v96
	v_lshl_add_u64 v[98:99], v[96:97], 2, s[24:25]
	global_load_dword v118, v[98:99], off
	v_lshlrev_b64 v[98:99], 10, v[96:97]
	v_lshl_add_u64 v[100:101], v[98:99], 0, v[140:141]
	v_lshlrev_b64 v[106:107], 1, v[100:101]
	v_lshl_add_u64 v[102:103], s[18:19], 0, v[106:107]
	global_load_dwordx2 v[104:105], v[102:103], off
	v_lshl_add_u64 v[100:101], s[16:17], 0, v[106:107]
	global_load_dwordx2 v[108:109], v[100:101], off
	global_load_dwordx2 v[114:115], v[100:101], off offset:32
	v_lshl_add_u64 v[102:103], v[98:99], 0, v[142:143]
	v_lshl_add_u64 v[110:111], v[98:99], 0, v[144:145]
	v_lshlrev_b64 v[112:113], 1, v[102:103]
	v_lshl_add_u64 v[106:107], s[28:29], 0, v[106:107]
	v_lshlrev_b64 v[102:103], 1, v[110:111]
	v_lshl_add_u64 v[110:111], s[18:19], 0, v[112:113]
	s_waitcnt vmcnt(3)
	v_fmamk_f32 v118, v118, 0x3a800000, v158
	v_mul_f32_e32 v119, 0x4b800000, v118
	v_cmp_gt_f32_e32 vcc, s54, v118
	s_waitcnt vmcnt(2)
	v_lshlrev_b32_e32 v120, 16, v104
	v_cndmask_b32_e32 v118, v118, v119, vcc
	v_rsq_f32_e32 v122, v118
	v_and_b32_e32 v121, 0xffff0000, v104
	s_waitcnt vmcnt(1)
	v_lshlrev_b32_e32 v118, 16, v108
	v_and_b32_e32 v119, 0xffff0000, v108
	v_mul_f32_e32 v104, 0x45800000, v122
	v_cndmask_b32_e32 v122, v122, v104, vcc
	v_mul_f32_e64 v92, v92, -v122
	v_mul_f32_e64 v93, v93, -v122
	v_mul_f32_e32 v92, 0x3fb8aa3b, v92
	v_mul_f32_e32 v93, 0x3fb8aa3b, v93
	v_mul_f32_e64 v94, v94, -v122
	v_mul_f32_e64 v95, v95, -v122
	v_exp_f32_e32 v92, v92
	v_exp_f32_e32 v93, v93
	v_mul_f32_e32 v94, 0x3fb8aa3b, v94
	v_mul_f32_e32 v95, 0x3fb8aa3b, v95
	v_exp_f32_e32 v94, v94
	v_exp_f32_e32 v95, v95
	v_pk_add_f32 v[92:93], v[92:93], 1.0 op_sel_hi:[1,0]
	v_lshlrev_b32_e32 v108, 16, v109
	v_pk_add_f32 v[94:95], v[94:95], 1.0 op_sel_hi:[1,0]
	v_div_scale_f32 v147, s[10:11], 1.0, v92, 1.0
	v_div_scale_f32 v149, s[12:13], 1.0, v95, 1.0
	v_div_scale_f32 v151, s[14:15], 1.0, v94, 1.0
	s_mov_b64 vcc, s[10:11]
	v_rcp_f32_e32 v93, v93
	s_mov_b64 vcc, s[12:13]
	v_rcp_f32_e32 v92, v92
	s_mov_b64 vcc, s[14:15]
	v_rcp_f32_e32 v95, v95
	v_and_b32_e32 v109, 0xffff0000, v109
	v_lshlrev_b32_e32 v104, 16, v105
	v_and_b32_e32 v105, 0xffff0000, v105
	v_rcp_f32_e32 v94, v94
	v_pk_fma_f32 v[92:93], v[92:93], v[118:119], v[120:121]
	v_pk_fma_f32 v[94:95], v[94:95], v[108:109], v[104:105]
	v_cvt_pk_bf16_f32 v118, v92, v93
	v_cvt_pk_bf16_f32 v119, v94, v95
	global_store_dwordx2 v[106:107], v[118:119], off
	global_load_dwordx2 v[104:105], v[110:111], off
	v_mul_f32_e64 v88, v88, -v122
	v_mul_f32_e64 v89, v89, -v122
	s_waitcnt vmcnt(2)
	v_lshlrev_b32_e32 v110, 16, v114
	v_and_b32_e32 v111, 0xffff0000, v114
	v_mul_f32_e64 v114, v84, -v122
	v_mul_f32_e32 v84, 0x3fb8aa3b, v88
	v_mul_f32_e32 v89, 0x3fb8aa3b, v89
	v_mul_f32_e64 v90, v90, -v122
	v_mul_f32_e64 v91, v91, -v122
	v_exp_f32_e32 v88, v84
	v_exp_f32_e32 v89, v89
	v_mul_f32_e32 v90, 0x3fb8aa3b, v90
	v_mul_f32_e32 v91, 0x3fb8aa3b, v91
	v_exp_f32_e32 v90, v90
	v_exp_f32_e32 v91, v91
	v_pk_add_f32 v[88:89], v[88:89], 1.0 op_sel_hi:[1,0]
	v_mul_f32_e64 v118, v86, -v122
	v_lshl_add_u64 v[106:107], s[28:29], 0, v[112:113]
	v_lshlrev_b32_e32 v112, 16, v115
	v_and_b32_e32 v113, 0xffff0000, v115
	v_mul_f32_e64 v115, v85, -v122
	v_pk_add_f32 v[84:85], v[90:91], 1.0 op_sel_hi:[1,0]
	v_div_scale_f32 v119, s[10:11], 1.0, v88, 1.0
	v_div_scale_f32 v121, s[12:13], 1.0, v85, 1.0
	v_div_scale_f32 v126, s[14:15], 1.0, v84, 1.0
	s_mov_b64 vcc, s[10:11]
	v_rcp_f32_e32 v89, v89
	s_mov_b64 vcc, s[12:13]
	v_rcp_f32_e32 v88, v88
	s_mov_b64 vcc, s[14:15]
	v_rcp_f32_e32 v85, v85
	v_rcp_f32_e32 v84, v84
	v_lshl_add_u64 v[108:109], s[18:19], 0, v[102:103]
	v_mul_f32_e64 v80, v80, -v122
	s_waitcnt vmcnt(0)
	v_lshlrev_b32_e32 v90, 16, v104
	v_and_b32_e32 v91, 0xffff0000, v104
	v_lshlrev_b32_e32 v104, 16, v105
	v_and_b32_e32 v105, 0xffff0000, v105
	v_pk_fma_f32 v[84:85], v[84:85], v[112:113], v[104:105]
	v_pk_fma_f32 v[88:89], v[88:89], v[110:111], v[90:91]
	v_cvt_pk_bf16_f32 v91, v84, v85
	v_cvt_pk_bf16_f32 v90, v88, v89
	global_store_dwordx2 v[106:107], v[90:91], off
	global_load_dwordx2 v[90:91], v[100:101], off offset:256
	v_mul_f32_e64 v104, v87, -v122
	global_load_dwordx2 v[86:87], v[108:109], off
	v_mul_f32_e32 v105, 0x3fb8aa3b, v114
	v_mul_f32_e32 v110, 0x3fb8aa3b, v115
	v_mul_f32_e32 v106, 0x3fb8aa3b, v118
	v_mul_f32_e32 v107, 0x3fb8aa3b, v104
	v_exp_f32_e32 v104, v105
	v_exp_f32_e32 v106, v106
	v_exp_f32_e32 v107, v107
	v_exp_f32_e32 v105, v110
	v_mul_f32_e32 v89, v89, v89
	v_fmac_f32_e32 v89, v88, v88
	v_pk_add_f32 v[106:107], v[106:107], 1.0 op_sel_hi:[1,0]
	v_pk_add_f32 v[104:105], v[104:105], 1.0 op_sel_hi:[1,0]
	v_div_scale_f32 v111, s[10:11], 1.0, v104, 1.0
	v_div_scale_f32 v113, s[12:13], 1.0, v107, 1.0
	v_div_scale_f32 v115, s[14:15], 1.0, v106, 1.0
	v_mul_f32_e32 v112, v93, v93
	v_fmac_f32_e32 v112, v92, v92
	s_mov_b64 vcc, s[10:11]
	v_rcp_f32_e32 v93, v105
	s_mov_b64 vcc, s[12:13]
	v_fmac_f32_e32 v112, v94, v94
	s_mov_b64 vcc, s[14:15]
	v_fmac_f32_e32 v89, v84, v84
	v_fmac_f32_e32 v112, v95, v95
	v_rcp_f32_e32 v95, v107
	v_fmac_f32_e32 v89, v85, v85
	v_rcp_f32_e32 v92, v104
	v_rcp_f32_e32 v94, v106
	v_add_f32_e32 v104, v112, v89
	v_mul_f32_e64 v81, v81, -v122
	v_mul_f32_e32 v80, 0x3fb8aa3b, v80
	v_mul_f32_e32 v81, 0x3fb8aa3b, v81
	s_waitcnt vmcnt(1)
	v_lshlrev_b32_e32 v84, 16, v90
	v_and_b32_e32 v85, 0xffff0000, v90
	v_lshlrev_b32_e32 v88, 16, v91
	v_and_b32_e32 v89, 0xffff0000, v91
	s_waitcnt vmcnt(0)
; DI unsigned cvtpk(float lo, float hi) { f32x2_t v = {lo, hi}; bf16x2_t b = __builtin_convertvector(v, bf16x2_t); return __builtin_bit_cast(unsigned, b); }
;   DI void operator()(const f32x4 (&acc)[2][2][4][2], const pg8::Unit& u, int wr, int wc, int fr, int fq) const {
;     ...
;         const int row = u.pm * 256 + ai * 128 + wr * 64 + m * 16 + fr; float rs = 0.f;
;         const float rstd = rsqrtf(ssx[row] * (1.f / DM) + EPS);
; #pragma unroll
;         for (int bj = 0; bj < 2; ++bj)
; #pragma unroll
;           for (int n = 0; n < 2; ++n) {
;             const int col = u.pn * 256 + bj * 128 + wc * 32 + n * 16 + fq * 4; const size_t off = (size_t)row * DM + col;
;             f32x4 g;
; #pragma unroll
;             for (int j = 0; j < 4; ++j) g[j] = 1.f / (1.f + __expf(-rstd * acc[ai][bj][m][n][j]));
;             const u32x2 pw = *(const u32x2*)(PT + off); f32x4 pp; pp.x = __uint_as_float(pw.x << 16); pp.y = __uint_as_float(pw.x & 0xffff0000u); pp.z = __uint_as_float(pw.y << 16); pp.w = __uint_as_float(pw.y & 0xffff0000u);
;             const u32x2 xw = *(const u32x2*)(X1B + off); f32x4 x1; x1.x = __uint_as_float(xw.x << 16); x1.y = __uint_as_float(xw.x & 0xffff0000u); x1.z = __uint_as_float(xw.y << 16); x1.w = __uint_as_float(xw.y & 0xffff0000u);
;             const f32x4 xn = x1 + pp * g;
;             if (layer != 0) *(f32x4*)(out + off) = xn;
;             if (layer == 0) {
;               rs += xn.x * xn.x + xn.y * xn.y + xn.z * xn.z + xn.w * xn.w;
;               u32x2 w; w.x = cvtpk(xn.x, xn.y); w.y = cvtpk(xn.z, xn.w); *(u32x2*)(H + off) = w;
;             }
;           }
;         if (layer == 0) { rs += __shfl_xor(rs, 16); rs += __shfl_xor(rs, 32); if (fq == 0) atomicAdd(ss1 + row, rs); }
	v_lshlrev_b32_e32 v90, 16, v86
	v_and_b32_e32 v91, 0xffff0000, v86
	v_lshlrev_b32_e32 v86, 16, v87
	v_and_b32_e32 v87, 0xffff0000, v87
	v_pk_fma_f32 v[86:87], v[94:95], v[88:89], v[86:87]
	v_pk_fma_f32 v[84:85], v[92:93], v[84:85], v[90:91]
	v_cvt_pk_bf16_f32 v89, v86, v87
	v_cvt_pk_bf16_f32 v88, v84, v85
	v_lshl_add_u64 v[90:91], s[28:29], 0, v[102:103]
	global_store_dwordx2 v[90:91], v[88:89], off
	v_lshl_add_u64 v[90:91], v[98:99], 0, v[116:117]
	v_lshlrev_b64 v[90:91], 1, v[90:91]
	v_lshl_add_u64 v[92:93], s[18:19], 0, v[90:91]
	global_load_dwordx2 v[88:89], v[100:101], off offset:288
	v_exp_f32_e32 v80, v80
	global_load_dwordx2 v[92:93], v[92:93], off
	v_exp_f32_e32 v81, v81
	v_mul_f32_e32 v85, v85, v85
	v_fmac_f32_e32 v85, v84, v84
	v_fmac_f32_e32 v85, v86, v86
	v_pk_add_f32 v[80:81], v[80:81], 1.0 op_sel_hi:[1,0]
	v_fmac_f32_e32 v85, v87, v87
	v_add_f32_e32 v94, v85, v104
	v_mul_f32_e64 v82, v82, -v122
	v_mul_f32_e64 v83, v83, -v122
	v_mul_f32_e32 v82, 0x3fb8aa3b, v82
	v_mul_f32_e32 v83, 0x3fb8aa3b, v83
	v_exp_f32_e32 v82, v82
	v_exp_f32_e32 v83, v83
	v_rcp_f32_e32 v81, v81
	v_pk_add_f32 v[82:83], v[82:83], 1.0 op_sel_hi:[1,0]
	v_rcp_f32_e32 v80, v80
	v_rcp_f32_e32 v83, v83
	v_rcp_f32_e32 v82, v82
	s_waitcnt vmcnt(1)
	v_lshlrev_b32_e32 v84, 16, v88
	v_and_b32_e32 v85, 0xffff0000, v88
	v_lshlrev_b32_e32 v86, 16, v89
	v_and_b32_e32 v87, 0xffff0000, v89
	s_waitcnt vmcnt(0)
	v_lshlrev_b32_e32 v88, 16, v92
	v_and_b32_e32 v89, 0xffff0000, v92
	v_pk_fma_f32 v[84:85], v[80:81], v[84:85], v[88:89]
	v_lshlrev_b32_e32 v92, 16, v93
	v_and_b32_e32 v93, 0xffff0000, v93
	v_mul_f32_e32 v80, v85, v85
	v_pk_fma_f32 v[82:83], v[82:83], v[86:87], v[92:93]
	v_fmac_f32_e32 v80, v84, v84
	v_fmac_f32_e32 v80, v82, v82
	v_fmac_f32_e32 v80, v83, v83
	v_add_f32_e32 v80, v94, v80
	ds_bpermute_b32 v81, v124, v80
	v_cvt_pk_bf16_f32 v84, v84, v85
	v_cvt_pk_bf16_f32 v85, v82, v83
	v_lshl_add_u64 v[82:83], s[28:29], 0, v[90:91]
	global_store_dwordx2 v[82:83], v[84:85], off
	s_waitcnt lgkmcnt(0)
	v_add_f32_e32 v80, v80, v81
	ds_bpermute_b32 v81, v125, v80
	s_and_saveexec_b64 s[0:1], s[6:7]
	s_cbranch_execz .LBB0_2378
	s_waitcnt lgkmcnt(0)
	v_add_f32_e32 v82, v80, v81
	v_lshl_add_u64 v[80:81], v[96:97], 2, s[22:23]
	global_atomic_add_f32 v[80:81], v82, off
.LBB0_2378:
	s_or_b64 exec, exec, s[0:1]
	v_or_b32_e32 v80, 48, v146
	s_waitcnt lgkmcnt(0)
	v_ashrrev_i32_e32 v81, 31, v80
	v_lshl_add_u64 v[82:83], v[80:81], 2, s[24:25]
	global_load_dword v100, v[82:83], off
	v_lshlrev_b64 v[82:83], 10, v[80:81]
	v_lshl_add_u64 v[84:85], v[82:83], 0, v[140:141]
	v_lshlrev_b64 v[90:91], 1, v[84:85]
	v_lshl_add_u64 v[86:87], s[18:19], 0, v[90:91]
	global_load_dwordx2 v[88:89], v[86:87], off
	v_lshl_add_u64 v[84:85], s[16:17], 0, v[90:91]
	global_load_dwordx2 v[92:93], v[84:85], off
	global_load_dwordx2 v[98:99], v[84:85], off offset:32
	v_lshl_add_u64 v[86:87], v[82:83], 0, v[142:143]
	v_lshl_add_u64 v[94:95], v[82:83], 0, v[144:145]
	v_lshlrev_b64 v[96:97], 1, v[86:87]
	v_lshl_add_u64 v[90:91], s[28:29], 0, v[90:91]
	v_lshlrev_b64 v[86:87], 1, v[94:95]
	v_lshl_add_u64 v[94:95], s[18:19], 0, v[96:97]
	s_waitcnt vmcnt(3)
	v_fmamk_f32 v100, v100, 0x3a800000, v158
	v_mul_f32_e32 v101, 0x4b800000, v100
	v_cmp_gt_f32_e32 vcc, s54, v100
	s_waitcnt vmcnt(2)
	v_lshlrev_b32_e32 v102, 16, v88
	v_cndmask_b32_e32 v100, v100, v101, vcc
	v_rsq_f32_e32 v104, v100
	v_and_b32_e32 v103, 0xffff0000, v88
	s_waitcnt vmcnt(1)
	v_lshlrev_b32_e32 v100, 16, v92
	v_and_b32_e32 v101, 0xffff0000, v92
	v_mul_f32_e32 v88, 0x45800000, v104
	v_cndmask_b32_e32 v104, v104, v88, vcc
	v_mul_f32_e64 v76, v76, -v104
	v_mul_f32_e64 v77, v77, -v104
	v_mul_f32_e32 v76, 0x3fb8aa3b, v76
	v_mul_f32_e32 v77, 0x3fb8aa3b, v77
	v_mul_f32_e64 v78, v78, -v104
	v_mul_f32_e64 v79, v79, -v104
	v_exp_f32_e32 v76, v76
	v_exp_f32_e32 v77, v77
	v_mul_f32_e32 v78, 0x3fb8aa3b, v78
	v_mul_f32_e32 v79, 0x3fb8aa3b, v79
	v_exp_f32_e32 v78, v78
	v_exp_f32_e32 v79, v79
	v_pk_add_f32 v[76:77], v[76:77], 1.0 op_sel_hi:[1,0]
	v_lshlrev_b32_e32 v92, 16, v93
	v_pk_add_f32 v[78:79], v[78:79], 1.0 op_sel_hi:[1,0]
	v_div_scale_f32 v108, s[10:11], 1.0, v76, 1.0
	v_div_scale_f32 v110, s[12:13], 1.0, v79, 1.0
	v_div_scale_f32 v112, s[14:15], 1.0, v78, 1.0
	s_mov_b64 vcc, s[10:11]
	v_rcp_f32_e32 v77, v77
	s_mov_b64 vcc, s[12:13]
	v_rcp_f32_e32 v76, v76
	s_mov_b64 vcc, s[14:15]
	v_rcp_f32_e32 v79, v79
	v_and_b32_e32 v93, 0xffff0000, v93
	v_lshlrev_b32_e32 v88, 16, v89
	v_and_b32_e32 v89, 0xffff0000, v89
	v_rcp_f32_e32 v78, v78
	v_pk_fma_f32 v[76:77], v[76:77], v[100:101], v[102:103]
	v_pk_fma_f32 v[78:79], v[78:79], v[92:93], v[88:89]
	v_cvt_pk_bf16_f32 v100, v76, v77
	v_cvt_pk_bf16_f32 v101, v78, v79
	global_store_dwordx2 v[90:91], v[100:101], off
	global_load_dwordx2 v[88:89], v[94:95], off
	v_mul_f32_e64 v72, v72, -v104
	v_mul_f32_e64 v73, v73, -v104
	s_waitcnt vmcnt(2)
	v_lshlrev_b32_e32 v94, 16, v98
	v_and_b32_e32 v95, 0xffff0000, v98
	v_mul_f32_e64 v98, v68, -v104
	v_mul_f32_e32 v68, 0x3fb8aa3b, v72
	v_mul_f32_e32 v73, 0x3fb8aa3b, v73
	v_mul_f32_e64 v74, v74, -v104
	v_mul_f32_e64 v75, v75, -v104
	v_exp_f32_e32 v72, v68
	v_exp_f32_e32 v73, v73
	v_mul_f32_e32 v74, 0x3fb8aa3b, v74
	v_mul_f32_e32 v75, 0x3fb8aa3b, v75
	v_exp_f32_e32 v74, v74
	v_exp_f32_e32 v75, v75
	v_pk_add_f32 v[72:73], v[72:73], 1.0 op_sel_hi:[1,0]
	v_mul_f32_e64 v100, v70, -v104
	v_lshl_add_u64 v[90:91], s[28:29], 0, v[96:97]
	v_lshlrev_b32_e32 v96, 16, v99
	v_and_b32_e32 v97, 0xffff0000, v99
	v_mul_f32_e64 v99, v69, -v104
	v_pk_add_f32 v[68:69], v[74:75], 1.0 op_sel_hi:[1,0]
	v_div_scale_f32 v101, s[10:11], 1.0, v72, 1.0
	v_div_scale_f32 v103, s[12:13], 1.0, v69, 1.0
	v_div_scale_f32 v106, s[14:15], 1.0, v68, 1.0
	s_mov_b64 vcc, s[10:11]
	v_rcp_f32_e32 v73, v73
	s_mov_b64 vcc, s[12:13]
	v_rcp_f32_e32 v72, v72
	s_mov_b64 vcc, s[14:15]
	v_rcp_f32_e32 v69, v69
	v_rcp_f32_e32 v68, v68
	v_lshl_add_u64 v[92:93], s[18:19], 0, v[86:87]
	v_mul_f32_e64 v64, v64, -v104
	s_waitcnt vmcnt(0)
; DI unsigned cvtpk(float lo, float hi) { f32x2_t v = {lo, hi}; bf16x2_t b = __builtin_convertvector(v, bf16x2_t); return __builtin_bit_cast(unsigned, b); }
;   DI void operator()(const f32x4 (&acc)[2][2][4][2], const pg8::Unit& u, int wr, int wc, int fr, int fq) const {
;     ...
;         const int row = u.pm * 256 + ai * 128 + wr * 64 + m * 16 + fr; float rs = 0.f;
;         const float rstd = rsqrtf(ssx[row] * (1.f / DM) + EPS);
; #pragma unroll
;         for (int bj = 0; bj < 2; ++bj)
; #pragma unroll
;           for (int n = 0; n < 2; ++n) {
;             const int col = u.pn * 256 + bj * 128 + wc * 32 + n * 16 + fq * 4; const size_t off = (size_t)row * DM + col;
;             f32x4 g;
; #pragma unroll
;             for (int j = 0; j < 4; ++j) g[j] = 1.f / (1.f + __expf(-rstd * acc[ai][bj][m][n][j]));
;             const u32x2 pw = *(const u32x2*)(PT + off); f32x4 pp; pp.x = __uint_as_float(pw.x << 16); pp.y = __uint_as_float(pw.x & 0xffff0000u); pp.z = __uint_as_float(pw.y << 16); pp.w = __uint_as_float(pw.y & 0xffff0000u);
;             const u32x2 xw = *(const u32x2*)(X1B + off); f32x4 x1; x1.x = __uint_as_float(xw.x << 16); x1.y = __uint_as_float(xw.x & 0xffff0000u); x1.z = __uint_as_float(xw.y << 16); x1.w = __uint_as_float(xw.y & 0xffff0000u);
;             const f32x4 xn = x1 + pp * g;
;             if (layer != 0) *(f32x4*)(out + off) = xn;
;             if (layer == 0) {
;               rs += xn.x * xn.x + xn.y * xn.y + xn.z * xn.z + xn.w * xn.w;
;               u32x2 w; w.x = cvtpk(xn.x, xn.y); w.y = cvtpk(xn.z, xn.w); *(u32x2*)(H + off) = w;
;             }
;           }
;         if (layer == 0) { rs += __shfl_xor(rs, 16); rs += __shfl_xor(rs, 32); if (fq == 0) atomicAdd(ss1 + row, rs); }
	v_lshlrev_b32_e32 v74, 16, v88
	v_and_b32_e32 v75, 0xffff0000, v88
	v_lshlrev_b32_e32 v88, 16, v89
	v_and_b32_e32 v89, 0xffff0000, v89
	v_pk_fma_f32 v[68:69], v[68:69], v[96:97], v[88:89]
	v_pk_fma_f32 v[72:73], v[72:73], v[94:95], v[74:75]
	v_cvt_pk_bf16_f32 v75, v68, v69
	v_cvt_pk_bf16_f32 v74, v72, v73
	global_store_dwordx2 v[90:91], v[74:75], off
	global_load_dwordx2 v[74:75], v[84:85], off offset:256
	v_mul_f32_e64 v88, v71, -v104
	global_load_dwordx2 v[70:71], v[92:93], off
	v_mul_f32_e32 v89, 0x3fb8aa3b, v98
	v_mul_f32_e32 v94, 0x3fb8aa3b, v99
	v_mul_f32_e32 v90, 0x3fb8aa3b, v100
	v_mul_f32_e32 v91, 0x3fb8aa3b, v88
	v_exp_f32_e32 v88, v89
	v_exp_f32_e32 v90, v90
	v_exp_f32_e32 v91, v91
	v_exp_f32_e32 v89, v94
	v_mul_f32_e32 v73, v73, v73
	v_fmac_f32_e32 v73, v72, v72
	v_pk_add_f32 v[90:91], v[90:91], 1.0 op_sel_hi:[1,0]
	v_pk_add_f32 v[88:89], v[88:89], 1.0 op_sel_hi:[1,0]
	v_div_scale_f32 v95, s[10:11], 1.0, v88, 1.0
	v_div_scale_f32 v97, s[12:13], 1.0, v91, 1.0
	v_div_scale_f32 v99, s[14:15], 1.0, v90, 1.0
	v_mul_f32_e32 v96, v77, v77
	v_fmac_f32_e32 v96, v76, v76
	s_mov_b64 vcc, s[10:11]
	v_rcp_f32_e32 v77, v89
	s_mov_b64 vcc, s[12:13]
	v_fmac_f32_e32 v96, v78, v78
	s_mov_b64 vcc, s[14:15]
	v_fmac_f32_e32 v73, v68, v68
	v_fmac_f32_e32 v96, v79, v79
	v_rcp_f32_e32 v79, v91
	v_fmac_f32_e32 v73, v69, v69
	v_rcp_f32_e32 v76, v88
	v_rcp_f32_e32 v78, v90
	v_add_f32_e32 v88, v96, v73
	v_mul_f32_e64 v65, v65, -v104
	v_mul_f32_e32 v64, 0x3fb8aa3b, v64
	v_mul_f32_e32 v65, 0x3fb8aa3b, v65
	s_waitcnt vmcnt(1)
	v_lshlrev_b32_e32 v68, 16, v74
	v_and_b32_e32 v69, 0xffff0000, v74
	v_lshlrev_b32_e32 v72, 16, v75
	v_and_b32_e32 v73, 0xffff0000, v75
	s_waitcnt vmcnt(0)
	v_lshlrev_b32_e32 v74, 16, v70
	v_and_b32_e32 v75, 0xffff0000, v70
	v_lshlrev_b32_e32 v70, 16, v71
	v_and_b32_e32 v71, 0xffff0000, v71
	v_pk_fma_f32 v[70:71], v[78:79], v[72:73], v[70:71]
	v_pk_fma_f32 v[68:69], v[76:77], v[68:69], v[74:75]
	v_cvt_pk_bf16_f32 v73, v70, v71
	v_cvt_pk_bf16_f32 v72, v68, v69
	v_lshl_add_u64 v[74:75], s[28:29], 0, v[86:87]
	global_store_dwordx2 v[74:75], v[72:73], off
	v_lshl_add_u64 v[74:75], v[82:83], 0, v[116:117]
	v_lshlrev_b64 v[74:75], 1, v[74:75]
	v_lshl_add_u64 v[76:77], s[18:19], 0, v[74:75]
	global_load_dwordx2 v[72:73], v[84:85], off offset:288
	v_exp_f32_e32 v64, v64
	global_load_dwordx2 v[76:77], v[76:77], off
	v_exp_f32_e32 v65, v65
	v_mul_f32_e32 v69, v69, v69
	v_fmac_f32_e32 v69, v68, v68
	v_fmac_f32_e32 v69, v70, v70
	v_pk_add_f32 v[64:65], v[64:65], 1.0 op_sel_hi:[1,0]
	v_fmac_f32_e32 v69, v71, v71
	v_add_f32_e32 v78, v69, v88
	v_mul_f32_e64 v66, v66, -v104
	v_mul_f32_e64 v67, v67, -v104
	v_mul_f32_e32 v66, 0x3fb8aa3b, v66
	v_mul_f32_e32 v67, 0x3fb8aa3b, v67
	v_exp_f32_e32 v66, v66
	v_exp_f32_e32 v67, v67
	v_rcp_f32_e32 v65, v65
	v_pk_add_f32 v[66:67], v[66:67], 1.0 op_sel_hi:[1,0]
	v_rcp_f32_e32 v64, v64
	v_rcp_f32_e32 v67, v67
	v_rcp_f32_e32 v66, v66
	s_waitcnt vmcnt(1)
	v_lshlrev_b32_e32 v68, 16, v72
	v_and_b32_e32 v69, 0xffff0000, v72
	v_lshlrev_b32_e32 v70, 16, v73
	v_and_b32_e32 v71, 0xffff0000, v73
	s_waitcnt vmcnt(0)
	v_lshlrev_b32_e32 v72, 16, v76
	v_and_b32_e32 v73, 0xffff0000, v76
	v_pk_fma_f32 v[68:69], v[64:65], v[68:69], v[72:73]
	v_lshlrev_b32_e32 v76, 16, v77
	v_and_b32_e32 v77, 0xffff0000, v77
	v_mul_f32_e32 v64, v69, v69
	v_pk_fma_f32 v[66:67], v[66:67], v[70:71], v[76:77]
	v_fmac_f32_e32 v64, v68, v68
	v_fmac_f32_e32 v64, v66, v66
	v_fmac_f32_e32 v64, v67, v67
	v_add_f32_e32 v64, v78, v64
	ds_bpermute_b32 v65, v124, v64
	v_cvt_pk_bf16_f32 v68, v68, v69
	v_cvt_pk_bf16_f32 v69, v66, v67
	v_lshl_add_u64 v[66:67], s[28:29], 0, v[74:75]
	global_store_dwordx2 v[66:67], v[68:69], off
	s_waitcnt lgkmcnt(0)
	v_add_f32_e32 v64, v64, v65
	ds_bpermute_b32 v65, v125, v64
	s_and_saveexec_b64 s[0:1], s[6:7]
	s_cbranch_execz .LBB0_2380
	s_waitcnt lgkmcnt(0)
	v_add_f32_e32 v66, v64, v65
	v_lshl_add_u64 v[64:65], v[80:81], 2, s[22:23]
	global_atomic_add_f32 v[64:65], v66, off
.LBB0_2380:
	s_or_b64 exec, exec, s[0:1]
	v_add_u32_e32 v64, 0x80, v146
	s_waitcnt lgkmcnt(0)
	v_ashrrev_i32_e32 v65, 31, v64
	v_lshl_add_u64 v[66:67], v[64:65], 2, s[24:25]
	global_load_dword v84, v[66:67], off
	v_lshlrev_b64 v[66:67], 10, v[64:65]
	v_lshl_add_u64 v[68:69], v[66:67], 0, v[140:141]
	v_lshlrev_b64 v[74:75], 1, v[68:69]
	v_lshl_add_u64 v[70:71], s[18:19], 0, v[74:75]
	global_load_dwordx2 v[72:73], v[70:71], off
	v_lshl_add_u64 v[68:69], s[16:17], 0, v[74:75]
	global_load_dwordx2 v[76:77], v[68:69], off
	global_load_dwordx2 v[82:83], v[68:69], off offset:32
	v_lshl_add_u64 v[70:71], v[66:67], 0, v[142:143]
	v_lshl_add_u64 v[78:79], v[66:67], 0, v[144:145]
	v_lshlrev_b64 v[80:81], 1, v[70:71]
	v_lshl_add_u64 v[74:75], s[28:29], 0, v[74:75]
	v_lshlrev_b64 v[70:71], 1, v[78:79]
	v_lshl_add_u64 v[78:79], s[18:19], 0, v[80:81]
	s_waitcnt vmcnt(3)
	v_fmamk_f32 v84, v84, 0x3a800000, v158
	v_mul_f32_e32 v85, 0x4b800000, v84
	v_cmp_gt_f32_e32 vcc, s54, v84
	s_waitcnt vmcnt(2)
	v_lshlrev_b32_e32 v86, 16, v72
	v_cndmask_b32_e32 v84, v84, v85, vcc
	v_rsq_f32_e32 v88, v84
	v_and_b32_e32 v87, 0xffff0000, v72
	s_waitcnt vmcnt(1)
; DI unsigned cvtpk(float lo, float hi) { f32x2_t v = {lo, hi}; bf16x2_t b = __builtin_convertvector(v, bf16x2_t); return __builtin_bit_cast(unsigned, b); }
;   DI void operator()(const f32x4 (&acc)[2][2][4][2], const pg8::Unit& u, int wr, int wc, int fr, int fq) const {
;     ...
;         const int row = u.pm * 256 + ai * 128 + wr * 64 + m * 16 + fr; float rs = 0.f;
;         const float rstd = rsqrtf(ssx[row] * (1.f / DM) + EPS);
; #pragma unroll
;         for (int bj = 0; bj < 2; ++bj)
; #pragma unroll
;           for (int n = 0; n < 2; ++n) {
;             const int col = u.pn * 256 + bj * 128 + wc * 32 + n * 16 + fq * 4; const size_t off = (size_t)row * DM + col;
;             f32x4 g;
; #pragma unroll
;             for (int j = 0; j < 4; ++j) g[j] = 1.f / (1.f + __expf(-rstd * acc[ai][bj][m][n][j]));
;             const u32x2 pw = *(const u32x2*)(PT + off); f32x4 pp; pp.x = __uint_as_float(pw.x << 16); pp.y = __uint_as_float(pw.x & 0xffff0000u); pp.z = __uint_as_float(pw.y << 16); pp.w = __uint_as_float(pw.y & 0xffff0000u);
;             const u32x2 xw = *(const u32x2*)(X1B + off); f32x4 x1; x1.x = __uint_as_float(xw.x << 16); x1.y = __uint_as_float(xw.x & 0xffff0000u); x1.z = __uint_as_float(xw.y << 16); x1.w = __uint_as_float(xw.y & 0xffff0000u);
;             const f32x4 xn = x1 + pp * g;
;             if (layer != 0) *(f32x4*)(out + off) = xn;
;             if (layer == 0) {
;               rs += xn.x * xn.x + xn.y * xn.y + xn.z * xn.z + xn.w * xn.w;
;               u32x2 w; w.x = cvtpk(xn.x, xn.y); w.y = cvtpk(xn.z, xn.w); *(u32x2*)(H + off) = w;
;             }
;           }
;         if (layer == 0) { rs += __shfl_xor(rs, 16); rs += __shfl_xor(rs, 32); if (fq == 0) atomicAdd(ss1 + row, rs); }
	v_lshlrev_b32_e32 v84, 16, v76
	v_and_b32_e32 v85, 0xffff0000, v76
	v_mul_f32_e32 v72, 0x45800000, v88
	v_cndmask_b32_e32 v88, v88, v72, vcc
	v_mul_f32_e64 v60, v60, -v88
	v_mul_f32_e64 v61, v61, -v88
	v_mul_f32_e32 v60, 0x3fb8aa3b, v60
	v_mul_f32_e32 v61, 0x3fb8aa3b, v61
	v_mul_f32_e64 v62, v62, -v88
	v_mul_f32_e64 v63, v63, -v88
	v_exp_f32_e32 v60, v60
	v_exp_f32_e32 v61, v61
	v_mul_f32_e32 v62, 0x3fb8aa3b, v62
	v_mul_f32_e32 v63, 0x3fb8aa3b, v63
	v_exp_f32_e32 v62, v62
	v_exp_f32_e32 v63, v63
	v_pk_add_f32 v[60:61], v[60:61], 1.0 op_sel_hi:[1,0]
	v_lshlrev_b32_e32 v76, 16, v77
	v_pk_add_f32 v[62:63], v[62:63], 1.0 op_sel_hi:[1,0]
	v_div_scale_f32 v92, s[10:11], 1.0, v60, 1.0
	v_div_scale_f32 v94, s[12:13], 1.0, v63, 1.0
	v_div_scale_f32 v96, s[14:15], 1.0, v62, 1.0
	s_mov_b64 vcc, s[10:11]
	v_rcp_f32_e32 v61, v61
	s_mov_b64 vcc, s[12:13]
	v_rcp_f32_e32 v60, v60
	s_mov_b64 vcc, s[14:15]
	v_rcp_f32_e32 v63, v63
	v_and_b32_e32 v77, 0xffff0000, v77
	v_lshlrev_b32_e32 v72, 16, v73
	v_and_b32_e32 v73, 0xffff0000, v73
	v_rcp_f32_e32 v62, v62
	v_pk_fma_f32 v[60:61], v[60:61], v[84:85], v[86:87]
	v_pk_fma_f32 v[62:63], v[62:63], v[76:77], v[72:73]
	v_cvt_pk_bf16_f32 v84, v60, v61
	v_cvt_pk_bf16_f32 v85, v62, v63
	global_store_dwordx2 v[74:75], v[84:85], off
	global_load_dwordx2 v[72:73], v[78:79], off
	v_mul_f32_e64 v56, v56, -v88
	v_mul_f32_e64 v57, v57, -v88
	s_waitcnt vmcnt(2)
	v_lshlrev_b32_e32 v78, 16, v82
	v_and_b32_e32 v79, 0xffff0000, v82
	v_mul_f32_e64 v82, v52, -v88
	v_mul_f32_e32 v52, 0x3fb8aa3b, v56
	v_mul_f32_e32 v57, 0x3fb8aa3b, v57
	v_mul_f32_e64 v58, v58, -v88
	v_mul_f32_e64 v59, v59, -v88
	v_exp_f32_e32 v56, v52
	v_exp_f32_e32 v57, v57
	v_mul_f32_e32 v58, 0x3fb8aa3b, v58
	v_mul_f32_e32 v59, 0x3fb8aa3b, v59
	v_exp_f32_e32 v58, v58
	v_exp_f32_e32 v59, v59
	v_pk_add_f32 v[56:57], v[56:57], 1.0 op_sel_hi:[1,0]
	v_mul_f32_e64 v84, v54, -v88
	v_lshl_add_u64 v[74:75], s[28:29], 0, v[80:81]
	v_lshlrev_b32_e32 v80, 16, v83
	v_and_b32_e32 v81, 0xffff0000, v83
	v_mul_f32_e64 v83, v53, -v88
	v_pk_add_f32 v[52:53], v[58:59], 1.0 op_sel_hi:[1,0]
	v_div_scale_f32 v85, s[10:11], 1.0, v56, 1.0
	v_div_scale_f32 v87, s[12:13], 1.0, v53, 1.0
	v_div_scale_f32 v90, s[14:15], 1.0, v52, 1.0
	s_mov_b64 vcc, s[10:11]
	v_rcp_f32_e32 v57, v57
	s_mov_b64 vcc, s[12:13]
	v_rcp_f32_e32 v56, v56
	s_mov_b64 vcc, s[14:15]
	v_rcp_f32_e32 v53, v53
	v_rcp_f32_e32 v52, v52
	v_lshl_add_u64 v[76:77], s[18:19], 0, v[70:71]
	v_mul_f32_e64 v48, v48, -v88
	s_waitcnt vmcnt(0)
	v_lshlrev_b32_e32 v58, 16, v72
	v_and_b32_e32 v59, 0xffff0000, v72
	v_lshlrev_b32_e32 v72, 16, v73
	v_and_b32_e32 v73, 0xffff0000, v73
	v_pk_fma_f32 v[52:53], v[52:53], v[80:81], v[72:73]
	v_pk_fma_f32 v[56:57], v[56:57], v[78:79], v[58:59]
	v_cvt_pk_bf16_f32 v59, v52, v53
	v_cvt_pk_bf16_f32 v58, v56, v57
	global_store_dwordx2 v[74:75], v[58:59], off
	global_load_dwordx2 v[58:59], v[68:69], off offset:256
	v_mul_f32_e64 v72, v55, -v88
	global_load_dwordx2 v[54:55], v[76:77], off
	v_mul_f32_e32 v73, 0x3fb8aa3b, v82
	v_mul_f32_e32 v78, 0x3fb8aa3b, v83
	v_mul_f32_e32 v74, 0x3fb8aa3b, v84
	v_mul_f32_e32 v75, 0x3fb8aa3b, v72
	v_exp_f32_e32 v72, v73
	v_exp_f32_e32 v74, v74
	v_exp_f32_e32 v75, v75
	v_exp_f32_e32 v73, v78
	v_mul_f32_e32 v57, v57, v57
	v_fmac_f32_e32 v57, v56, v56
	v_pk_add_f32 v[74:75], v[74:75], 1.0 op_sel_hi:[1,0]
	v_pk_add_f32 v[72:73], v[72:73], 1.0 op_sel_hi:[1,0]
	v_div_scale_f32 v79, s[10:11], 1.0, v72, 1.0
	v_div_scale_f32 v81, s[12:13], 1.0, v75, 1.0
	v_div_scale_f32 v83, s[14:15], 1.0, v74, 1.0
	v_mul_f32_e32 v80, v61, v61
	v_fmac_f32_e32 v80, v60, v60
	s_mov_b64 vcc, s[10:11]
	v_rcp_f32_e32 v61, v73
	s_mov_b64 vcc, s[12:13]
	v_fmac_f32_e32 v80, v62, v62
	s_mov_b64 vcc, s[14:15]
	v_fmac_f32_e32 v57, v52, v52
	v_fmac_f32_e32 v80, v63, v63
	v_rcp_f32_e32 v63, v75
	v_fmac_f32_e32 v57, v53, v53
	v_rcp_f32_e32 v60, v72
	v_rcp_f32_e32 v62, v74
	v_add_f32_e32 v72, v80, v57
	v_mul_f32_e64 v49, v49, -v88
	v_mul_f32_e32 v48, 0x3fb8aa3b, v48
	v_mul_f32_e32 v49, 0x3fb8aa3b, v49
	s_waitcnt vmcnt(1)
	v_lshlrev_b32_e32 v52, 16, v58
	v_and_b32_e32 v53, 0xffff0000, v58
	v_lshlrev_b32_e32 v56, 16, v59
	v_and_b32_e32 v57, 0xffff0000, v59
	s_waitcnt vmcnt(0)
	v_lshlrev_b32_e32 v58, 16, v54
	v_and_b32_e32 v59, 0xffff0000, v54
	v_lshlrev_b32_e32 v54, 16, v55
	v_and_b32_e32 v55, 0xffff0000, v55
	v_pk_fma_f32 v[54:55], v[62:63], v[56:57], v[54:55]
	v_pk_fma_f32 v[52:53], v[60:61], v[52:53], v[58:59]
	v_cvt_pk_bf16_f32 v57, v54, v55
	v_cvt_pk_bf16_f32 v56, v52, v53
	v_lshl_add_u64 v[58:59], s[28:29], 0, v[70:71]
	global_store_dwordx2 v[58:59], v[56:57], off
	v_lshl_add_u64 v[58:59], v[66:67], 0, v[116:117]
	v_lshlrev_b64 v[58:59], 1, v[58:59]
	v_lshl_add_u64 v[60:61], s[18:19], 0, v[58:59]
	global_load_dwordx2 v[56:57], v[68:69], off offset:288
	v_exp_f32_e32 v48, v48
	global_load_dwordx2 v[60:61], v[60:61], off
	v_exp_f32_e32 v49, v49
	v_mul_f32_e32 v53, v53, v53
	v_fmac_f32_e32 v53, v52, v52
	v_fmac_f32_e32 v53, v54, v54
	v_pk_add_f32 v[48:49], v[48:49], 1.0 op_sel_hi:[1,0]
	v_fmac_f32_e32 v53, v55, v55
	v_add_f32_e32 v62, v53, v72
	v_mul_f32_e64 v50, v50, -v88
	v_mul_f32_e64 v51, v51, -v88
	v_mul_f32_e32 v50, 0x3fb8aa3b, v50
	v_mul_f32_e32 v51, 0x3fb8aa3b, v51
	v_exp_f32_e32 v50, v50
	v_exp_f32_e32 v51, v51
	v_rcp_f32_e32 v49, v49
	v_pk_add_f32 v[50:51], v[50:51], 1.0 op_sel_hi:[1,0]
	v_rcp_f32_e32 v48, v48
	v_rcp_f32_e32 v51, v51
	v_rcp_f32_e32 v50, v50
	s_waitcnt vmcnt(1)
	v_lshlrev_b32_e32 v52, 16, v56
	v_and_b32_e32 v53, 0xffff0000, v56
	v_lshlrev_b32_e32 v54, 16, v57
	v_and_b32_e32 v55, 0xffff0000, v57
	s_waitcnt vmcnt(0)
	v_lshlrev_b32_e32 v56, 16, v60
	v_and_b32_e32 v57, 0xffff0000, v60
	v_pk_fma_f32 v[52:53], v[48:49], v[52:53], v[56:57]
	v_lshlrev_b32_e32 v60, 16, v61
	v_and_b32_e32 v61, 0xffff0000, v61
	v_mul_f32_e32 v48, v53, v53
	v_pk_fma_f32 v[50:51], v[50:51], v[54:55], v[60:61]
	v_fmac_f32_e32 v48, v52, v52
	v_fmac_f32_e32 v48, v50, v50
	v_fmac_f32_e32 v48, v51, v51
	v_add_f32_e32 v48, v62, v48
	ds_bpermute_b32 v49, v124, v48
	v_cvt_pk_bf16_f32 v52, v52, v53
	v_cvt_pk_bf16_f32 v53, v50, v51
	v_lshl_add_u64 v[50:51], s[28:29], 0, v[58:59]
	global_store_dwordx2 v[50:51], v[52:53], off
	s_waitcnt lgkmcnt(0)
	v_add_f32_e32 v48, v48, v49
	ds_bpermute_b32 v49, v125, v48
	s_and_saveexec_b64 s[0:1], s[6:7]
	s_cbranch_execz .LBB0_2382
	s_waitcnt lgkmcnt(0)
	v_add_f32_e32 v50, v48, v49
	v_lshl_add_u64 v[48:49], v[64:65], 2, s[22:23]
	global_atomic_add_f32 v[48:49], v50, off
; DI unsigned cvtpk(float lo, float hi) { f32x2_t v = {lo, hi}; bf16x2_t b = __builtin_convertvector(v, bf16x2_t); return __builtin_bit_cast(unsigned, b); }
;   DI void operator()(const f32x4 (&acc)[2][2][4][2], const pg8::Unit& u, int wr, int wc, int fr, int fq) const {
;     ...
;         const int row = u.pm * 256 + ai * 128 + wr * 64 + m * 16 + fr; float rs = 0.f;
;         const float rstd = rsqrtf(ssx[row] * (1.f / DM) + EPS);
; #pragma unroll
;         for (int bj = 0; bj < 2; ++bj)
; #pragma unroll
;           for (int n = 0; n < 2; ++n) {
;             const int col = u.pn * 256 + bj * 128 + wc * 32 + n * 16 + fq * 4; const size_t off = (size_t)row * DM + col;
;             f32x4 g;
; #pragma unroll
;             for (int j = 0; j < 4; ++j) g[j] = 1.f / (1.f + __expf(-rstd * acc[ai][bj][m][n][j]));
;             const u32x2 pw = *(const u32x2*)(PT + off); f32x4 pp; pp.x = __uint_as_float(pw.x << 16); pp.y = __uint_as_float(pw.x & 0xffff0000u); pp.z = __uint_as_float(pw.y << 16); pp.w = __uint_as_float(pw.y & 0xffff0000u);
;             const u32x2 xw = *(const u32x2*)(X1B + off); f32x4 x1; x1.x = __uint_as_float(xw.x << 16); x1.y = __uint_as_float(xw.x & 0xffff0000u); x1.z = __uint_as_float(xw.y << 16); x1.w = __uint_as_float(xw.y & 0xffff0000u);
;             const f32x4 xn = x1 + pp * g;
;             if (layer != 0) *(f32x4*)(out + off) = xn;
;             if (layer == 0) {
;               rs += xn.x * xn.x + xn.y * xn.y + xn.z * xn.z + xn.w * xn.w;
;               u32x2 w; w.x = cvtpk(xn.x, xn.y); w.y = cvtpk(xn.z, xn.w); *(u32x2*)(H + off) = w;
;             }
;           }
;         if (layer == 0) { rs += __shfl_xor(rs, 16); rs += __shfl_xor(rs, 32); if (fq == 0) atomicAdd(ss1 + row, rs); }
.LBB0_2382:
	s_or_b64 exec, exec, s[0:1]
	v_add_u32_e32 v48, 0x90, v146
	s_waitcnt lgkmcnt(0)
	v_ashrrev_i32_e32 v49, 31, v48
	v_lshl_add_u64 v[50:51], v[48:49], 2, s[24:25]
	global_load_dword v68, v[50:51], off
	v_lshlrev_b64 v[50:51], 10, v[48:49]
	v_lshl_add_u64 v[52:53], v[50:51], 0, v[140:141]
	v_lshlrev_b64 v[58:59], 1, v[52:53]
	v_lshl_add_u64 v[54:55], s[18:19], 0, v[58:59]
	global_load_dwordx2 v[56:57], v[54:55], off
	v_lshl_add_u64 v[52:53], s[16:17], 0, v[58:59]
	global_load_dwordx2 v[60:61], v[52:53], off
	global_load_dwordx2 v[66:67], v[52:53], off offset:32
	v_lshl_add_u64 v[54:55], v[50:51], 0, v[142:143]
	v_lshl_add_u64 v[62:63], v[50:51], 0, v[144:145]
	v_lshlrev_b64 v[64:65], 1, v[54:55]
	v_lshl_add_u64 v[58:59], s[28:29], 0, v[58:59]
	v_lshlrev_b64 v[54:55], 1, v[62:63]
	v_lshl_add_u64 v[62:63], s[18:19], 0, v[64:65]
	s_waitcnt vmcnt(3)
	v_fmamk_f32 v68, v68, 0x3a800000, v158
	v_mul_f32_e32 v69, 0x4b800000, v68
	v_cmp_gt_f32_e32 vcc, s54, v68
	s_waitcnt vmcnt(2)
	v_lshlrev_b32_e32 v70, 16, v56
	v_cndmask_b32_e32 v68, v68, v69, vcc
	v_rsq_f32_e32 v72, v68
	v_and_b32_e32 v71, 0xffff0000, v56
	s_waitcnt vmcnt(1)
	v_lshlrev_b32_e32 v68, 16, v60
	v_and_b32_e32 v69, 0xffff0000, v60
	v_mul_f32_e32 v56, 0x45800000, v72
	v_cndmask_b32_e32 v72, v72, v56, vcc
	v_mul_f32_e64 v44, v44, -v72
	v_mul_f32_e64 v45, v45, -v72
	v_mul_f32_e32 v44, 0x3fb8aa3b, v44
	v_mul_f32_e32 v45, 0x3fb8aa3b, v45
	v_mul_f32_e64 v46, v46, -v72
	v_mul_f32_e64 v47, v47, -v72
	v_exp_f32_e32 v44, v44
	v_exp_f32_e32 v45, v45
	v_mul_f32_e32 v46, 0x3fb8aa3b, v46
	v_mul_f32_e32 v47, 0x3fb8aa3b, v47
	v_exp_f32_e32 v46, v46
	v_exp_f32_e32 v47, v47
	v_pk_add_f32 v[44:45], v[44:45], 1.0 op_sel_hi:[1,0]
	v_lshlrev_b32_e32 v60, 16, v61
	v_pk_add_f32 v[46:47], v[46:47], 1.0 op_sel_hi:[1,0]
	v_div_scale_f32 v76, s[10:11], 1.0, v44, 1.0
	v_div_scale_f32 v78, s[12:13], 1.0, v47, 1.0
	v_div_scale_f32 v80, s[14:15], 1.0, v46, 1.0
	s_mov_b64 vcc, s[10:11]
	v_rcp_f32_e32 v45, v45
	s_mov_b64 vcc, s[12:13]
	v_rcp_f32_e32 v44, v44
	s_mov_b64 vcc, s[14:15]
	v_rcp_f32_e32 v47, v47
	v_and_b32_e32 v61, 0xffff0000, v61
	v_lshlrev_b32_e32 v56, 16, v57
	v_and_b32_e32 v57, 0xffff0000, v57
	v_rcp_f32_e32 v46, v46
	v_pk_fma_f32 v[44:45], v[44:45], v[68:69], v[70:71]
	v_pk_fma_f32 v[46:47], v[46:47], v[60:61], v[56:57]
	v_cvt_pk_bf16_f32 v68, v44, v45
	v_cvt_pk_bf16_f32 v69, v46, v47
	global_store_dwordx2 v[58:59], v[68:69], off
	global_load_dwordx2 v[56:57], v[62:63], off
	v_mul_f32_e64 v40, v40, -v72
	v_mul_f32_e64 v41, v41, -v72
	s_waitcnt vmcnt(2)
	v_lshlrev_b32_e32 v62, 16, v66
	v_and_b32_e32 v63, 0xffff0000, v66
	v_mul_f32_e64 v66, v36, -v72
	v_mul_f32_e32 v36, 0x3fb8aa3b, v40
	v_mul_f32_e32 v41, 0x3fb8aa3b, v41
	v_mul_f32_e64 v42, v42, -v72
	v_mul_f32_e64 v43, v43, -v72
	v_exp_f32_e32 v40, v36
	v_exp_f32_e32 v41, v41
	v_mul_f32_e32 v42, 0x3fb8aa3b, v42
	v_mul_f32_e32 v43, 0x3fb8aa3b, v43
	v_exp_f32_e32 v42, v42
	v_exp_f32_e32 v43, v43
	v_pk_add_f32 v[40:41], v[40:41], 1.0 op_sel_hi:[1,0]
	v_mul_f32_e64 v68, v38, -v72
	v_lshl_add_u64 v[58:59], s[28:29], 0, v[64:65]
	v_lshlrev_b32_e32 v64, 16, v67
	v_and_b32_e32 v65, 0xffff0000, v67
	v_mul_f32_e64 v67, v37, -v72
	v_pk_add_f32 v[36:37], v[42:43], 1.0 op_sel_hi:[1,0]
	v_div_scale_f32 v69, s[10:11], 1.0, v40, 1.0
	v_div_scale_f32 v71, s[12:13], 1.0, v37, 1.0
	v_div_scale_f32 v74, s[14:15], 1.0, v36, 1.0
	s_mov_b64 vcc, s[10:11]
	v_rcp_f32_e32 v41, v41
	s_mov_b64 vcc, s[12:13]
	v_rcp_f32_e32 v40, v40
	s_mov_b64 vcc, s[14:15]
	v_rcp_f32_e32 v37, v37
	v_rcp_f32_e32 v36, v36
	v_lshl_add_u64 v[60:61], s[18:19], 0, v[54:55]
	v_mul_f32_e64 v32, v32, -v72
	s_waitcnt vmcnt(0)
	v_lshlrev_b32_e32 v42, 16, v56
	v_and_b32_e32 v43, 0xffff0000, v56
	v_lshlrev_b32_e32 v56, 16, v57
	v_and_b32_e32 v57, 0xffff0000, v57
	v_pk_fma_f32 v[36:37], v[36:37], v[64:65], v[56:57]
	v_pk_fma_f32 v[40:41], v[40:41], v[62:63], v[42:43]
	v_cvt_pk_bf16_f32 v43, v36, v37
	v_cvt_pk_bf16_f32 v42, v40, v41
	global_store_dwordx2 v[58:59], v[42:43], off
	global_load_dwordx2 v[42:43], v[52:53], off offset:256
	v_mul_f32_e64 v56, v39, -v72
	global_load_dwordx2 v[38:39], v[60:61], off
	v_mul_f32_e32 v57, 0x3fb8aa3b, v66
	v_mul_f32_e32 v62, 0x3fb8aa3b, v67
	v_mul_f32_e32 v58, 0x3fb8aa3b, v68
	v_mul_f32_e32 v59, 0x3fb8aa3b, v56
	v_exp_f32_e32 v56, v57
	v_exp_f32_e32 v58, v58
	v_exp_f32_e32 v59, v59
	v_exp_f32_e32 v57, v62
	v_mul_f32_e32 v41, v41, v41
	v_fmac_f32_e32 v41, v40, v40
	v_pk_add_f32 v[58:59], v[58:59], 1.0 op_sel_hi:[1,0]
	v_pk_add_f32 v[56:57], v[56:57], 1.0 op_sel_hi:[1,0]
	v_div_scale_f32 v63, s[10:11], 1.0, v56, 1.0
	v_div_scale_f32 v65, s[12:13], 1.0, v59, 1.0
	v_div_scale_f32 v67, s[14:15], 1.0, v58, 1.0
	v_mul_f32_e32 v64, v45, v45
	v_fmac_f32_e32 v64, v44, v44
	s_mov_b64 vcc, s[10:11]
	v_rcp_f32_e32 v45, v57
	s_mov_b64 vcc, s[12:13]
	v_fmac_f32_e32 v64, v46, v46
	s_mov_b64 vcc, s[14:15]
	v_fmac_f32_e32 v41, v36, v36
	v_fmac_f32_e32 v64, v47, v47
	v_rcp_f32_e32 v47, v59
	v_fmac_f32_e32 v41, v37, v37
	v_rcp_f32_e32 v44, v56
	v_rcp_f32_e32 v46, v58
	v_add_f32_e32 v56, v64, v41
	v_mul_f32_e64 v33, v33, -v72
	v_mul_f32_e32 v32, 0x3fb8aa3b, v32
	v_mul_f32_e32 v33, 0x3fb8aa3b, v33
	s_waitcnt vmcnt(1)
	v_lshlrev_b32_e32 v36, 16, v42
	v_and_b32_e32 v37, 0xffff0000, v42
	v_lshlrev_b32_e32 v40, 16, v43
	v_and_b32_e32 v41, 0xffff0000, v43
	s_waitcnt vmcnt(0)
; DI unsigned cvtpk(float lo, float hi) { f32x2_t v = {lo, hi}; bf16x2_t b = __builtin_convertvector(v, bf16x2_t); return __builtin_bit_cast(unsigned, b); }
;   DI void operator()(const f32x4 (&acc)[2][2][4][2], const pg8::Unit& u, int wr, int wc, int fr, int fq) const {
;     ...
;         const int row = u.pm * 256 + ai * 128 + wr * 64 + m * 16 + fr; float rs = 0.f;
;         const float rstd = rsqrtf(ssx[row] * (1.f / DM) + EPS);
; #pragma unroll
;         for (int bj = 0; bj < 2; ++bj)
; #pragma unroll
;           for (int n = 0; n < 2; ++n) {
;             const int col = u.pn * 256 + bj * 128 + wc * 32 + n * 16 + fq * 4; const size_t off = (size_t)row * DM + col;
;             f32x4 g;
; #pragma unroll
;             for (int j = 0; j < 4; ++j) g[j] = 1.f / (1.f + __expf(-rstd * acc[ai][bj][m][n][j]));
;             const u32x2 pw = *(const u32x2*)(PT + off); f32x4 pp; pp.x = __uint_as_float(pw.x << 16); pp.y = __uint_as_float(pw.x & 0xffff0000u); pp.z = __uint_as_float(pw.y << 16); pp.w = __uint_as_float(pw.y & 0xffff0000u);
;             const u32x2 xw = *(const u32x2*)(X1B + off); f32x4 x1; x1.x = __uint_as_float(xw.x << 16); x1.y = __uint_as_float(xw.x & 0xffff0000u); x1.z = __uint_as_float(xw.y << 16); x1.w = __uint_as_float(xw.y & 0xffff0000u);
;             const f32x4 xn = x1 + pp * g;
;             if (layer != 0) *(f32x4*)(out + off) = xn;
;             if (layer == 0) {
;               rs += xn.x * xn.x + xn.y * xn.y + xn.z * xn.z + xn.w * xn.w;
;               u32x2 w; w.x = cvtpk(xn.x, xn.y); w.y = cvtpk(xn.z, xn.w); *(u32x2*)(H + off) = w;
;             }
;           }
;         if (layer == 0) { rs += __shfl_xor(rs, 16); rs += __shfl_xor(rs, 32); if (fq == 0) atomicAdd(ss1 + row, rs); }
	v_lshlrev_b32_e32 v42, 16, v38
	v_and_b32_e32 v43, 0xffff0000, v38
	v_lshlrev_b32_e32 v38, 16, v39
	v_and_b32_e32 v39, 0xffff0000, v39
	v_pk_fma_f32 v[38:39], v[46:47], v[40:41], v[38:39]
	v_pk_fma_f32 v[36:37], v[44:45], v[36:37], v[42:43]
	v_cvt_pk_bf16_f32 v41, v38, v39
	v_cvt_pk_bf16_f32 v40, v36, v37
	v_lshl_add_u64 v[42:43], s[28:29], 0, v[54:55]
	global_store_dwordx2 v[42:43], v[40:41], off
	v_lshl_add_u64 v[42:43], v[50:51], 0, v[116:117]
	v_lshlrev_b64 v[42:43], 1, v[42:43]
	v_lshl_add_u64 v[44:45], s[18:19], 0, v[42:43]
	global_load_dwordx2 v[40:41], v[52:53], off offset:288
	v_exp_f32_e32 v32, v32
	global_load_dwordx2 v[44:45], v[44:45], off
	v_exp_f32_e32 v33, v33
	v_mul_f32_e32 v37, v37, v37
	v_fmac_f32_e32 v37, v36, v36
	v_fmac_f32_e32 v37, v38, v38
	v_pk_add_f32 v[32:33], v[32:33], 1.0 op_sel_hi:[1,0]
	v_fmac_f32_e32 v37, v39, v39
	v_add_f32_e32 v46, v37, v56
	v_mul_f32_e64 v34, v34, -v72
	v_mul_f32_e64 v35, v35, -v72
	v_mul_f32_e32 v34, 0x3fb8aa3b, v34
	v_mul_f32_e32 v35, 0x3fb8aa3b, v35
	v_exp_f32_e32 v34, v34
	v_exp_f32_e32 v35, v35
	v_rcp_f32_e32 v33, v33
	v_pk_add_f32 v[34:35], v[34:35], 1.0 op_sel_hi:[1,0]
	v_rcp_f32_e32 v32, v32
	v_rcp_f32_e32 v35, v35
	v_rcp_f32_e32 v34, v34
	s_waitcnt vmcnt(1)
	v_lshlrev_b32_e32 v36, 16, v40
	v_and_b32_e32 v37, 0xffff0000, v40
	v_lshlrev_b32_e32 v38, 16, v41
	v_and_b32_e32 v39, 0xffff0000, v41
	s_waitcnt vmcnt(0)
	v_lshlrev_b32_e32 v40, 16, v44
	v_and_b32_e32 v41, 0xffff0000, v44
	v_pk_fma_f32 v[36:37], v[32:33], v[36:37], v[40:41]
	v_lshlrev_b32_e32 v44, 16, v45
	v_and_b32_e32 v45, 0xffff0000, v45
	v_mul_f32_e32 v32, v37, v37
	v_pk_fma_f32 v[34:35], v[34:35], v[38:39], v[44:45]
	v_fmac_f32_e32 v32, v36, v36
	v_fmac_f32_e32 v32, v34, v34
	v_fmac_f32_e32 v32, v35, v35
	v_add_f32_e32 v32, v46, v32
	ds_bpermute_b32 v33, v124, v32
	v_cvt_pk_bf16_f32 v36, v36, v37
	v_cvt_pk_bf16_f32 v37, v34, v35
	v_lshl_add_u64 v[34:35], s[28:29], 0, v[42:43]
	global_store_dwordx2 v[34:35], v[36:37], off
	s_waitcnt lgkmcnt(0)
	v_add_f32_e32 v32, v32, v33
	ds_bpermute_b32 v33, v125, v32
	s_and_saveexec_b64 s[0:1], s[6:7]
	s_cbranch_execz .LBB0_2384
	s_waitcnt lgkmcnt(0)
	v_add_f32_e32 v34, v32, v33
	v_lshl_add_u64 v[32:33], v[48:49], 2, s[22:23]
	global_atomic_add_f32 v[32:33], v34, off
.LBB0_2384:
	s_or_b64 exec, exec, s[0:1]
	v_add_u32_e32 v32, 0xa0, v146
	s_waitcnt lgkmcnt(0)
	v_ashrrev_i32_e32 v33, 31, v32
	v_lshl_add_u64 v[34:35], v[32:33], 2, s[24:25]
	global_load_dword v52, v[34:35], off
	v_lshlrev_b64 v[34:35], 10, v[32:33]
	v_lshl_add_u64 v[36:37], v[34:35], 0, v[140:141]
	v_lshlrev_b64 v[42:43], 1, v[36:37]
	v_lshl_add_u64 v[38:39], s[18:19], 0, v[42:43]
	global_load_dwordx2 v[40:41], v[38:39], off
	v_lshl_add_u64 v[36:37], s[16:17], 0, v[42:43]
	global_load_dwordx2 v[44:45], v[36:37], off
	global_load_dwordx2 v[50:51], v[36:37], off offset:32
	v_lshl_add_u64 v[38:39], v[34:35], 0, v[142:143]
	v_lshl_add_u64 v[46:47], v[34:35], 0, v[144:145]
	v_lshlrev_b64 v[48:49], 1, v[38:39]
	v_lshl_add_u64 v[42:43], s[28:29], 0, v[42:43]
	v_lshlrev_b64 v[38:39], 1, v[46:47]
	v_lshl_add_u64 v[46:47], s[18:19], 0, v[48:49]
	s_waitcnt vmcnt(3)
	v_fmamk_f32 v52, v52, 0x3a800000, v158
	v_mul_f32_e32 v53, 0x4b800000, v52
	v_cmp_gt_f32_e32 vcc, s54, v52
	s_waitcnt vmcnt(2)
	v_lshlrev_b32_e32 v54, 16, v40
	v_cndmask_b32_e32 v52, v52, v53, vcc
	v_rsq_f32_e32 v56, v52
	v_and_b32_e32 v55, 0xffff0000, v40
	s_waitcnt vmcnt(1)
	v_lshlrev_b32_e32 v52, 16, v44
	v_and_b32_e32 v53, 0xffff0000, v44
	v_mul_f32_e32 v40, 0x45800000, v56
	v_cndmask_b32_e32 v56, v56, v40, vcc
	v_mul_f32_e64 v28, v28, -v56
	v_mul_f32_e64 v29, v29, -v56
	v_mul_f32_e32 v28, 0x3fb8aa3b, v28
	v_mul_f32_e32 v29, 0x3fb8aa3b, v29
	v_mul_f32_e64 v30, v30, -v56
	v_mul_f32_e64 v31, v31, -v56
	v_exp_f32_e32 v28, v28
	v_exp_f32_e32 v29, v29
	v_mul_f32_e32 v30, 0x3fb8aa3b, v30
	v_mul_f32_e32 v31, 0x3fb8aa3b, v31
	v_exp_f32_e32 v30, v30
	v_exp_f32_e32 v31, v31
	v_pk_add_f32 v[28:29], v[28:29], 1.0 op_sel_hi:[1,0]
	v_lshlrev_b32_e32 v44, 16, v45
	v_pk_add_f32 v[30:31], v[30:31], 1.0 op_sel_hi:[1,0]
	v_div_scale_f32 v60, s[10:11], 1.0, v28, 1.0
	v_div_scale_f32 v62, s[12:13], 1.0, v31, 1.0
	v_div_scale_f32 v64, s[14:15], 1.0, v30, 1.0
	s_mov_b64 vcc, s[10:11]
	v_rcp_f32_e32 v29, v29
	s_mov_b64 vcc, s[12:13]
	v_rcp_f32_e32 v28, v28
	s_mov_b64 vcc, s[14:15]
	v_rcp_f32_e32 v31, v31
	v_and_b32_e32 v45, 0xffff0000, v45
	v_lshlrev_b32_e32 v40, 16, v41
	v_and_b32_e32 v41, 0xffff0000, v41
	v_rcp_f32_e32 v30, v30
	v_pk_fma_f32 v[28:29], v[28:29], v[52:53], v[54:55]
	v_pk_fma_f32 v[30:31], v[30:31], v[44:45], v[40:41]
	v_cvt_pk_bf16_f32 v52, v28, v29
	v_cvt_pk_bf16_f32 v53, v30, v31
	global_store_dwordx2 v[42:43], v[52:53], off
	global_load_dwordx2 v[40:41], v[46:47], off
	v_mul_f32_e64 v24, v24, -v56
	v_mul_f32_e64 v25, v25, -v56
	s_waitcnt vmcnt(2)
	v_lshlrev_b32_e32 v46, 16, v50
	v_and_b32_e32 v47, 0xffff0000, v50
	v_mul_f32_e64 v50, v20, -v56
	v_mul_f32_e32 v20, 0x3fb8aa3b, v24
	v_mul_f32_e32 v25, 0x3fb8aa3b, v25
	v_mul_f32_e64 v26, v26, -v56
	v_mul_f32_e64 v27, v27, -v56
	v_exp_f32_e32 v24, v20
	v_exp_f32_e32 v25, v25
	v_mul_f32_e32 v26, 0x3fb8aa3b, v26
	v_mul_f32_e32 v27, 0x3fb8aa3b, v27
	v_exp_f32_e32 v26, v26
	v_exp_f32_e32 v27, v27
	v_pk_add_f32 v[24:25], v[24:25], 1.0 op_sel_hi:[1,0]
	v_mul_f32_e64 v52, v22, -v56
	v_lshl_add_u64 v[42:43], s[28:29], 0, v[48:49]
	v_lshlrev_b32_e32 v48, 16, v51
	v_and_b32_e32 v49, 0xffff0000, v51
	v_mul_f32_e64 v51, v21, -v56
	v_pk_add_f32 v[20:21], v[26:27], 1.0 op_sel_hi:[1,0]
	v_div_scale_f32 v53, s[10:11], 1.0, v24, 1.0
	v_div_scale_f32 v55, s[12:13], 1.0, v21, 1.0
	v_div_scale_f32 v58, s[14:15], 1.0, v20, 1.0
	s_mov_b64 vcc, s[10:11]
	v_rcp_f32_e32 v25, v25
	s_mov_b64 vcc, s[12:13]
	v_rcp_f32_e32 v24, v24
	s_mov_b64 vcc, s[14:15]
	v_rcp_f32_e32 v21, v21
	v_rcp_f32_e32 v20, v20
	v_lshl_add_u64 v[44:45], s[18:19], 0, v[38:39]
	v_mul_f32_e64 v16, v16, -v56
	s_waitcnt vmcnt(0)
; DI unsigned cvtpk(float lo, float hi) { f32x2_t v = {lo, hi}; bf16x2_t b = __builtin_convertvector(v, bf16x2_t); return __builtin_bit_cast(unsigned, b); }
;   DI void operator()(const f32x4 (&acc)[2][2][4][2], const pg8::Unit& u, int wr, int wc, int fr, int fq) const {
;     ...
;         const int row = u.pm * 256 + ai * 128 + wr * 64 + m * 16 + fr; float rs = 0.f;
;         const float rstd = rsqrtf(ssx[row] * (1.f / DM) + EPS);
; #pragma unroll
;         for (int bj = 0; bj < 2; ++bj)
; #pragma unroll
;           for (int n = 0; n < 2; ++n) {
;             const int col = u.pn * 256 + bj * 128 + wc * 32 + n * 16 + fq * 4; const size_t off = (size_t)row * DM + col;
;             f32x4 g;
; #pragma unroll
;             for (int j = 0; j < 4; ++j) g[j] = 1.f / (1.f + __expf(-rstd * acc[ai][bj][m][n][j]));
;             const u32x2 pw = *(const u32x2*)(PT + off); f32x4 pp; pp.x = __uint_as_float(pw.x << 16); pp.y = __uint_as_float(pw.x & 0xffff0000u); pp.z = __uint_as_float(pw.y << 16); pp.w = __uint_as_float(pw.y & 0xffff0000u);
;             const u32x2 xw = *(const u32x2*)(X1B + off); f32x4 x1; x1.x = __uint_as_float(xw.x << 16); x1.y = __uint_as_float(xw.x & 0xffff0000u); x1.z = __uint_as_float(xw.y << 16); x1.w = __uint_as_float(xw.y & 0xffff0000u);
;             const f32x4 xn = x1 + pp * g;
;             if (layer != 0) *(f32x4*)(out + off) = xn;
;             if (layer == 0) {
;               rs += xn.x * xn.x + xn.y * xn.y + xn.z * xn.z + xn.w * xn.w;
;               u32x2 w; w.x = cvtpk(xn.x, xn.y); w.y = cvtpk(xn.z, xn.w); *(u32x2*)(H + off) = w;
;             }
;           }
;         if (layer == 0) { rs += __shfl_xor(rs, 16); rs += __shfl_xor(rs, 32); if (fq == 0) atomicAdd(ss1 + row, rs); }
	v_lshlrev_b32_e32 v26, 16, v40
	v_and_b32_e32 v27, 0xffff0000, v40
	v_lshlrev_b32_e32 v40, 16, v41
	v_and_b32_e32 v41, 0xffff0000, v41
	v_pk_fma_f32 v[20:21], v[20:21], v[48:49], v[40:41]
	v_pk_fma_f32 v[24:25], v[24:25], v[46:47], v[26:27]
	v_cvt_pk_bf16_f32 v27, v20, v21
	v_cvt_pk_bf16_f32 v26, v24, v25
	global_store_dwordx2 v[42:43], v[26:27], off
	global_load_dwordx2 v[26:27], v[36:37], off offset:256
	v_mul_f32_e64 v40, v23, -v56
	global_load_dwordx2 v[22:23], v[44:45], off
	v_mul_f32_e32 v41, 0x3fb8aa3b, v50
	v_mul_f32_e32 v46, 0x3fb8aa3b, v51
	v_mul_f32_e32 v42, 0x3fb8aa3b, v52
	v_mul_f32_e32 v43, 0x3fb8aa3b, v40
	v_exp_f32_e32 v40, v41
	v_exp_f32_e32 v42, v42
	v_exp_f32_e32 v43, v43
	v_exp_f32_e32 v41, v46
	v_mul_f32_e32 v25, v25, v25
	v_fmac_f32_e32 v25, v24, v24
	v_pk_add_f32 v[42:43], v[42:43], 1.0 op_sel_hi:[1,0]
	v_pk_add_f32 v[40:41], v[40:41], 1.0 op_sel_hi:[1,0]
	v_div_scale_f32 v47, s[10:11], 1.0, v40, 1.0
	v_div_scale_f32 v49, s[12:13], 1.0, v43, 1.0
	v_div_scale_f32 v51, s[14:15], 1.0, v42, 1.0
	v_mul_f32_e32 v48, v29, v29
	v_fmac_f32_e32 v48, v28, v28
	s_mov_b64 vcc, s[10:11]
	v_rcp_f32_e32 v29, v41
	s_mov_b64 vcc, s[12:13]
	v_fmac_f32_e32 v48, v30, v30
	s_mov_b64 vcc, s[14:15]
	v_fmac_f32_e32 v25, v20, v20
	v_fmac_f32_e32 v48, v31, v31
	v_rcp_f32_e32 v31, v43
	v_fmac_f32_e32 v25, v21, v21
	v_rcp_f32_e32 v28, v40
	v_rcp_f32_e32 v30, v42
	v_add_f32_e32 v40, v48, v25
	v_mul_f32_e64 v17, v17, -v56
	v_mul_f32_e32 v16, 0x3fb8aa3b, v16
	v_mul_f32_e32 v17, 0x3fb8aa3b, v17
	s_waitcnt vmcnt(1)
	v_lshlrev_b32_e32 v20, 16, v26
	v_and_b32_e32 v21, 0xffff0000, v26
	v_lshlrev_b32_e32 v24, 16, v27
	v_and_b32_e32 v25, 0xffff0000, v27
	s_waitcnt vmcnt(0)
	v_lshlrev_b32_e32 v26, 16, v22
	v_and_b32_e32 v27, 0xffff0000, v22
	v_lshlrev_b32_e32 v22, 16, v23
	v_and_b32_e32 v23, 0xffff0000, v23
	v_pk_fma_f32 v[22:23], v[30:31], v[24:25], v[22:23]
	v_pk_fma_f32 v[20:21], v[28:29], v[20:21], v[26:27]
	v_cvt_pk_bf16_f32 v25, v22, v23
	v_cvt_pk_bf16_f32 v24, v20, v21
	v_lshl_add_u64 v[26:27], s[28:29], 0, v[38:39]
	global_store_dwordx2 v[26:27], v[24:25], off
	v_lshl_add_u64 v[26:27], v[34:35], 0, v[116:117]
	v_lshlrev_b64 v[26:27], 1, v[26:27]
	v_lshl_add_u64 v[28:29], s[18:19], 0, v[26:27]
	global_load_dwordx2 v[24:25], v[36:37], off offset:288
	v_exp_f32_e32 v16, v16
	global_load_dwordx2 v[28:29], v[28:29], off
	v_exp_f32_e32 v17, v17
	v_mul_f32_e32 v21, v21, v21
	v_fmac_f32_e32 v21, v20, v20
	v_fmac_f32_e32 v21, v22, v22
	v_pk_add_f32 v[16:17], v[16:17], 1.0 op_sel_hi:[1,0]
	v_fmac_f32_e32 v21, v23, v23
	v_add_f32_e32 v30, v21, v40
	v_mul_f32_e64 v18, v18, -v56
	v_mul_f32_e64 v19, v19, -v56
	v_mul_f32_e32 v18, 0x3fb8aa3b, v18
	v_mul_f32_e32 v19, 0x3fb8aa3b, v19
	v_exp_f32_e32 v18, v18
	v_exp_f32_e32 v19, v19
	v_rcp_f32_e32 v17, v17
	v_pk_add_f32 v[18:19], v[18:19], 1.0 op_sel_hi:[1,0]
	v_rcp_f32_e32 v16, v16
	v_rcp_f32_e32 v19, v19
	v_rcp_f32_e32 v18, v18
	s_waitcnt vmcnt(1)
	v_lshlrev_b32_e32 v20, 16, v24
	v_and_b32_e32 v21, 0xffff0000, v24
	v_lshlrev_b32_e32 v22, 16, v25
	v_and_b32_e32 v23, 0xffff0000, v25
	s_waitcnt vmcnt(0)
	v_lshlrev_b32_e32 v24, 16, v28
	v_and_b32_e32 v25, 0xffff0000, v28
	v_pk_fma_f32 v[20:21], v[16:17], v[20:21], v[24:25]
	v_lshlrev_b32_e32 v28, 16, v29
	v_and_b32_e32 v29, 0xffff0000, v29
	v_mul_f32_e32 v16, v21, v21
	v_pk_fma_f32 v[18:19], v[18:19], v[22:23], v[28:29]
	v_fmac_f32_e32 v16, v20, v20
	v_fmac_f32_e32 v16, v18, v18
	v_fmac_f32_e32 v16, v19, v19
	v_add_f32_e32 v16, v30, v16
	ds_bpermute_b32 v17, v124, v16
	v_cvt_pk_bf16_f32 v20, v20, v21
	v_cvt_pk_bf16_f32 v21, v18, v19
	v_lshl_add_u64 v[18:19], s[28:29], 0, v[26:27]
	global_store_dwordx2 v[18:19], v[20:21], off
	s_waitcnt lgkmcnt(0)
	v_add_f32_e32 v16, v16, v17
	ds_bpermute_b32 v17, v125, v16
	s_and_saveexec_b64 s[0:1], s[6:7]
	s_cbranch_execz .LBB0_2386
	s_waitcnt lgkmcnt(0)
	v_add_f32_e32 v18, v16, v17
	v_lshl_add_u64 v[16:17], v[32:33], 2, s[22:23]
	global_atomic_add_f32 v[16:17], v18, off
.LBB0_2386:
	s_or_b64 exec, exec, s[0:1]
	v_add_u32_e32 v16, 0xb0, v146
	s_waitcnt lgkmcnt(0)
	v_ashrrev_i32_e32 v17, 31, v16
	v_lshl_add_u64 v[18:19], v[16:17], 2, s[24:25]
	global_load_dword v36, v[18:19], off
	v_lshlrev_b64 v[18:19], 10, v[16:17]
	v_lshl_add_u64 v[20:21], v[18:19], 0, v[140:141]
	v_lshlrev_b64 v[26:27], 1, v[20:21]
	v_lshl_add_u64 v[22:23], s[18:19], 0, v[26:27]
	global_load_dwordx2 v[24:25], v[22:23], off
	v_lshl_add_u64 v[20:21], s[16:17], 0, v[26:27]
	global_load_dwordx2 v[28:29], v[20:21], off
	global_load_dwordx2 v[34:35], v[20:21], off offset:32
	v_lshl_add_u64 v[22:23], v[18:19], 0, v[142:143]
	v_lshl_add_u64 v[30:31], v[18:19], 0, v[144:145]
	v_lshlrev_b64 v[32:33], 1, v[22:23]
	v_lshl_add_u64 v[26:27], s[28:29], 0, v[26:27]
	v_lshlrev_b64 v[22:23], 1, v[30:31]
	v_lshl_add_u64 v[30:31], s[18:19], 0, v[32:33]
	s_waitcnt vmcnt(3)
	v_fmamk_f32 v36, v36, 0x3a800000, v158
	v_mul_f32_e32 v37, 0x4b800000, v36
	v_cmp_gt_f32_e32 vcc, s54, v36
	s_waitcnt vmcnt(2)
	v_lshlrev_b32_e32 v38, 16, v24
	v_cndmask_b32_e32 v36, v36, v37, vcc
	v_rsq_f32_e32 v40, v36
	v_and_b32_e32 v39, 0xffff0000, v24
	s_waitcnt vmcnt(1)
; DI unsigned cvtpk(float lo, float hi) { f32x2_t v = {lo, hi}; bf16x2_t b = __builtin_convertvector(v, bf16x2_t); return __builtin_bit_cast(unsigned, b); }
;   DI void operator()(const f32x4 (&acc)[2][2][4][2], const pg8::Unit& u, int wr, int wc, int fr, int fq) const {
;     ...
;         const int row = u.pm * 256 + ai * 128 + wr * 64 + m * 16 + fr; float rs = 0.f;
;         const float rstd = rsqrtf(ssx[row] * (1.f / DM) + EPS);
; #pragma unroll
;         for (int bj = 0; bj < 2; ++bj)
; #pragma unroll
;           for (int n = 0; n < 2; ++n) {
;             const int col = u.pn * 256 + bj * 128 + wc * 32 + n * 16 + fq * 4; const size_t off = (size_t)row * DM + col;
;             f32x4 g;
; #pragma unroll
;             for (int j = 0; j < 4; ++j) g[j] = 1.f / (1.f + __expf(-rstd * acc[ai][bj][m][n][j]));
;             const u32x2 pw = *(const u32x2*)(PT + off); f32x4 pp; pp.x = __uint_as_float(pw.x << 16); pp.y = __uint_as_float(pw.x & 0xffff0000u); pp.z = __uint_as_float(pw.y << 16); pp.w = __uint_as_float(pw.y & 0xffff0000u);
;             const u32x2 xw = *(const u32x2*)(X1B + off); f32x4 x1; x1.x = __uint_as_float(xw.x << 16); x1.y = __uint_as_float(xw.x & 0xffff0000u); x1.z = __uint_as_float(xw.y << 16); x1.w = __uint_as_float(xw.y & 0xffff0000u);
;             const f32x4 xn = x1 + pp * g;
;             if (layer != 0) *(f32x4*)(out + off) = xn;
;             if (layer == 0) {
;               rs += xn.x * xn.x + xn.y * xn.y + xn.z * xn.z + xn.w * xn.w;
;               u32x2 w; w.x = cvtpk(xn.x, xn.y); w.y = cvtpk(xn.z, xn.w); *(u32x2*)(H + off) = w;
;             }
;           }
;         if (layer == 0) { rs += __shfl_xor(rs, 16); rs += __shfl_xor(rs, 32); if (fq == 0) atomicAdd(ss1 + row, rs); }
	v_lshlrev_b32_e32 v36, 16, v28
	v_and_b32_e32 v37, 0xffff0000, v28
	v_mul_f32_e32 v24, 0x45800000, v40
	v_cndmask_b32_e32 v40, v40, v24, vcc
	v_mul_f32_e64 v12, v12, -v40
	v_mul_f32_e64 v13, v13, -v40
	v_mul_f32_e32 v12, 0x3fb8aa3b, v12
	v_mul_f32_e32 v13, 0x3fb8aa3b, v13
	v_mul_f32_e64 v14, v14, -v40
	v_mul_f32_e64 v15, v15, -v40
	v_exp_f32_e32 v12, v12
	v_exp_f32_e32 v13, v13
	v_mul_f32_e32 v14, 0x3fb8aa3b, v14
	v_mul_f32_e32 v15, 0x3fb8aa3b, v15
	v_exp_f32_e32 v14, v14
	v_exp_f32_e32 v15, v15
	v_pk_add_f32 v[12:13], v[12:13], 1.0 op_sel_hi:[1,0]
	v_lshlrev_b32_e32 v28, 16, v29
	v_pk_add_f32 v[14:15], v[14:15], 1.0 op_sel_hi:[1,0]
	v_div_scale_f32 v44, s[10:11], 1.0, v12, 1.0
	v_div_scale_f32 v46, s[12:13], 1.0, v15, 1.0
	v_div_scale_f32 v48, s[14:15], 1.0, v14, 1.0
	s_mov_b64 vcc, s[10:11]
	v_rcp_f32_e32 v13, v13
	s_mov_b64 vcc, s[12:13]
	v_rcp_f32_e32 v12, v12
	s_mov_b64 vcc, s[14:15]
	v_rcp_f32_e32 v15, v15
	v_and_b32_e32 v29, 0xffff0000, v29
	v_lshlrev_b32_e32 v24, 16, v25
	v_and_b32_e32 v25, 0xffff0000, v25
	v_rcp_f32_e32 v14, v14
	v_pk_fma_f32 v[12:13], v[12:13], v[36:37], v[38:39]
	v_pk_fma_f32 v[14:15], v[14:15], v[28:29], v[24:25]
	v_cvt_pk_bf16_f32 v36, v12, v13
	v_cvt_pk_bf16_f32 v37, v14, v15
	global_store_dwordx2 v[26:27], v[36:37], off
	global_load_dwordx2 v[24:25], v[30:31], off
	v_mul_f32_e64 v8, v8, -v40
	v_mul_f32_e64 v9, v9, -v40
	s_waitcnt vmcnt(2)
	v_lshlrev_b32_e32 v30, 16, v34
	v_and_b32_e32 v31, 0xffff0000, v34
	v_mul_f32_e64 v34, v4, -v40
	v_mul_f32_e32 v4, 0x3fb8aa3b, v8
	v_mul_f32_e32 v9, 0x3fb8aa3b, v9
	v_mul_f32_e64 v10, v10, -v40
	v_mul_f32_e64 v11, v11, -v40
	v_exp_f32_e32 v8, v4
	v_exp_f32_e32 v9, v9
	v_mul_f32_e32 v10, 0x3fb8aa3b, v10
	v_mul_f32_e32 v11, 0x3fb8aa3b, v11
	v_exp_f32_e32 v10, v10
	v_exp_f32_e32 v11, v11
	v_pk_add_f32 v[8:9], v[8:9], 1.0 op_sel_hi:[1,0]
	v_mul_f32_e64 v36, v6, -v40
	v_lshl_add_u64 v[26:27], s[28:29], 0, v[32:33]
	v_lshlrev_b32_e32 v32, 16, v35
	v_and_b32_e32 v33, 0xffff0000, v35
	v_mul_f32_e64 v35, v5, -v40
	v_pk_add_f32 v[4:5], v[10:11], 1.0 op_sel_hi:[1,0]
	v_div_scale_f32 v37, s[10:11], 1.0, v8, 1.0
	v_div_scale_f32 v39, s[12:13], 1.0, v5, 1.0
	v_div_scale_f32 v42, s[14:15], 1.0, v4, 1.0
	s_mov_b64 vcc, s[10:11]
	v_rcp_f32_e32 v9, v9
	s_mov_b64 vcc, s[12:13]
	v_rcp_f32_e32 v8, v8
	s_mov_b64 vcc, s[14:15]
	v_rcp_f32_e32 v5, v5
	v_rcp_f32_e32 v4, v4
	v_lshl_add_u64 v[28:29], s[18:19], 0, v[22:23]
	v_mul_f32_e64 v0, v0, -v40
	s_waitcnt vmcnt(0)
	v_lshlrev_b32_e32 v10, 16, v24
	v_and_b32_e32 v11, 0xffff0000, v24
	v_lshlrev_b32_e32 v24, 16, v25
	v_and_b32_e32 v25, 0xffff0000, v25
	v_pk_fma_f32 v[4:5], v[4:5], v[32:33], v[24:25]
	v_pk_fma_f32 v[8:9], v[8:9], v[30:31], v[10:11]
	v_cvt_pk_bf16_f32 v11, v4, v5
	v_cvt_pk_bf16_f32 v10, v8, v9
	global_store_dwordx2 v[26:27], v[10:11], off
	global_load_dwordx2 v[10:11], v[20:21], off offset:256
	v_mul_f32_e64 v24, v7, -v40
	global_load_dwordx2 v[6:7], v[28:29], off
	v_mul_f32_e32 v25, 0x3fb8aa3b, v34
	v_mul_f32_e32 v30, 0x3fb8aa3b, v35
	v_mul_f32_e32 v26, 0x3fb8aa3b, v36
	v_mul_f32_e32 v27, 0x3fb8aa3b, v24
	v_exp_f32_e32 v24, v25
	v_exp_f32_e32 v26, v26
	v_exp_f32_e32 v27, v27
	v_exp_f32_e32 v25, v30
	v_mul_f32_e32 v9, v9, v9
	v_fmac_f32_e32 v9, v8, v8
	v_pk_add_f32 v[26:27], v[26:27], 1.0 op_sel_hi:[1,0]
	v_pk_add_f32 v[24:25], v[24:25], 1.0 op_sel_hi:[1,0]
	v_div_scale_f32 v31, s[10:11], 1.0, v24, 1.0
	v_div_scale_f32 v33, s[12:13], 1.0, v27, 1.0
	v_div_scale_f32 v35, s[14:15], 1.0, v26, 1.0
	v_mul_f32_e32 v32, v13, v13
	v_fmac_f32_e32 v32, v12, v12
	s_mov_b64 vcc, s[10:11]
	v_rcp_f32_e32 v13, v25
	s_mov_b64 vcc, s[12:13]
	v_fmac_f32_e32 v32, v14, v14
	s_mov_b64 vcc, s[14:15]
	v_fmac_f32_e32 v9, v4, v4
	v_fmac_f32_e32 v32, v15, v15
	v_rcp_f32_e32 v15, v27
	v_fmac_f32_e32 v9, v5, v5
	v_rcp_f32_e32 v12, v24
	v_rcp_f32_e32 v14, v26
	v_add_f32_e32 v24, v32, v9
	v_mul_f32_e64 v1, v1, -v40
	v_mul_f32_e32 v0, 0x3fb8aa3b, v0
	v_mul_f32_e32 v1, 0x3fb8aa3b, v1
	s_waitcnt vmcnt(1)
	v_lshlrev_b32_e32 v4, 16, v10
	v_and_b32_e32 v5, 0xffff0000, v10
	v_lshlrev_b32_e32 v8, 16, v11
	v_and_b32_e32 v9, 0xffff0000, v11
	s_waitcnt vmcnt(0)
	v_lshlrev_b32_e32 v10, 16, v6
	v_and_b32_e32 v11, 0xffff0000, v6
	v_lshlrev_b32_e32 v6, 16, v7
	v_and_b32_e32 v7, 0xffff0000, v7
	v_pk_fma_f32 v[6:7], v[14:15], v[8:9], v[6:7]
	v_pk_fma_f32 v[4:5], v[12:13], v[4:5], v[10:11]
	v_cvt_pk_bf16_f32 v9, v6, v7
	v_cvt_pk_bf16_f32 v8, v4, v5
	v_lshl_add_u64 v[10:11], s[28:29], 0, v[22:23]
	global_store_dwordx2 v[10:11], v[8:9], off
	v_lshl_add_u64 v[10:11], v[18:19], 0, v[116:117]
	v_lshlrev_b64 v[10:11], 1, v[10:11]
	v_lshl_add_u64 v[12:13], s[18:19], 0, v[10:11]
	global_load_dwordx2 v[8:9], v[20:21], off offset:288
	v_exp_f32_e32 v0, v0
	global_load_dwordx2 v[12:13], v[12:13], off
	v_exp_f32_e32 v1, v1
	v_mul_f32_e32 v5, v5, v5
	v_fmac_f32_e32 v5, v4, v4
	v_fmac_f32_e32 v5, v6, v6
	v_pk_add_f32 v[0:1], v[0:1], 1.0 op_sel_hi:[1,0]
	v_fmac_f32_e32 v5, v7, v7
	v_add_f32_e32 v14, v5, v24
	v_mul_f32_e64 v2, v2, -v40
	v_mul_f32_e64 v3, v3, -v40
	v_mul_f32_e32 v2, 0x3fb8aa3b, v2
	v_mul_f32_e32 v3, 0x3fb8aa3b, v3
	v_exp_f32_e32 v2, v2
	v_exp_f32_e32 v3, v3
	v_rcp_f32_e32 v1, v1
	v_pk_add_f32 v[2:3], v[2:3], 1.0 op_sel_hi:[1,0]
	v_rcp_f32_e32 v0, v0
	v_rcp_f32_e32 v3, v3
	v_rcp_f32_e32 v2, v2
	s_waitcnt vmcnt(1)
	v_lshlrev_b32_e32 v4, 16, v8
	v_and_b32_e32 v5, 0xffff0000, v8
	v_lshlrev_b32_e32 v6, 16, v9
	v_and_b32_e32 v7, 0xffff0000, v9
	s_waitcnt vmcnt(0)
	v_lshlrev_b32_e32 v8, 16, v12
	v_and_b32_e32 v9, 0xffff0000, v12
	v_pk_fma_f32 v[4:5], v[0:1], v[4:5], v[8:9]
	v_lshlrev_b32_e32 v12, 16, v13
	v_and_b32_e32 v13, 0xffff0000, v13
	v_mul_f32_e32 v0, v5, v5
	v_pk_fma_f32 v[2:3], v[2:3], v[6:7], v[12:13]
	v_fmac_f32_e32 v0, v4, v4
	v_fmac_f32_e32 v0, v2, v2
	v_fmac_f32_e32 v0, v3, v3
	v_add_f32_e32 v0, v14, v0
	ds_bpermute_b32 v1, v124, v0
	v_cvt_pk_bf16_f32 v4, v4, v5
	v_cvt_pk_bf16_f32 v5, v2, v3
	v_lshl_add_u64 v[2:3], s[28:29], 0, v[10:11]
	global_store_dwordx2 v[2:3], v[4:5], off
	s_waitcnt lgkmcnt(0)
	v_add_f32_e32 v0, v0, v1
	ds_bpermute_b32 v1, v125, v0
	s_and_saveexec_b64 s[0:1], s[6:7]
	s_cbranch_execz .LBB0_2388
	s_waitcnt lgkmcnt(0)
	v_add_f32_e32 v2, v0, v1
	v_lshl_add_u64 v[0:1], v[16:17], 2, s[22:23]
	global_atomic_add_f32 v[0:1], v2, off

;   DI void operator()(const f32x4 (&acc)[2][2][4][2], const pg8::Unit& u, int wr, int wc, int fr, int fq) const {
;     ...
;         if (type == T_SILU) {
; #pragma unroll
;           for (int n = 0; n < 2; ++n)
; #pragma unroll
;             for (int j = 0; j < 4; ++j) { const float a = v1[n][j]; v1[n][j] = a / (1.f + __expf(-a)); const float b = v2[n][j]; v2[n][j] = b / (1.f + __expf(-b)); }
;         }
.LBB0_2474:
	s_cmp_eq_u32 s11, 3
	s_cselect_b64 s[14:15], -1, 0
	s_cmp_lg_u32 s11, 3
	s_cbranch_scc1 .LBB0_2476
	v_mul_f32_e32 v161, 0xbfb8aa3b, v117
	v_exp_f32_e32 v163, v161
	v_mul_f32_e32 v161, 0xbfb8aa3b, v126
	v_exp_f32_e32 v164, v161
	v_mul_f32_e32 v161, 0xbfb8aa3b, v118
	v_exp_f32_e32 v166, v161
	v_mul_f32_e32 v161, 0xbfb8aa3b, v127
	v_mul_f32_e32 v171, 0xbfb8aa3b, v150
	v_exp_f32_e32 v165, v161
	v_mul_f32_e32 v161, 0xbfb8aa3b, v119
	v_exp_f32_e32 v172, v171
	v_mul_f32_e32 v171, 0xbfb8aa3b, v151
	v_exp_f32_e32 v167, v161
	v_mul_f32_e32 v161, 0xbfb8aa3b, v120
	v_exp_f32_e32 v173, v171
	v_exp_f32_e32 v168, v161
	v_mul_f32_e32 v161, 0xbfb8aa3b, v114
	v_exp_f32_e32 v170, v161
	v_mul_f32_e32 v161, 0xbfb8aa3b, v121
	v_exp_f32_e32 v169, v161
	v_mul_f32_e32 v161, 0xbfb8aa3b, v115
	v_exp_f32_e32 v171, v161
	v_mul_f32_e32 v161, 0xbfb8aa3b, v122
	v_pk_add_f32 v[172:173], v[172:173], 1.0 op_sel_hi:[1,0]
	v_exp_f32_e32 v174, v161
	v_pk_add_f32 v[168:169], v[168:169], 1.0 op_sel_hi:[1,0]
	v_pk_add_f32 v[164:165], v[164:165], 1.0 op_sel_hi:[1,0]
	v_mul_f32_e32 v113, 0xbfb8aa3b, v116
	v_rcp_f32_e32 v161, v173
	s_nop 0
	v_mul_f32_e32 v151, v151, v161
	v_mul_f32_e32 v112, 0xbfb8aa3b, v124
	v_rcp_f32_e32 v161, v172
	s_nop 0
	v_mul_f32_e32 v150, v150, v161
	v_exp_f32_e32 v162, v113
	v_rcp_f32_e32 v161, v169
	s_nop 0
	v_mul_f32_e32 v121, v121, v161
	v_mul_f32_e32 v113, 0xbfb8aa3b, v125
	v_rcp_f32_e32 v161, v168
	s_nop 0
	v_mul_f32_e32 v120, v120, v161
	v_exp_f32_e32 v112, v112
	v_exp_f32_e32 v113, v113
	v_rcp_f32_e32 v161, v165
	s_nop 0
	v_mul_f32_e32 v127, v127, v161
	v_pk_add_f32 v[112:113], v[112:113], 1.0 op_sel_hi:[1,0]
	v_rcp_f32_e32 v161, v164
	s_nop 0
	v_mul_f32_e32 v126, v126, v161
	v_pk_add_f32 v[162:163], v[162:163], 1.0 op_sel_hi:[1,0]
	v_rcp_f32_e32 v161, v113
	s_nop 0
	v_mul_f32_e32 v125, v125, v161
	v_mul_f32_e32 v164, 0xbfb8aa3b, v123
	v_exp_f32_e32 v175, v164
	v_rcp_f32_e32 v113, v112
	s_nop 0
	v_mul_f32_e32 v124, v124, v113
	v_pk_add_f32 v[112:113], v[174:175], 1.0 op_sel_hi:[1,0]
	v_pk_add_f32 v[164:165], v[166:167], 1.0 op_sel_hi:[1,0]
	v_pk_add_f32 v[166:167], v[170:171], 1.0 op_sel_hi:[1,0]
	v_rcp_f32_e32 v161, v113
	s_nop 0
	v_mul_f32_e32 v123, v123, v161
	v_rcp_f32_e32 v113, v112
	s_nop 0
	v_mul_f32_e32 v122, v122, v113
	v_rcp_f32_e32 v112, v167
	s_nop 0
	v_mul_f32_e32 v115, v115, v112
	v_rcp_f32_e32 v112, v166
	s_nop 0
	v_mul_f32_e32 v114, v114, v112
	v_rcp_f32_e32 v112, v165
	s_nop 0
	v_mul_f32_e32 v119, v119, v112
	v_rcp_f32_e32 v112, v164
	s_nop 0
	v_mul_f32_e32 v118, v118, v112
	v_rcp_f32_e32 v112, v163
	s_nop 0
	v_mul_f32_e32 v117, v117, v112
	v_rcp_f32_e32 v112, v162
	s_nop 0
	v_mul_f32_e32 v116, v116, v112

;   DI void operator()(const f32x4 (&acc)[2][2][4][2], const pg8::Unit& u, int wr, int wc, int fr, int fq) const {
;     ...
;         if (type == T_SILU) {
; #pragma unroll
;           for (int n = 0; n < 2; ++n)
; #pragma unroll
;             for (int j = 0; j < 4; ++j) { const float a = v1[n][j]; v1[n][j] = a / (1.f + __expf(-a)); const float b = v2[n][j]; v2[n][j] = b / (1.f + __expf(-b)); }
;         }
.LBB0_2479:
	v_mul_f32_e32 v148, 0xbfb8aa3b, v106
	v_mul_f32_e32 v149, 0xbfb8aa3b, v107
	v_exp_f32_e32 v148, v148
	v_exp_f32_e32 v149, v149
	v_mul_f32_e32 v125, 0xbfb8aa3b, v96
	v_mul_f32_e32 v124, 0xbfb8aa3b, v100
	v_exp_f32_e32 v126, v125
	v_pk_add_f32 v[148:149], v[148:149], 1.0 op_sel_hi:[1,0]
	v_mul_f32_e32 v125, 0xbfb8aa3b, v101
	v_exp_f32_e32 v124, v124
	v_exp_f32_e32 v125, v125
	v_mul_f32_e32 v121, 0xbfb8aa3b, v102
	v_rcp_f32_e32 v151, v149
	s_nop 0
	v_mul_f32_e32 v107, v107, v151
	v_pk_add_f32 v[124:125], v[124:125], 1.0 op_sel_hi:[1,0]
	v_rcp_f32_e32 v149, v148
	s_nop 0
	v_mul_f32_e32 v106, v106, v149
	v_mul_f32_e32 v120, 0xbfb8aa3b, v110
	v_exp_f32_e32 v122, v121
	v_mul_f32_e32 v121, 0xbfb8aa3b, v111
	v_exp_f32_e32 v120, v120
	v_exp_f32_e32 v121, v121
	v_rcp_f32_e32 v148, v125
	s_nop 0
	v_mul_f32_e32 v101, v101, v148
	v_pk_add_f32 v[120:121], v[120:121], 1.0 op_sel_hi:[1,0]
	v_rcp_f32_e32 v125, v124
	s_nop 0
	v_mul_f32_e32 v100, v100, v125
	v_mul_f32_e32 v105, 0xbfb8aa3b, v108
	v_mul_f32_e32 v104, 0xbfb8aa3b, v116
	v_exp_f32_e32 v118, v105
	v_mul_f32_e32 v105, 0xbfb8aa3b, v117
	v_exp_f32_e32 v104, v104
	v_exp_f32_e32 v105, v105
	v_rcp_f32_e32 v124, v121
	s_nop 0
	v_mul_f32_e32 v111, v111, v124
	v_pk_add_f32 v[104:105], v[104:105], 1.0 op_sel_hi:[1,0]
	v_rcp_f32_e32 v121, v120
	s_nop 0
	v_mul_f32_e32 v110, v110, v121
	v_mul_f32_e32 v150, 0xbfb8aa3b, v98
	v_rcp_f32_e32 v120, v105
	s_nop 0
	v_mul_f32_e32 v117, v117, v120
	v_exp_f32_e32 v150, v150
	v_mul_f32_e32 v121, 0xbfb8aa3b, v99
	v_exp_f32_e32 v151, v121
	v_rcp_f32_e32 v105, v104
	s_nop 0
	v_mul_f32_e32 v116, v116, v105
	v_pk_add_f32 v[104:105], v[150:151], 1.0 op_sel_hi:[1,0]
	v_mul_f32_e32 v123, 0xbfb8aa3b, v103
	v_mul_f32_e32 v127, 0xbfb8aa3b, v97
	v_exp_f32_e32 v123, v123
	v_exp_f32_e32 v127, v127
	v_mul_f32_e32 v119, 0xbfb8aa3b, v109
	v_pk_add_f32 v[120:121], v[122:123], 1.0 op_sel_hi:[1,0]
	v_pk_add_f32 v[122:123], v[126:127], 1.0 op_sel_hi:[1,0]
	v_rcp_f32_e32 v124, v105
	s_nop 0
	v_mul_f32_e32 v99, v99, v124
	v_exp_f32_e32 v119, v119
	v_rcp_f32_e32 v105, v104
	s_nop 0
	v_mul_f32_e32 v98, v98, v105
	v_pk_add_f32 v[118:119], v[118:119], 1.0 op_sel_hi:[1,0]
	v_rcp_f32_e32 v104, v123
	s_nop 0
	v_mul_f32_e32 v97, v97, v104
	v_rcp_f32_e32 v104, v122
	s_nop 0
	v_mul_f32_e32 v96, v96, v104
	v_rcp_f32_e32 v104, v121
	s_nop 0
	v_mul_f32_e32 v103, v103, v104
	v_rcp_f32_e32 v104, v120
	s_nop 0
	v_mul_f32_e32 v102, v102, v104
	v_rcp_f32_e32 v104, v119
	s_nop 0
	v_mul_f32_e32 v109, v109, v104
	v_rcp_f32_e32 v104, v118
	s_nop 0
	v_mul_f32_e32 v108, v108, v104

;   DI void operator()(const f32x4 (&acc)[2][2][4][2], const pg8::Unit& u, int wr, int wc, int fr, int fq) const {
;     ...
;         if (type == T_SILU) {
; #pragma unroll
;           for (int n = 0; n < 2; ++n)
; #pragma unroll
;             for (int j = 0; j < 4; ++j) { const float a = v1[n][j]; v1[n][j] = a / (1.f + __expf(-a)); const float b = v2[n][j]; v2[n][j] = b / (1.f + __expf(-b)); }
;         }
.LBB0_2483:
	v_mul_f32_e32 v110, 0xbfb8aa3b, v90
	v_mul_f32_e32 v111, 0xbfb8aa3b, v91
	v_exp_f32_e32 v110, v110
	v_exp_f32_e32 v111, v111
	v_mul_f32_e32 v107, 0xbfb8aa3b, v80
	v_mul_f32_e32 v106, 0xbfb8aa3b, v84
	v_exp_f32_e32 v108, v107
	v_pk_add_f32 v[110:111], v[110:111], 1.0 op_sel_hi:[1,0]
	v_mul_f32_e32 v107, 0xbfb8aa3b, v85
	v_exp_f32_e32 v106, v106
	v_exp_f32_e32 v107, v107
	v_mul_f32_e32 v103, 0xbfb8aa3b, v86
	v_rcp_f32_e32 v115, v111
	s_nop 0
	v_mul_f32_e32 v91, v91, v115
	v_pk_add_f32 v[106:107], v[106:107], 1.0 op_sel_hi:[1,0]
	v_rcp_f32_e32 v111, v110
	s_nop 0
	v_mul_f32_e32 v90, v90, v111
	v_mul_f32_e32 v102, 0xbfb8aa3b, v94
	v_exp_f32_e32 v104, v103
	v_mul_f32_e32 v103, 0xbfb8aa3b, v95
	v_exp_f32_e32 v102, v102
	v_exp_f32_e32 v103, v103
	v_rcp_f32_e32 v110, v107
	s_nop 0
	v_mul_f32_e32 v85, v85, v110
	v_pk_add_f32 v[102:103], v[102:103], 1.0 op_sel_hi:[1,0]
	v_rcp_f32_e32 v107, v106
	s_nop 0
	v_mul_f32_e32 v84, v84, v107
	v_mul_f32_e32 v89, 0xbfb8aa3b, v92
	v_mul_f32_e32 v88, 0xbfb8aa3b, v98
	v_exp_f32_e32 v100, v89
	v_mul_f32_e32 v89, 0xbfb8aa3b, v99
	v_exp_f32_e32 v88, v88
	v_exp_f32_e32 v89, v89
	v_rcp_f32_e32 v106, v103
	s_nop 0
	v_mul_f32_e32 v95, v95, v106
	v_pk_add_f32 v[88:89], v[88:89], 1.0 op_sel_hi:[1,0]
	v_rcp_f32_e32 v103, v102
	s_nop 0
	v_mul_f32_e32 v94, v94, v103
	v_mul_f32_e32 v114, 0xbfb8aa3b, v82
	v_rcp_f32_e32 v102, v89
	s_nop 0
	v_mul_f32_e32 v99, v99, v102
	v_exp_f32_e32 v114, v114
	v_mul_f32_e32 v103, 0xbfb8aa3b, v83
	v_exp_f32_e32 v115, v103
	v_rcp_f32_e32 v89, v88
	s_nop 0
	v_mul_f32_e32 v98, v98, v89
	v_pk_add_f32 v[88:89], v[114:115], 1.0 op_sel_hi:[1,0]
	v_mul_f32_e32 v105, 0xbfb8aa3b, v87
	v_mul_f32_e32 v109, 0xbfb8aa3b, v81
	v_exp_f32_e32 v105, v105
	v_exp_f32_e32 v109, v109
	v_mul_f32_e32 v101, 0xbfb8aa3b, v93
	v_pk_add_f32 v[102:103], v[104:105], 1.0 op_sel_hi:[1,0]
	v_pk_add_f32 v[104:105], v[108:109], 1.0 op_sel_hi:[1,0]
	v_rcp_f32_e32 v106, v89
	s_nop 0
	v_mul_f32_e32 v83, v83, v106
	v_exp_f32_e32 v101, v101
	v_rcp_f32_e32 v89, v88
	s_nop 0
	v_mul_f32_e32 v82, v82, v89
	v_pk_add_f32 v[100:101], v[100:101], 1.0 op_sel_hi:[1,0]
	v_rcp_f32_e32 v88, v105
	s_nop 0
	v_mul_f32_e32 v81, v81, v88
	v_rcp_f32_e32 v88, v104
	s_nop 0
	v_mul_f32_e32 v80, v80, v88
	v_rcp_f32_e32 v88, v103
	s_nop 0
	v_mul_f32_e32 v87, v87, v88
	v_rcp_f32_e32 v88, v102
	s_nop 0
	v_mul_f32_e32 v86, v86, v88
	v_rcp_f32_e32 v88, v101
	s_nop 0
	v_mul_f32_e32 v93, v93, v88
	v_rcp_f32_e32 v88, v100
	s_nop 0
	v_mul_f32_e32 v92, v92, v88

;   DI void operator()(const f32x4 (&acc)[2][2][4][2], const pg8::Unit& u, int wr, int wc, int fr, int fq) const {
;     ...
;         if (type == T_SILU) {
; #pragma unroll
;           for (int n = 0; n < 2; ++n)
; #pragma unroll
;             for (int j = 0; j < 4; ++j) { const float a = v1[n][j]; v1[n][j] = a / (1.f + __expf(-a)); const float b = v2[n][j]; v2[n][j] = b / (1.f + __expf(-b)); }
;         }
.LBB0_2487:
	v_mul_f32_e32 v94, 0xbfb8aa3b, v74
	v_mul_f32_e32 v95, 0xbfb8aa3b, v75
	v_exp_f32_e32 v94, v94
	v_exp_f32_e32 v95, v95
	v_mul_f32_e32 v91, 0xbfb8aa3b, v64
	v_mul_f32_e32 v90, 0xbfb8aa3b, v68
	v_exp_f32_e32 v92, v91
	v_pk_add_f32 v[94:95], v[94:95], 1.0 op_sel_hi:[1,0]
	v_mul_f32_e32 v91, 0xbfb8aa3b, v69
	v_exp_f32_e32 v90, v90
	v_exp_f32_e32 v91, v91
	v_mul_f32_e32 v87, 0xbfb8aa3b, v70
	v_rcp_f32_e32 v97, v95
	s_nop 0
	v_mul_f32_e32 v75, v75, v97
	v_pk_add_f32 v[90:91], v[90:91], 1.0 op_sel_hi:[1,0]
	v_rcp_f32_e32 v95, v94
	s_nop 0
	v_mul_f32_e32 v74, v74, v95
	v_mul_f32_e32 v86, 0xbfb8aa3b, v78
	v_exp_f32_e32 v88, v87
	v_mul_f32_e32 v87, 0xbfb8aa3b, v79
	v_exp_f32_e32 v86, v86
	v_exp_f32_e32 v87, v87
	v_rcp_f32_e32 v94, v91
	s_nop 0
	v_mul_f32_e32 v69, v69, v94
	v_pk_add_f32 v[86:87], v[86:87], 1.0 op_sel_hi:[1,0]
	v_rcp_f32_e32 v91, v90
	s_nop 0
	v_mul_f32_e32 v68, v68, v91
	v_mul_f32_e32 v73, 0xbfb8aa3b, v76
	v_mul_f32_e32 v72, 0xbfb8aa3b, v82
	v_exp_f32_e32 v84, v73
	v_mul_f32_e32 v73, 0xbfb8aa3b, v83
	v_exp_f32_e32 v72, v72
	v_exp_f32_e32 v73, v73
	v_rcp_f32_e32 v90, v87
	s_nop 0
	v_mul_f32_e32 v79, v79, v90
	v_pk_add_f32 v[72:73], v[72:73], 1.0 op_sel_hi:[1,0]
	v_rcp_f32_e32 v87, v86
	s_nop 0
	v_mul_f32_e32 v78, v78, v87
	v_mul_f32_e32 v96, 0xbfb8aa3b, v66
	v_rcp_f32_e32 v86, v73
	s_nop 0
	v_mul_f32_e32 v83, v83, v86
	v_exp_f32_e32 v96, v96
	v_mul_f32_e32 v87, 0xbfb8aa3b, v67
	v_exp_f32_e32 v97, v87
	v_rcp_f32_e32 v73, v72
	s_nop 0
	v_mul_f32_e32 v82, v82, v73
	v_pk_add_f32 v[72:73], v[96:97], 1.0 op_sel_hi:[1,0]
	v_mul_f32_e32 v89, 0xbfb8aa3b, v71
	v_mul_f32_e32 v93, 0xbfb8aa3b, v65
	v_exp_f32_e32 v89, v89
	v_exp_f32_e32 v93, v93
	v_mul_f32_e32 v85, 0xbfb8aa3b, v77
	v_pk_add_f32 v[86:87], v[88:89], 1.0 op_sel_hi:[1,0]
	v_pk_add_f32 v[88:89], v[92:93], 1.0 op_sel_hi:[1,0]
	v_rcp_f32_e32 v90, v73
	s_nop 0
	v_mul_f32_e32 v67, v67, v90
	v_exp_f32_e32 v85, v85
	v_rcp_f32_e32 v73, v72
	s_nop 0
	v_mul_f32_e32 v66, v66, v73
	v_pk_add_f32 v[84:85], v[84:85], 1.0 op_sel_hi:[1,0]
	v_rcp_f32_e32 v72, v89
	s_nop 0
	v_mul_f32_e32 v65, v65, v72
	v_rcp_f32_e32 v72, v88
	s_nop 0
	v_mul_f32_e32 v64, v64, v72
	v_rcp_f32_e32 v72, v87
	s_nop 0
	v_mul_f32_e32 v71, v71, v72
	v_rcp_f32_e32 v72, v86
	s_nop 0
	v_mul_f32_e32 v70, v70, v72
	v_rcp_f32_e32 v72, v85
	s_nop 0
	v_mul_f32_e32 v77, v77, v72
	v_rcp_f32_e32 v72, v84
	s_nop 0
	v_mul_f32_e32 v76, v76, v72

;   DI void operator()(const f32x4 (&acc)[2][2][4][2], const pg8::Unit& u, int wr, int wc, int fr, int fq) const {
;     ...
;         if (type == T_SILU) {
; #pragma unroll
;           for (int n = 0; n < 2; ++n)
; #pragma unroll
;             for (int j = 0; j < 4; ++j) { const float a = v1[n][j]; v1[n][j] = a / (1.f + __expf(-a)); const float b = v2[n][j]; v2[n][j] = b / (1.f + __expf(-b)); }
;         }
.LBB0_2491:
	v_mul_f32_e32 v78, 0xbfb8aa3b, v58
	v_mul_f32_e32 v79, 0xbfb8aa3b, v59
	v_exp_f32_e32 v78, v78
	v_exp_f32_e32 v79, v79
	v_mul_f32_e32 v75, 0xbfb8aa3b, v48
	v_mul_f32_e32 v74, 0xbfb8aa3b, v52
	v_exp_f32_e32 v76, v75
	v_pk_add_f32 v[78:79], v[78:79], 1.0 op_sel_hi:[1,0]
	v_mul_f32_e32 v75, 0xbfb8aa3b, v53
	v_exp_f32_e32 v74, v74
	v_exp_f32_e32 v75, v75
	v_mul_f32_e32 v71, 0xbfb8aa3b, v54
	v_rcp_f32_e32 v81, v79
	s_nop 0
	v_mul_f32_e32 v59, v59, v81
	v_pk_add_f32 v[74:75], v[74:75], 1.0 op_sel_hi:[1,0]
	v_rcp_f32_e32 v79, v78
	s_nop 0
	v_mul_f32_e32 v58, v58, v79
	v_mul_f32_e32 v70, 0xbfb8aa3b, v62
	v_exp_f32_e32 v72, v71
	v_mul_f32_e32 v71, 0xbfb8aa3b, v63
	v_exp_f32_e32 v70, v70
	v_exp_f32_e32 v71, v71
	v_rcp_f32_e32 v78, v75
	s_nop 0
	v_mul_f32_e32 v53, v53, v78
	v_pk_add_f32 v[70:71], v[70:71], 1.0 op_sel_hi:[1,0]
	v_rcp_f32_e32 v75, v74
	s_nop 0
	v_mul_f32_e32 v52, v52, v75
	v_mul_f32_e32 v57, 0xbfb8aa3b, v60
	v_mul_f32_e32 v56, 0xbfb8aa3b, v66
	v_exp_f32_e32 v68, v57
	v_mul_f32_e32 v57, 0xbfb8aa3b, v67
	v_exp_f32_e32 v56, v56
	v_exp_f32_e32 v57, v57
	v_rcp_f32_e32 v74, v71
	s_nop 0
	v_mul_f32_e32 v63, v63, v74
	v_pk_add_f32 v[56:57], v[56:57], 1.0 op_sel_hi:[1,0]
	v_rcp_f32_e32 v71, v70
	s_nop 0
	v_mul_f32_e32 v62, v62, v71
	v_mul_f32_e32 v80, 0xbfb8aa3b, v50
	v_rcp_f32_e32 v70, v57
	s_nop 0
	v_mul_f32_e32 v67, v67, v70
	v_exp_f32_e32 v80, v80
	v_mul_f32_e32 v71, 0xbfb8aa3b, v51
	v_exp_f32_e32 v81, v71
	v_rcp_f32_e32 v57, v56
	s_nop 0
	v_mul_f32_e32 v66, v66, v57
	v_pk_add_f32 v[56:57], v[80:81], 1.0 op_sel_hi:[1,0]
	v_mul_f32_e32 v73, 0xbfb8aa3b, v55
	v_mul_f32_e32 v77, 0xbfb8aa3b, v49
	v_exp_f32_e32 v73, v73
	v_exp_f32_e32 v77, v77
	v_mul_f32_e32 v69, 0xbfb8aa3b, v61
	v_pk_add_f32 v[70:71], v[72:73], 1.0 op_sel_hi:[1,0]
	v_pk_add_f32 v[72:73], v[76:77], 1.0 op_sel_hi:[1,0]
	v_rcp_f32_e32 v74, v57
	s_nop 0
	v_mul_f32_e32 v51, v51, v74
	v_exp_f32_e32 v69, v69
	v_rcp_f32_e32 v57, v56
	s_nop 0
	v_mul_f32_e32 v50, v50, v57
	v_pk_add_f32 v[68:69], v[68:69], 1.0 op_sel_hi:[1,0]
	v_rcp_f32_e32 v56, v73
	s_nop 0
	v_mul_f32_e32 v49, v49, v56
	v_rcp_f32_e32 v56, v72
	s_nop 0
	v_mul_f32_e32 v48, v48, v56
	v_rcp_f32_e32 v56, v71
	s_nop 0
	v_mul_f32_e32 v55, v55, v56
	v_rcp_f32_e32 v56, v70
	s_nop 0
	v_mul_f32_e32 v54, v54, v56
	v_rcp_f32_e32 v56, v69
	s_nop 0
	v_mul_f32_e32 v61, v61, v56
	v_rcp_f32_e32 v56, v68
	s_nop 0
	v_mul_f32_e32 v60, v60, v56

;   DI void operator()(const f32x4 (&acc)[2][2][4][2], const pg8::Unit& u, int wr, int wc, int fr, int fq) const {
;     ...
;         if (type == T_SILU) {
; #pragma unroll
;           for (int n = 0; n < 2; ++n)
; #pragma unroll
;             for (int j = 0; j < 4; ++j) { const float a = v1[n][j]; v1[n][j] = a / (1.f + __expf(-a)); const float b = v2[n][j]; v2[n][j] = b / (1.f + __expf(-b)); }
;         }
.LBB0_2495:
	v_mul_f32_e32 v62, 0xbfb8aa3b, v42
	v_mul_f32_e32 v63, 0xbfb8aa3b, v43
	v_exp_f32_e32 v62, v62
	v_exp_f32_e32 v63, v63
	v_mul_f32_e32 v59, 0xbfb8aa3b, v32
	v_mul_f32_e32 v58, 0xbfb8aa3b, v36
	v_exp_f32_e32 v60, v59
	v_pk_add_f32 v[62:63], v[62:63], 1.0 op_sel_hi:[1,0]
	v_mul_f32_e32 v59, 0xbfb8aa3b, v37
	v_exp_f32_e32 v58, v58
	v_exp_f32_e32 v59, v59
	v_mul_f32_e32 v55, 0xbfb8aa3b, v38
	v_rcp_f32_e32 v65, v63
	s_nop 0
	v_mul_f32_e32 v43, v43, v65
	v_pk_add_f32 v[58:59], v[58:59], 1.0 op_sel_hi:[1,0]
	v_rcp_f32_e32 v63, v62
	s_nop 0
	v_mul_f32_e32 v42, v42, v63
	v_mul_f32_e32 v54, 0xbfb8aa3b, v46
	v_exp_f32_e32 v56, v55
	v_mul_f32_e32 v55, 0xbfb8aa3b, v47
	v_exp_f32_e32 v54, v54
	v_exp_f32_e32 v55, v55
	v_rcp_f32_e32 v62, v59
	s_nop 0
	v_mul_f32_e32 v37, v37, v62
	v_pk_add_f32 v[54:55], v[54:55], 1.0 op_sel_hi:[1,0]
	v_rcp_f32_e32 v59, v58
	s_nop 0
	v_mul_f32_e32 v36, v36, v59
	v_mul_f32_e32 v41, 0xbfb8aa3b, v44
	v_mul_f32_e32 v40, 0xbfb8aa3b, v50
	v_exp_f32_e32 v52, v41
	v_mul_f32_e32 v41, 0xbfb8aa3b, v51
	v_exp_f32_e32 v40, v40
	v_exp_f32_e32 v41, v41
	v_rcp_f32_e32 v58, v55
	s_nop 0
	v_mul_f32_e32 v47, v47, v58
	v_pk_add_f32 v[40:41], v[40:41], 1.0 op_sel_hi:[1,0]
	v_rcp_f32_e32 v55, v54
	s_nop 0
	v_mul_f32_e32 v46, v46, v55
	v_mul_f32_e32 v64, 0xbfb8aa3b, v34
	v_rcp_f32_e32 v54, v41
	s_nop 0
	v_mul_f32_e32 v51, v51, v54
	v_exp_f32_e32 v64, v64
	v_mul_f32_e32 v55, 0xbfb8aa3b, v35
	v_exp_f32_e32 v65, v55
	v_rcp_f32_e32 v41, v40
	s_nop 0
	v_mul_f32_e32 v50, v50, v41
	v_pk_add_f32 v[40:41], v[64:65], 1.0 op_sel_hi:[1,0]
	v_mul_f32_e32 v57, 0xbfb8aa3b, v39
	v_mul_f32_e32 v61, 0xbfb8aa3b, v33
	v_exp_f32_e32 v57, v57
	v_exp_f32_e32 v61, v61
	v_mul_f32_e32 v53, 0xbfb8aa3b, v45
	v_pk_add_f32 v[54:55], v[56:57], 1.0 op_sel_hi:[1,0]
	v_pk_add_f32 v[56:57], v[60:61], 1.0 op_sel_hi:[1,0]
	v_rcp_f32_e32 v58, v41
	s_nop 0
	v_mul_f32_e32 v35, v35, v58
	v_exp_f32_e32 v53, v53
	v_rcp_f32_e32 v41, v40
	s_nop 0
	v_mul_f32_e32 v34, v34, v41
	v_pk_add_f32 v[52:53], v[52:53], 1.0 op_sel_hi:[1,0]
	v_rcp_f32_e32 v40, v57
	s_nop 0
	v_mul_f32_e32 v33, v33, v40
	v_rcp_f32_e32 v40, v56
	s_nop 0
	v_mul_f32_e32 v32, v32, v40
	v_rcp_f32_e32 v40, v55
	s_nop 0
	v_mul_f32_e32 v39, v39, v40
	v_rcp_f32_e32 v40, v54
	s_nop 0
	v_mul_f32_e32 v38, v38, v40
	v_rcp_f32_e32 v40, v53
	s_nop 0
	v_mul_f32_e32 v45, v45, v40
	v_rcp_f32_e32 v40, v52
	s_nop 0
	v_mul_f32_e32 v44, v44, v40

;   DI void operator()(const f32x4 (&acc)[2][2][4][2], const pg8::Unit& u, int wr, int wc, int fr, int fq) const {
;     ...
;         if (type == T_SILU) {
; #pragma unroll
;           for (int n = 0; n < 2; ++n)
; #pragma unroll
;             for (int j = 0; j < 4; ++j) { const float a = v1[n][j]; v1[n][j] = a / (1.f + __expf(-a)); const float b = v2[n][j]; v2[n][j] = b / (1.f + __expf(-b)); }
;         }
.LBB0_2499:
	v_mul_f32_e32 v46, 0xbfb8aa3b, v26
	v_mul_f32_e32 v47, 0xbfb8aa3b, v27
	v_exp_f32_e32 v46, v46
	v_exp_f32_e32 v47, v47
	v_mul_f32_e32 v43, 0xbfb8aa3b, v16
	v_mul_f32_e32 v42, 0xbfb8aa3b, v20
	v_exp_f32_e32 v44, v43
	v_pk_add_f32 v[46:47], v[46:47], 1.0 op_sel_hi:[1,0]
	v_mul_f32_e32 v43, 0xbfb8aa3b, v21
	v_exp_f32_e32 v42, v42
	v_exp_f32_e32 v43, v43
	v_mul_f32_e32 v39, 0xbfb8aa3b, v22
	v_rcp_f32_e32 v49, v47
	s_nop 0
	v_mul_f32_e32 v27, v27, v49
	v_pk_add_f32 v[42:43], v[42:43], 1.0 op_sel_hi:[1,0]
	v_rcp_f32_e32 v47, v46
	s_nop 0
	v_mul_f32_e32 v26, v26, v47
	v_mul_f32_e32 v38, 0xbfb8aa3b, v30
	v_exp_f32_e32 v40, v39
	v_mul_f32_e32 v39, 0xbfb8aa3b, v31
	v_exp_f32_e32 v38, v38
	v_exp_f32_e32 v39, v39
	v_rcp_f32_e32 v46, v43
	s_nop 0
	v_mul_f32_e32 v21, v21, v46
	v_pk_add_f32 v[38:39], v[38:39], 1.0 op_sel_hi:[1,0]
	v_rcp_f32_e32 v43, v42
	s_nop 0
	v_mul_f32_e32 v20, v20, v43
	v_mul_f32_e32 v25, 0xbfb8aa3b, v28
	v_mul_f32_e32 v24, 0xbfb8aa3b, v34
	v_exp_f32_e32 v36, v25
	v_mul_f32_e32 v25, 0xbfb8aa3b, v35
	v_exp_f32_e32 v24, v24
	v_exp_f32_e32 v25, v25
	v_rcp_f32_e32 v42, v39
	s_nop 0
	v_mul_f32_e32 v31, v31, v42
	v_pk_add_f32 v[24:25], v[24:25], 1.0 op_sel_hi:[1,0]
	v_rcp_f32_e32 v39, v38
	s_nop 0
	v_mul_f32_e32 v30, v30, v39
	v_mul_f32_e32 v48, 0xbfb8aa3b, v18
	v_rcp_f32_e32 v38, v25
	s_nop 0
	v_mul_f32_e32 v35, v35, v38
	v_exp_f32_e32 v48, v48
	v_mul_f32_e32 v39, 0xbfb8aa3b, v19
	v_exp_f32_e32 v49, v39
	v_rcp_f32_e32 v25, v24
	s_nop 0
	v_mul_f32_e32 v34, v34, v25
	v_pk_add_f32 v[24:25], v[48:49], 1.0 op_sel_hi:[1,0]
	v_mul_f32_e32 v41, 0xbfb8aa3b, v23
	v_mul_f32_e32 v45, 0xbfb8aa3b, v17
	v_exp_f32_e32 v41, v41
	v_exp_f32_e32 v45, v45
	v_mul_f32_e32 v37, 0xbfb8aa3b, v29
	v_pk_add_f32 v[38:39], v[40:41], 1.0 op_sel_hi:[1,0]
	v_pk_add_f32 v[40:41], v[44:45], 1.0 op_sel_hi:[1,0]
	v_rcp_f32_e32 v42, v25
	s_nop 0
	v_mul_f32_e32 v19, v19, v42
	v_exp_f32_e32 v37, v37
	v_rcp_f32_e32 v25, v24
	s_nop 0
	v_mul_f32_e32 v18, v18, v25
	v_pk_add_f32 v[36:37], v[36:37], 1.0 op_sel_hi:[1,0]
	v_rcp_f32_e32 v24, v41
	s_nop 0
	v_mul_f32_e32 v17, v17, v24
	v_rcp_f32_e32 v24, v40
	s_nop 0
	v_mul_f32_e32 v16, v16, v24
	v_rcp_f32_e32 v24, v39
	s_nop 0
	v_mul_f32_e32 v23, v23, v24
	v_rcp_f32_e32 v24, v38
	s_nop 0
	v_mul_f32_e32 v22, v22, v24
	v_rcp_f32_e32 v24, v37
	s_nop 0
	v_mul_f32_e32 v29, v29, v24
	v_rcp_f32_e32 v24, v36
	s_nop 0
	v_mul_f32_e32 v28, v28, v24

;   DI void operator()(const f32x4 (&acc)[2][2][4][2], const pg8::Unit& u, int wr, int wc, int fr, int fq) const {
;     ...
;         if (type == T_SILU) {
; #pragma unroll
;           for (int n = 0; n < 2; ++n)
; #pragma unroll
;             for (int j = 0; j < 4; ++j) { const float a = v1[n][j]; v1[n][j] = a / (1.f + __expf(-a)); const float b = v2[n][j]; v2[n][j] = b / (1.f + __expf(-b)); }
;         }
.LBB0_2503:
	v_mul_f32_e32 v30, 0xbfb8aa3b, v10
	v_mul_f32_e32 v31, 0xbfb8aa3b, v11
	v_exp_f32_e32 v30, v30
	v_exp_f32_e32 v31, v31
	v_mul_f32_e32 v27, 0xbfb8aa3b, v0
	v_mul_f32_e32 v26, 0xbfb8aa3b, v4
	v_exp_f32_e32 v28, v27
	v_pk_add_f32 v[30:31], v[30:31], 1.0 op_sel_hi:[1,0]
	v_mul_f32_e32 v27, 0xbfb8aa3b, v5
	v_exp_f32_e32 v26, v26
	v_exp_f32_e32 v27, v27
	v_mul_f32_e32 v23, 0xbfb8aa3b, v6
	v_rcp_f32_e32 v33, v31
	s_nop 0
	v_mul_f32_e32 v11, v11, v33
	v_pk_add_f32 v[26:27], v[26:27], 1.0 op_sel_hi:[1,0]
	v_rcp_f32_e32 v31, v30
	s_nop 0
	v_mul_f32_e32 v10, v10, v31
	v_mul_f32_e32 v22, 0xbfb8aa3b, v14
	v_exp_f32_e32 v24, v23
	v_mul_f32_e32 v23, 0xbfb8aa3b, v15
	v_exp_f32_e32 v22, v22
	v_exp_f32_e32 v23, v23
	v_rcp_f32_e32 v30, v27
	s_nop 0
	v_mul_f32_e32 v5, v5, v30
	v_pk_add_f32 v[22:23], v[22:23], 1.0 op_sel_hi:[1,0]
	v_rcp_f32_e32 v27, v26
	s_nop 0
	v_mul_f32_e32 v4, v4, v27
	v_mul_f32_e32 v9, 0xbfb8aa3b, v12
	v_mul_f32_e32 v8, 0xbfb8aa3b, v18
	v_exp_f32_e32 v20, v9
	v_mul_f32_e32 v9, 0xbfb8aa3b, v19
	v_exp_f32_e32 v8, v8
	v_exp_f32_e32 v9, v9
	v_rcp_f32_e32 v26, v23
	s_nop 0
	v_mul_f32_e32 v15, v15, v26
	v_pk_add_f32 v[8:9], v[8:9], 1.0 op_sel_hi:[1,0]
	v_rcp_f32_e32 v23, v22
	s_nop 0
	v_mul_f32_e32 v14, v14, v23
	v_mul_f32_e32 v32, 0xbfb8aa3b, v2
	v_rcp_f32_e32 v22, v9
	s_nop 0
	v_mul_f32_e32 v19, v19, v22
	v_exp_f32_e32 v32, v32
	v_mul_f32_e32 v23, 0xbfb8aa3b, v3
	v_exp_f32_e32 v33, v23
	v_rcp_f32_e32 v9, v8
	s_nop 0
	v_mul_f32_e32 v18, v18, v9
	v_pk_add_f32 v[8:9], v[32:33], 1.0 op_sel_hi:[1,0]
	v_mul_f32_e32 v25, 0xbfb8aa3b, v7
	v_mul_f32_e32 v29, 0xbfb8aa3b, v1
	v_exp_f32_e32 v25, v25
	v_exp_f32_e32 v29, v29
	v_mul_f32_e32 v21, 0xbfb8aa3b, v13
	v_pk_add_f32 v[22:23], v[24:25], 1.0 op_sel_hi:[1,0]
	v_pk_add_f32 v[24:25], v[28:29], 1.0 op_sel_hi:[1,0]
	v_rcp_f32_e32 v26, v9
	s_nop 0
	v_mul_f32_e32 v3, v3, v26
	v_exp_f32_e32 v21, v21
	v_rcp_f32_e32 v9, v8
	s_nop 0
	v_mul_f32_e32 v2, v2, v9
	v_pk_add_f32 v[20:21], v[20:21], 1.0 op_sel_hi:[1,0]
	v_rcp_f32_e32 v8, v25
	s_nop 0
	v_mul_f32_e32 v1, v1, v8
	v_rcp_f32_e32 v8, v24
	s_nop 0
	v_mul_f32_e32 v0, v0, v8
	v_rcp_f32_e32 v8, v23
	s_nop 0
	v_mul_f32_e32 v7, v7, v8
	v_rcp_f32_e32 v8, v22
	s_nop 0
	v_mul_f32_e32 v6, v6, v8
	v_rcp_f32_e32 v8, v21
	s_nop 0
	v_mul_f32_e32 v13, v13, v8
	v_rcp_f32_e32 v8, v20
	s_nop 0
	v_mul_f32_e32 v12, v12, v8

; __global__ void __launch_bounds__(NTHREADS) fwd_kernel(Params p) {
;     ...
;   if (p.ws == nullptr) grid.sync();
.LBB0_2573:
	s_or_b64 exec, exec, s[6:7]
	s_mov_b64 s[6:7], exec
	v_mbcnt_lo_u32_b32 v0, s6, 0
	v_mbcnt_hi_u32_b32 v0, s7, v0
	v_cmp_eq_u32_e32 vcc, 0, v0
	s_waitcnt vmcnt(0)
	buffer_inv sc1
	s_and_saveexec_b64 s[8:9], vcc
	s_cbranch_execz .LBB0_2575
	s_bcnt1_i32_b64 s6, s[6:7]
	v_mov_b32_e32 v0, 0x2000
	v_mov_b32_e32 v1, s6
	global_atomic_add v0, v1, s[2:3] offset:1024
	s_nop 0
	s_nop 0
	s_nop 0
	s_nop 0
	s_nop 0
	s_nop 0
	s_nop 0
	s_nop 0
	s_nop 0
	s_nop 0
	s_nop 0
	s_nop 0
	s_nop 0
	s_nop 0

;   DI void operator()(const f32x4 (&acc)[2][2][4][2], const pg8::Unit& u, int wr, int wc, int fr, int fq) const {
;     ...
;         const int row = u.pm * 256 + ai * 128 + wr * 64 + m * 16 + fr; float rs = 0.f;
;         const float rstd = rsqrtf(ssx[row] * (1.f / DM) + EPS);
; #pragma unroll
;         for (int bj = 0; bj < 2; ++bj)
; #pragma unroll
;           for (int n = 0; n < 2; ++n) {
;             const int col = u.pn * 256 + bj * 128 + wc * 32 + n * 16 + fq * 4; const size_t off = (size_t)row * DM + col;
;             f32x4 g;
; #pragma unroll
;             for (int j = 0; j < 4; ++j) g[j] = 1.f / (1.f + __expf(-rstd * acc[ai][bj][m][n][j]));
;             const u32x2 pw = *(const u32x2*)(PT + off); f32x4 pp; pp.x = __uint_as_float(pw.x << 16); pp.y = __uint_as_float(pw.x & 0xffff0000u); pp.z = __uint_as_float(pw.y << 16); pp.w = __uint_as_float(pw.y & 0xffff0000u);
;             const u32x2 xw = *(const u32x2*)(X1B + off); f32x4 x1; x1.x = __uint_as_float(xw.x << 16); x1.y = __uint_as_float(xw.x & 0xffff0000u); x1.z = __uint_as_float(xw.y << 16); x1.w = __uint_as_float(xw.y & 0xffff0000u);
;             const f32x4 xn = x1 + pp * g;
;             if (layer != 0) *(f32x4*)(out + off) = xn;
.LBB0_2826:
	v_lshl_add_u32 v144, s2, 8, v152
	v_ashrrev_i32_e32 v145, 31, v144
	v_lshl_add_u64 v[140:141], v[144:145], 2, s[18:19]
	global_load_dword v159, v[140:141], off
	v_lshl_or_b32 v142, s45, 8, v154
	v_lshlrev_b64 v[146:147], 10, v[144:145]
	v_ashrrev_i32_e32 v143, 31, v142
	v_lshl_add_u64 v[148:149], v[146:147], 0, v[142:143]
	v_lshlrev_b64 v[140:141], 1, v[148:149]
	v_lshl_add_u64 v[150:151], s[10:11], 0, v[140:141]
	v_lshl_add_u64 v[140:141], s[12:13], 0, v[140:141]
	global_load_dwordx2 v[160:161], v[150:151], off
	global_load_dwordx2 v[162:163], v[140:141], off
	v_or_b32_e32 v140, 16, v142
	v_lshl_add_u64 v[148:149], v[148:149], 2, s[14:15]
	s_waitcnt vmcnt(0)
	v_fmamk_f32 v141, v159, 0x3a800000, v158
	v_mul_f32_e32 v145, 0x4b800000, v141
	v_cmp_gt_f32_e32 vcc, s44, v141
	v_lshlrev_b32_e32 v164, 16, v160
	s_nop 0
	v_cndmask_b32_e32 v141, v141, v145, vcc
	v_rsq_f32_e32 v141, v141
	v_and_b32_e32 v165, 0xffff0000, v160
	v_lshlrev_b32_e32 v160, 16, v161
	v_and_b32_e32 v161, 0xffff0000, v161
	v_mul_f32_e32 v145, 0x45800000, v141
	v_cndmask_b32_e32 v145, v141, v145, vcc
	v_mul_f32_e64 v124, v124, -v145
	v_mul_f32_e64 v125, v125, -v145
	v_mul_f32_e32 v124, 0x3fb8aa3b, v124
	v_mul_f32_e32 v125, 0x3fb8aa3b, v125
	v_mul_f32_e64 v126, v126, -v145
	v_mul_f32_e64 v127, v127, -v145
	v_exp_f32_e32 v124, v124
	v_exp_f32_e32 v125, v125
	v_mul_f32_e32 v126, 0x3fb8aa3b, v126
	v_mul_f32_e32 v127, 0x3fb8aa3b, v127
	v_exp_f32_e32 v126, v126
	v_exp_f32_e32 v127, v127
	v_pk_add_f32 v[124:125], v[124:125], 1.0 op_sel_hi:[1,0]
	v_lshlrev_b32_e32 v166, 16, v162
	v_pk_add_f32 v[126:127], v[126:127], 1.0 op_sel_hi:[1,0]
	v_div_scale_f32 v169, s[4:5], 1.0, v124, 1.0
	v_div_scale_f32 v171, s[6:7], 1.0, v127, 1.0
	v_div_scale_f32 v173, s[8:9], 1.0, v126, 1.0
	s_mov_b64 vcc, s[4:5]
	v_rcp_f32_e32 v125, v125
	s_mov_b64 vcc, s[6:7]
	v_rcp_f32_e32 v124, v124
	s_mov_b64 vcc, s[8:9]
	v_rcp_f32_e32 v127, v127
	v_and_b32_e32 v167, 0xffff0000, v162
	v_lshlrev_b32_e32 v162, 16, v163
	v_and_b32_e32 v163, 0xffff0000, v163
	v_rcp_f32_e32 v126, v126
	v_pk_fma_f32 v[124:125], v[124:125], v[164:165], v[166:167]
	v_pk_fma_f32 v[126:127], v[126:127], v[160:161], v[162:163]
	v_ashrrev_i32_e32 v141, 31, v140
	global_store_dwordx4 v[148:149], v[124:127], off
	global_load_dwordx2 v[124:125], v[150:151], off offset:32
	v_mul_f32_e64 v120, v120, -v145
	v_lshl_add_u64 v[126:127], v[146:147], 0, v[140:141]
	v_lshl_add_u64 v[126:127], v[126:127], 1, s[12:13]
	global_load_dwordx2 v[126:127], v[126:127], off
	v_mul_f32_e64 v121, v121, -v145
	v_mul_f32_e64 v123, v123, -v145
	v_mul_f32_e64 v122, v122, -v145
	v_mul_f32_e32 v120, 0x3fb8aa3b, v120
	v_mul_f32_e32 v121, 0x3fb8aa3b, v121
	v_mul_f32_e32 v123, 0x3fb8aa3b, v123
	v_mul_f32_e32 v159, 0x3fb8aa3b, v122
	v_exp_f32_e32 v122, v120
	v_exp_f32_e32 v161, v123
	v_exp_f32_e32 v123, v121
	v_exp_f32_e32 v160, v159
	v_or_b32_e32 v120, 0x80, v142
	v_mul_f32_e64 v116, v116, -v145
	v_pk_add_f32 v[122:123], v[122:123], 1.0 op_sel_hi:[1,0]
	v_pk_add_f32 v[160:161], v[160:161], 1.0 op_sel_hi:[1,0]
	v_div_scale_f32 v163, s[4:5], 1.0, v122, 1.0
	v_div_scale_f32 v165, s[6:7], 1.0, v161, 1.0
	v_div_scale_f32 v167, s[8:9], 1.0, v160, 1.0
	s_mov_b64 vcc, s[4:5]
	v_rcp_f32_e32 v123, v123
	s_mov_b64 vcc, s[6:7]
	v_rcp_f32_e32 v122, v122
	s_mov_b64 vcc, s[8:9]
	v_rcp_f32_e32 v161, v161
	v_rcp_f32_e32 v160, v160
	v_ashrrev_i32_e32 v121, 31, v120
	v_mul_f32_e64 v117, v117, -v145
	v_mul_f32_e64 v119, v119, -v145
	v_mul_f32_e64 v118, v118, -v145
	v_mul_f32_e32 v116, 0x3fb8aa3b, v116
	s_waitcnt vmcnt(1)
	v_lshlrev_b32_e32 v162, 16, v124
	v_and_b32_e32 v163, 0xffff0000, v124
	v_lshlrev_b32_e32 v124, 16, v125
	v_and_b32_e32 v125, 0xffff0000, v125
	s_waitcnt vmcnt(0)
	v_lshlrev_b32_e32 v164, 16, v126
	v_and_b32_e32 v165, 0xffff0000, v126
	v_lshlrev_b32_e32 v126, 16, v127
	v_and_b32_e32 v127, 0xffff0000, v127
	v_pk_fma_f32 v[124:125], v[160:161], v[124:125], v[126:127]
	v_pk_fma_f32 v[122:123], v[122:123], v[162:163], v[164:165]
	global_store_dwordx4 v[148:149], v[122:125], off offset:64
	global_load_dwordx2 v[122:123], v[150:151], off offset:256
	v_mul_f32_e32 v117, 0x3fb8aa3b, v117
	v_lshl_add_u64 v[124:125], v[146:147], 0, v[120:121]
	v_lshl_add_u64 v[124:125], v[124:125], 1, s[12:13]
	global_load_dwordx2 v[124:125], v[124:125], off
	v_mul_f32_e32 v119, 0x3fb8aa3b, v119
	v_mul_f32_e32 v126, 0x3fb8aa3b, v118
	v_exp_f32_e32 v118, v116
	v_exp_f32_e32 v127, v119
	v_exp_f32_e32 v119, v117
	v_exp_f32_e32 v126, v126
	v_or_b32_e32 v116, 0x90, v142
	v_mul_f32_e64 v112, v112, -v145
	v_pk_add_f32 v[118:119], v[118:119], 1.0 op_sel_hi:[1,0]
	v_pk_add_f32 v[126:127], v[126:127], 1.0 op_sel_hi:[1,0]
	v_div_scale_f32 v161, s[4:5], 1.0, v118, 1.0
	v_div_scale_f32 v163, s[6:7], 1.0, v127, 1.0
	v_div_scale_f32 v165, s[8:9], 1.0, v126, 1.0
	s_mov_b64 vcc, s[4:5]
	v_rcp_f32_e32 v119, v119
	s_mov_b64 vcc, s[6:7]
	v_rcp_f32_e32 v118, v118
	s_mov_b64 vcc, s[8:9]
	v_rcp_f32_e32 v127, v127
	v_rcp_f32_e32 v126, v126
	v_ashrrev_i32_e32 v117, 31, v116
	v_mul_f32_e64 v113, v113, -v145
	v_mul_f32_e32 v112, 0x3fb8aa3b, v112
	v_mul_f32_e32 v113, 0x3fb8aa3b, v113
	v_mul_f32_e64 v114, v114, -v145
	v_mul_f32_e64 v115, v115, -v145
	v_exp_f32_e32 v112, v112
	v_exp_f32_e32 v113, v113
	v_mul_f32_e32 v114, 0x3fb8aa3b, v114
	v_mul_f32_e32 v115, 0x3fb8aa3b, v115
	s_waitcnt vmcnt(1)
	v_lshlrev_b32_e32 v160, 16, v122
	v_and_b32_e32 v161, 0xffff0000, v122
	v_lshlrev_b32_e32 v122, 16, v123
	v_and_b32_e32 v123, 0xffff0000, v123
	s_waitcnt vmcnt(0)
;   DI void operator()(const f32x4 (&acc)[2][2][4][2], const pg8::Unit& u, int wr, int wc, int fr, int fq) const {
;     ...
;         const int row = u.pm * 256 + ai * 128 + wr * 64 + m * 16 + fr; float rs = 0.f;
;         const float rstd = rsqrtf(ssx[row] * (1.f / DM) + EPS);
; #pragma unroll
;         for (int bj = 0; bj < 2; ++bj)
; #pragma unroll
;           for (int n = 0; n < 2; ++n) {
;             const int col = u.pn * 256 + bj * 128 + wc * 32 + n * 16 + fq * 4; const size_t off = (size_t)row * DM + col;
;             f32x4 g;
; #pragma unroll
;             for (int j = 0; j < 4; ++j) g[j] = 1.f / (1.f + __expf(-rstd * acc[ai][bj][m][n][j]));
;             const u32x2 pw = *(const u32x2*)(PT + off); f32x4 pp; pp.x = __uint_as_float(pw.x << 16); pp.y = __uint_as_float(pw.x & 0xffff0000u); pp.z = __uint_as_float(pw.y << 16); pp.w = __uint_as_float(pw.y & 0xffff0000u);
;             const u32x2 xw = *(const u32x2*)(X1B + off); f32x4 x1; x1.x = __uint_as_float(xw.x << 16); x1.y = __uint_as_float(xw.x & 0xffff0000u); x1.z = __uint_as_float(xw.y << 16); x1.w = __uint_as_float(xw.y & 0xffff0000u);
;             const f32x4 xn = x1 + pp * g;
;             if (layer != 0) *(f32x4*)(out + off) = xn;
	v_lshlrev_b32_e32 v162, 16, v124
	v_and_b32_e32 v163, 0xffff0000, v124
	v_lshlrev_b32_e32 v124, 16, v125
	v_and_b32_e32 v125, 0xffff0000, v125
	v_pk_fma_f32 v[124:125], v[126:127], v[122:123], v[124:125]
	v_pk_fma_f32 v[122:123], v[118:119], v[160:161], v[162:163]
	global_store_dwordx4 v[148:149], v[122:125], off offset:512
	global_load_dwordx2 v[118:119], v[150:151], off offset:288
	v_exp_f32_e32 v114, v114
	v_lshl_add_u64 v[122:123], v[146:147], 0, v[116:117]
	v_lshl_add_u64 v[122:123], v[122:123], 1, s[12:13]
	global_load_dwordx2 v[122:123], v[122:123], off
	v_exp_f32_e32 v115, v115
	v_pk_add_f32 v[112:113], v[112:113], 1.0 op_sel_hi:[1,0]
	v_or_b32_e32 v124, 16, v144
	v_pk_add_f32 v[114:115], v[114:115], 1.0 op_sel_hi:[1,0]
	v_div_scale_f32 v150, s[4:5], 1.0, v112, 1.0
	v_div_scale_f32 v159, s[6:7], 1.0, v115, 1.0
	v_div_scale_f32 v161, s[8:9], 1.0, v114, 1.0
	s_mov_b64 vcc, s[4:5]
	v_rcp_f32_e32 v113, v113
	s_mov_b64 vcc, s[6:7]
	v_rcp_f32_e32 v112, v112
	s_mov_b64 vcc, s[8:9]
	v_rcp_f32_e32 v115, v115
	v_rcp_f32_e32 v114, v114
	v_ashrrev_i32_e32 v125, 31, v124
	v_lshl_add_u64 v[126:127], v[124:125], 2, s[18:19]
	s_waitcnt vmcnt(1)
	v_lshlrev_b32_e32 v146, 16, v118
	v_and_b32_e32 v147, 0xffff0000, v118
	v_lshlrev_b32_e32 v118, 16, v119
	v_and_b32_e32 v119, 0xffff0000, v119
	s_waitcnt vmcnt(0)
	v_lshlrev_b32_e32 v150, 16, v122
	v_and_b32_e32 v151, 0xffff0000, v122
	v_lshlrev_b32_e32 v122, 16, v123
	v_and_b32_e32 v123, 0xffff0000, v123
	v_pk_fma_f32 v[114:115], v[114:115], v[118:119], v[122:123]
	v_pk_fma_f32 v[112:113], v[112:113], v[146:147], v[150:151]
	global_store_dwordx4 v[148:149], v[112:115], off offset:576
	s_nop 1
	v_lshlrev_b64 v[114:115], 10, v[124:125]
	v_lshl_add_u64 v[112:113], v[114:115], 0, v[142:143]
	v_lshlrev_b64 v[122:123], 1, v[112:113]
	v_lshl_add_u64 v[118:119], s[10:11], 0, v[122:123]
	global_load_dword v126, v[126:127], off
	s_nop 0
	global_load_dwordx2 v[124:125], v[118:119], off
	v_lshl_add_u64 v[122:123], s[12:13], 0, v[122:123]
	global_load_dwordx2 v[122:123], v[122:123], off
	v_lshl_add_u64 v[112:113], v[112:113], 2, s[14:15]
	s_waitcnt vmcnt(2)
	v_fmamk_f32 v145, v126, 0x3a800000, v158
	v_mul_f32_e32 v146, 0x4b800000, v145
	v_cmp_gt_f32_e32 vcc, s44, v145
	s_waitcnt vmcnt(0)
	v_and_b32_e32 v147, 0xffff0000, v122
	v_lshlrev_b32_e32 v148, 16, v123
	v_cndmask_b32_e32 v145, v145, v146, vcc
	v_rsq_f32_e32 v145, v145
	v_lshlrev_b32_e32 v146, 16, v122
	v_and_b32_e32 v149, 0xffff0000, v123
	v_lshlrev_b32_e32 v126, 16, v124
	v_mul_f32_e32 v122, 0x45800000, v145
	v_cndmask_b32_e32 v122, v145, v122, vcc
	v_mul_f32_e64 v108, v108, -v122
	v_mul_f32_e64 v109, v109, -v122
	v_mul_f32_e32 v108, 0x3fb8aa3b, v108
	v_mul_f32_e32 v109, 0x3fb8aa3b, v109
	v_mul_f32_e64 v110, v110, -v122
	v_mul_f32_e64 v111, v111, -v122
	v_exp_f32_e32 v108, v108
	v_exp_f32_e32 v109, v109
	v_mul_f32_e32 v110, 0x3fb8aa3b, v110
	v_mul_f32_e32 v111, 0x3fb8aa3b, v111
	v_exp_f32_e32 v110, v110
	v_exp_f32_e32 v111, v111
	v_pk_add_f32 v[108:109], v[108:109], 1.0 op_sel_hi:[1,0]
	v_and_b32_e32 v127, 0xffff0000, v124
	v_pk_add_f32 v[110:111], v[110:111], 1.0 op_sel_hi:[1,0]
	v_div_scale_f32 v151, s[4:5], 1.0, v108, 1.0
	v_div_scale_f32 v160, s[6:7], 1.0, v111, 1.0
	v_div_scale_f32 v162, s[8:9], 1.0, v110, 1.0
	s_mov_b64 vcc, s[4:5]
	v_rcp_f32_e32 v109, v109
	s_mov_b64 vcc, s[6:7]
	v_rcp_f32_e32 v108, v108
	s_mov_b64 vcc, s[8:9]
	v_rcp_f32_e32 v111, v111
	v_lshlrev_b32_e32 v124, 16, v125
	v_and_b32_e32 v125, 0xffff0000, v125
	v_rcp_f32_e32 v110, v110
	v_pk_fma_f32 v[108:109], v[108:109], v[126:127], v[146:147]
	v_pk_fma_f32 v[110:111], v[110:111], v[124:125], v[148:149]
	global_store_dwordx4 v[112:113], v[108:111], off
	global_load_dwordx2 v[108:109], v[118:119], off offset:32
	v_mul_f32_e64 v104, v104, -v122
	v_lshl_add_u64 v[110:111], v[114:115], 0, v[140:141]
	v_lshl_add_u64 v[110:111], v[110:111], 1, s[12:13]
	global_load_dwordx2 v[110:111], v[110:111], off
	v_mul_f32_e64 v105, v105, -v122
	v_mul_f32_e32 v104, 0x3fb8aa3b, v104
	v_mul_f32_e32 v105, 0x3fb8aa3b, v105
	v_mul_f32_e64 v106, v106, -v122
	v_mul_f32_e64 v107, v107, -v122
	v_exp_f32_e32 v104, v104
	v_exp_f32_e32 v105, v105
	v_mul_f32_e32 v106, 0x3fb8aa3b, v106
	v_mul_f32_e32 v107, 0x3fb8aa3b, v107
	v_exp_f32_e32 v106, v106
	v_exp_f32_e32 v107, v107
	v_pk_add_f32 v[104:105], v[104:105], 1.0 op_sel_hi:[1,0]
	v_mul_f32_e64 v100, v100, -v122
	v_pk_add_f32 v[106:107], v[106:107], 1.0 op_sel_hi:[1,0]
	v_div_scale_f32 v126, s[4:5], 1.0, v104, 1.0
	v_div_scale_f32 v145, s[6:7], 1.0, v107, 1.0
	v_div_scale_f32 v147, s[8:9], 1.0, v106, 1.0
	s_mov_b64 vcc, s[4:5]
	v_rcp_f32_e32 v105, v105
	s_mov_b64 vcc, s[6:7]
	v_rcp_f32_e32 v104, v104
	s_mov_b64 vcc, s[8:9]
	v_rcp_f32_e32 v107, v107
	v_rcp_f32_e32 v106, v106
	v_mul_f32_e64 v101, v101, -v122
	v_mul_f32_e32 v100, 0x3fb8aa3b, v100
	v_mul_f32_e32 v101, 0x3fb8aa3b, v101
	v_mul_f32_e64 v102, v102, -v122
	v_mul_f32_e64 v103, v103, -v122
	v_exp_f32_e32 v100, v100
	s_waitcnt vmcnt(1)
	v_lshlrev_b32_e32 v124, 16, v108
	v_and_b32_e32 v125, 0xffff0000, v108
	v_lshlrev_b32_e32 v108, 16, v109
	v_and_b32_e32 v109, 0xffff0000, v109
	s_waitcnt vmcnt(0)
;   DI void operator()(const f32x4 (&acc)[2][2][4][2], const pg8::Unit& u, int wr, int wc, int fr, int fq) const {
;     ...
;         const int row = u.pm * 256 + ai * 128 + wr * 64 + m * 16 + fr; float rs = 0.f;
;         const float rstd = rsqrtf(ssx[row] * (1.f / DM) + EPS);
; #pragma unroll
;         for (int bj = 0; bj < 2; ++bj)
; #pragma unroll
;           for (int n = 0; n < 2; ++n) {
;             const int col = u.pn * 256 + bj * 128 + wc * 32 + n * 16 + fq * 4; const size_t off = (size_t)row * DM + col;
;             f32x4 g;
; #pragma unroll
;             for (int j = 0; j < 4; ++j) g[j] = 1.f / (1.f + __expf(-rstd * acc[ai][bj][m][n][j]));
;             const u32x2 pw = *(const u32x2*)(PT + off); f32x4 pp; pp.x = __uint_as_float(pw.x << 16); pp.y = __uint_as_float(pw.x & 0xffff0000u); pp.z = __uint_as_float(pw.y << 16); pp.w = __uint_as_float(pw.y & 0xffff0000u);
;             const u32x2 xw = *(const u32x2*)(X1B + off); f32x4 x1; x1.x = __uint_as_float(xw.x << 16); x1.y = __uint_as_float(xw.x & 0xffff0000u); x1.z = __uint_as_float(xw.y << 16); x1.w = __uint_as_float(xw.y & 0xffff0000u);
;             const f32x4 xn = x1 + pp * g;
;             if (layer != 0) *(f32x4*)(out + off) = xn;
	v_lshlrev_b32_e32 v126, 16, v110
	v_and_b32_e32 v127, 0xffff0000, v110
	v_lshlrev_b32_e32 v110, 16, v111
	v_and_b32_e32 v111, 0xffff0000, v111
	v_pk_fma_f32 v[106:107], v[106:107], v[108:109], v[110:111]
	v_pk_fma_f32 v[104:105], v[104:105], v[124:125], v[126:127]
	global_store_dwordx4 v[112:113], v[104:107], off offset:64
	global_load_dwordx2 v[104:105], v[118:119], off offset:256
	v_exp_f32_e32 v101, v101
	v_lshl_add_u64 v[106:107], v[114:115], 0, v[120:121]
	v_lshl_add_u64 v[106:107], v[106:107], 1, s[12:13]
	global_load_dwordx2 v[106:107], v[106:107], off
	v_mul_f32_e32 v102, 0x3fb8aa3b, v102
	v_mul_f32_e32 v103, 0x3fb8aa3b, v103
	v_exp_f32_e32 v102, v102
	v_exp_f32_e32 v103, v103
	v_pk_add_f32 v[100:101], v[100:101], 1.0 op_sel_hi:[1,0]
	v_mul_f32_e64 v96, v96, -v122
	v_pk_add_f32 v[102:103], v[102:103], 1.0 op_sel_hi:[1,0]
	v_div_scale_f32 v123, s[4:5], 1.0, v100, 1.0
	v_div_scale_f32 v125, s[6:7], 1.0, v103, 1.0
	v_div_scale_f32 v127, s[8:9], 1.0, v102, 1.0
	s_mov_b64 vcc, s[4:5]
	v_rcp_f32_e32 v101, v101
	s_mov_b64 vcc, s[6:7]
	v_rcp_f32_e32 v100, v100
	s_mov_b64 vcc, s[8:9]
	v_rcp_f32_e32 v103, v103
	v_rcp_f32_e32 v102, v102
	v_mul_f32_e64 v97, v97, -v122
	v_mul_f32_e32 v96, 0x3fb8aa3b, v96
	v_mul_f32_e32 v97, 0x3fb8aa3b, v97
	v_mul_f32_e64 v98, v98, -v122
	v_mul_f32_e64 v99, v99, -v122
	v_exp_f32_e32 v96, v96
	v_exp_f32_e32 v97, v97
	v_mul_f32_e32 v98, 0x3fb8aa3b, v98
	v_mul_f32_e32 v99, 0x3fb8aa3b, v99
	v_or_b32_e32 v108, 32, v144
	v_pk_add_f32 v[96:97], v[96:97], 1.0 op_sel_hi:[1,0]
	v_ashrrev_i32_e32 v109, 31, v108
	s_waitcnt vmcnt(1)
	v_lshlrev_b32_e32 v110, 16, v104
	v_and_b32_e32 v111, 0xffff0000, v104
	v_lshlrev_b32_e32 v104, 16, v105
	v_and_b32_e32 v105, 0xffff0000, v105
	s_waitcnt vmcnt(0)
	v_lshlrev_b32_e32 v124, 16, v106
	v_and_b32_e32 v125, 0xffff0000, v106
	v_lshlrev_b32_e32 v106, 16, v107
	v_and_b32_e32 v107, 0xffff0000, v107
	v_pk_fma_f32 v[102:103], v[102:103], v[104:105], v[106:107]
	v_pk_fma_f32 v[100:101], v[100:101], v[110:111], v[124:125]
	global_store_dwordx4 v[112:113], v[100:103], off offset:512
	global_load_dwordx2 v[102:103], v[118:119], off offset:288
	v_exp_f32_e32 v110, v98
	v_lshl_add_u64 v[100:101], v[114:115], 0, v[116:117]
	v_lshl_add_u64 v[100:101], v[100:101], 1, s[12:13]
	global_load_dwordx2 v[104:105], v[100:101], off
	v_exp_f32_e32 v111, v99
	s_nop 0
	v_pk_add_f32 v[110:111], v[110:111], 1.0 op_sel_hi:[1,0]
	v_div_scale_f32 v123, s[4:5], 1.0, v96, 1.0
	v_div_scale_f32 v125, s[6:7], 1.0, v111, 1.0
	v_div_scale_f32 v127, s[8:9], 1.0, v110, 1.0
	s_mov_b64 vcc, s[4:5]
	v_rcp_f32_e32 v97, v97
	s_mov_b64 vcc, s[6:7]
	v_rcp_f32_e32 v96, v96
	s_mov_b64 vcc, s[8:9]
	v_rcp_f32_e32 v111, v111
	v_rcp_f32_e32 v110, v110
	v_lshlrev_b64 v[100:101], 10, v[108:109]
	v_lshl_add_u64 v[106:107], v[108:109], 2, s[18:19]
	v_lshl_add_u64 v[108:109], v[100:101], 0, v[142:143]
	v_lshlrev_b64 v[114:115], 1, v[108:109]
	v_lshl_add_u64 v[98:99], s[10:11], 0, v[114:115]
	s_waitcnt vmcnt(1)
	v_lshlrev_b32_e32 v118, 16, v102
	v_and_b32_e32 v119, 0xffff0000, v102
	v_lshlrev_b32_e32 v102, 16, v103
	v_and_b32_e32 v103, 0xffff0000, v103
	s_waitcnt vmcnt(0)
	v_lshlrev_b32_e32 v122, 16, v104
	v_and_b32_e32 v123, 0xffff0000, v104
	v_lshlrev_b32_e32 v104, 16, v105
	v_and_b32_e32 v105, 0xffff0000, v105
	v_pk_fma_f32 v[104:105], v[110:111], v[102:103], v[104:105]
	v_pk_fma_f32 v[102:103], v[96:97], v[118:119], v[122:123]
	global_store_dwordx4 v[112:113], v[102:105], off offset:576
	global_load_dword v106, v[106:107], off
	s_nop 0
	global_load_dwordx2 v[102:103], v[98:99], off
	v_lshl_add_u64 v[96:97], s[12:13], 0, v[114:115]
	global_load_dwordx2 v[104:105], v[96:97], off
	v_lshl_add_u64 v[96:97], v[108:109], 2, s[14:15]
	s_waitcnt vmcnt(2)
	v_fmamk_f32 v109, v106, 0x3a800000, v158
	s_waitcnt vmcnt(1)
	v_lshlrev_b32_e32 v106, 16, v102
	v_and_b32_e32 v107, 0xffff0000, v102
	v_mul_f32_e32 v102, 0x4b800000, v109
	v_cmp_gt_f32_e32 vcc, s44, v109
	v_lshlrev_b32_e32 v108, 16, v103
	s_waitcnt vmcnt(0)
	v_lshlrev_b32_e32 v110, 16, v104
	v_cndmask_b32_e32 v102, v109, v102, vcc
	v_rsq_f32_e32 v102, v102
	v_and_b32_e32 v109, 0xffff0000, v103
	v_and_b32_e32 v111, 0xffff0000, v104
	v_lshlrev_b32_e32 v104, 16, v105
	v_mul_f32_e32 v103, 0x45800000, v102
	v_cndmask_b32_e32 v102, v102, v103, vcc
	v_mul_f32_e64 v92, v92, -v102
	v_mul_f32_e64 v93, v93, -v102
	v_mul_f32_e32 v92, 0x3fb8aa3b, v92
	v_mul_f32_e32 v93, 0x3fb8aa3b, v93
	v_mul_f32_e64 v94, v94, -v102
	v_mul_f32_e64 v95, v95, -v102
	v_exp_f32_e32 v92, v92
	v_exp_f32_e32 v93, v93
	v_mul_f32_e32 v94, 0x3fb8aa3b, v94
	v_mul_f32_e32 v95, 0x3fb8aa3b, v95
	v_exp_f32_e32 v94, v94
	v_exp_f32_e32 v95, v95
	v_pk_add_f32 v[92:93], v[92:93], 1.0 op_sel_hi:[1,0]
	v_and_b32_e32 v105, 0xffff0000, v105
	v_pk_add_f32 v[94:95], v[94:95], 1.0 op_sel_hi:[1,0]
	v_div_scale_f32 v114, s[4:5], 1.0, v92, 1.0
	v_div_scale_f32 v118, s[6:7], 1.0, v95, 1.0
	v_div_scale_f32 v122, s[8:9], 1.0, v94, 1.0
	s_mov_b64 vcc, s[4:5]
	v_rcp_f32_e32 v93, v93
	s_mov_b64 vcc, s[6:7]
	v_rcp_f32_e32 v92, v92
	s_mov_b64 vcc, s[8:9]
	v_rcp_f32_e32 v95, v95
	v_rcp_f32_e32 v94, v94
	v_pk_fma_f32 v[92:93], v[92:93], v[106:107], v[110:111]
	v_pk_fma_f32 v[94:95], v[94:95], v[108:109], v[104:105]
	global_store_dwordx4 v[96:97], v[92:95], off
	global_load_dwordx2 v[92:93], v[98:99], off offset:32
	v_mul_f32_e64 v88, v88, -v102
	v_lshl_add_u64 v[94:95], v[100:101], 0, v[140:141]
	v_lshl_add_u64 v[94:95], v[94:95], 1, s[12:13]
	global_load_dwordx2 v[94:95], v[94:95], off
	v_mul_f32_e64 v89, v89, -v102
	v_mul_f32_e32 v88, 0x3fb8aa3b, v88
	v_mul_f32_e32 v89, 0x3fb8aa3b, v89
	v_mul_f32_e64 v90, v90, -v102
	v_mul_f32_e64 v91, v91, -v102
	v_exp_f32_e32 v88, v88
	v_exp_f32_e32 v89, v89
	v_mul_f32_e32 v90, 0x3fb8aa3b, v90
	v_mul_f32_e32 v91, 0x3fb8aa3b, v91
	v_exp_f32_e32 v90, v90
	v_exp_f32_e32 v91, v91
	v_pk_add_f32 v[88:89], v[88:89], 1.0 op_sel_hi:[1,0]
	v_mul_f32_e64 v84, v84, -v102
	v_pk_add_f32 v[90:91], v[90:91], 1.0 op_sel_hi:[1,0]
	v_div_scale_f32 v106, s[4:5], 1.0, v88, 1.0
	v_div_scale_f32 v108, s[6:7], 1.0, v91, 1.0
	v_div_scale_f32 v110, s[8:9], 1.0, v90, 1.0
	s_mov_b64 vcc, s[4:5]
	v_rcp_f32_e32 v89, v89
	s_mov_b64 vcc, s[6:7]
	v_rcp_f32_e32 v88, v88
	s_mov_b64 vcc, s[8:9]
	v_rcp_f32_e32 v91, v91
	v_rcp_f32_e32 v90, v90
	v_mul_f32_e64 v85, v85, -v102
	v_mul_f32_e32 v84, 0x3fb8aa3b, v84
	v_mul_f32_e32 v85, 0x3fb8aa3b, v85
	v_mul_f32_e64 v86, v86, -v102
	v_mul_f32_e64 v87, v87, -v102
	v_exp_f32_e32 v84, v84
	s_waitcnt vmcnt(1)
;   DI void operator()(const f32x4 (&acc)[2][2][4][2], const pg8::Unit& u, int wr, int wc, int fr, int fq) const {
;     ...
;         const int row = u.pm * 256 + ai * 128 + wr * 64 + m * 16 + fr; float rs = 0.f;
;         const float rstd = rsqrtf(ssx[row] * (1.f / DM) + EPS);
; #pragma unroll
;         for (int bj = 0; bj < 2; ++bj)
; #pragma unroll
;           for (int n = 0; n < 2; ++n) {
;             const int col = u.pn * 256 + bj * 128 + wc * 32 + n * 16 + fq * 4; const size_t off = (size_t)row * DM + col;
;             f32x4 g;
; #pragma unroll
;             for (int j = 0; j < 4; ++j) g[j] = 1.f / (1.f + __expf(-rstd * acc[ai][bj][m][n][j]));
;             const u32x2 pw = *(const u32x2*)(PT + off); f32x4 pp; pp.x = __uint_as_float(pw.x << 16); pp.y = __uint_as_float(pw.x & 0xffff0000u); pp.z = __uint_as_float(pw.y << 16); pp.w = __uint_as_float(pw.y & 0xffff0000u);
;             const u32x2 xw = *(const u32x2*)(X1B + off); f32x4 x1; x1.x = __uint_as_float(xw.x << 16); x1.y = __uint_as_float(xw.x & 0xffff0000u); x1.z = __uint_as_float(xw.y << 16); x1.w = __uint_as_float(xw.y & 0xffff0000u);
;             const f32x4 xn = x1 + pp * g;
;             if (layer != 0) *(f32x4*)(out + off) = xn;
	v_lshlrev_b32_e32 v104, 16, v92
	v_and_b32_e32 v105, 0xffff0000, v92
	v_lshlrev_b32_e32 v92, 16, v93
	v_and_b32_e32 v93, 0xffff0000, v93
	s_waitcnt vmcnt(0)
	v_lshlrev_b32_e32 v106, 16, v94
	v_and_b32_e32 v107, 0xffff0000, v94
	v_lshlrev_b32_e32 v94, 16, v95
	v_and_b32_e32 v95, 0xffff0000, v95
	v_pk_fma_f32 v[90:91], v[90:91], v[92:93], v[94:95]
	v_pk_fma_f32 v[88:89], v[88:89], v[104:105], v[106:107]
	global_store_dwordx4 v[96:97], v[88:91], off offset:64
	global_load_dwordx2 v[88:89], v[98:99], off offset:256
	v_exp_f32_e32 v85, v85
	v_lshl_add_u64 v[90:91], v[100:101], 0, v[120:121]
	v_lshl_add_u64 v[90:91], v[90:91], 1, s[12:13]
	global_load_dwordx2 v[90:91], v[90:91], off
	v_mul_f32_e32 v86, 0x3fb8aa3b, v86
	v_mul_f32_e32 v87, 0x3fb8aa3b, v87
	v_exp_f32_e32 v86, v86
	v_exp_f32_e32 v87, v87
	v_pk_add_f32 v[84:85], v[84:85], 1.0 op_sel_hi:[1,0]
	v_mul_f32_e64 v80, v80, -v102
	v_pk_add_f32 v[86:87], v[86:87], 1.0 op_sel_hi:[1,0]
	v_div_scale_f32 v103, s[4:5], 1.0, v84, 1.0
	v_div_scale_f32 v105, s[6:7], 1.0, v87, 1.0
	v_div_scale_f32 v107, s[8:9], 1.0, v86, 1.0
	s_mov_b64 vcc, s[4:5]
	v_rcp_f32_e32 v85, v85
	s_mov_b64 vcc, s[6:7]
	v_rcp_f32_e32 v84, v84
	s_mov_b64 vcc, s[8:9]
	v_rcp_f32_e32 v87, v87
	v_rcp_f32_e32 v86, v86
	v_mul_f32_e64 v81, v81, -v102
	v_mul_f32_e32 v80, 0x3fb8aa3b, v80
	v_mul_f32_e32 v81, 0x3fb8aa3b, v81
	v_mul_f32_e64 v82, v82, -v102
	v_mul_f32_e64 v83, v83, -v102
	v_exp_f32_e32 v80, v80
	v_exp_f32_e32 v81, v81
	v_mul_f32_e32 v82, 0x3fb8aa3b, v82
	v_mul_f32_e32 v83, 0x3fb8aa3b, v83
	v_or_b32_e32 v92, 48, v144
	v_pk_add_f32 v[80:81], v[80:81], 1.0 op_sel_hi:[1,0]
	v_ashrrev_i32_e32 v93, 31, v92
	s_waitcnt vmcnt(1)
	v_lshlrev_b32_e32 v94, 16, v88
	v_and_b32_e32 v95, 0xffff0000, v88
	v_lshlrev_b32_e32 v88, 16, v89
	v_and_b32_e32 v89, 0xffff0000, v89
	s_waitcnt vmcnt(0)
	v_lshlrev_b32_e32 v104, 16, v90
	v_and_b32_e32 v105, 0xffff0000, v90
	v_lshlrev_b32_e32 v90, 16, v91
	v_and_b32_e32 v91, 0xffff0000, v91
	v_pk_fma_f32 v[86:87], v[86:87], v[88:89], v[90:91]
	v_pk_fma_f32 v[84:85], v[84:85], v[94:95], v[104:105]
	global_store_dwordx4 v[96:97], v[84:87], off offset:512
	global_load_dwordx2 v[86:87], v[98:99], off offset:288
	v_exp_f32_e32 v94, v82
	v_lshl_add_u64 v[84:85], v[100:101], 0, v[116:117]
	v_lshl_add_u64 v[84:85], v[84:85], 1, s[12:13]
	global_load_dwordx2 v[88:89], v[84:85], off
	v_exp_f32_e32 v95, v83
	s_nop 0
	v_pk_add_f32 v[94:95], v[94:95], 1.0 op_sel_hi:[1,0]
	v_div_scale_f32 v103, s[4:5], 1.0, v80, 1.0
	v_div_scale_f32 v105, s[6:7], 1.0, v95, 1.0
	v_div_scale_f32 v107, s[8:9], 1.0, v94, 1.0
	s_mov_b64 vcc, s[4:5]
	v_rcp_f32_e32 v81, v81
	s_mov_b64 vcc, s[6:7]
	v_rcp_f32_e32 v80, v80
	s_mov_b64 vcc, s[8:9]
	v_rcp_f32_e32 v95, v95
	v_rcp_f32_e32 v94, v94
	v_lshlrev_b64 v[84:85], 10, v[92:93]
	v_lshl_add_u64 v[90:91], v[92:93], 2, s[18:19]
	v_lshl_add_u64 v[92:93], v[84:85], 0, v[142:143]
	v_lshlrev_b64 v[98:99], 1, v[92:93]
	v_lshl_add_u64 v[82:83], s[10:11], 0, v[98:99]
	s_waitcnt vmcnt(1)
	v_lshlrev_b32_e32 v100, 16, v86
	v_and_b32_e32 v101, 0xffff0000, v86
	v_lshlrev_b32_e32 v86, 16, v87
	v_and_b32_e32 v87, 0xffff0000, v87
	s_waitcnt vmcnt(0)
	v_lshlrev_b32_e32 v102, 16, v88
	v_and_b32_e32 v103, 0xffff0000, v88
	v_lshlrev_b32_e32 v88, 16, v89
	v_and_b32_e32 v89, 0xffff0000, v89
	v_pk_fma_f32 v[88:89], v[94:95], v[86:87], v[88:89]
	v_pk_fma_f32 v[86:87], v[80:81], v[100:101], v[102:103]
	global_store_dwordx4 v[96:97], v[86:89], off offset:576
	global_load_dword v90, v[90:91], off
	s_nop 0
	global_load_dwordx2 v[86:87], v[82:83], off
	v_lshl_add_u64 v[80:81], s[12:13], 0, v[98:99]
	global_load_dwordx2 v[88:89], v[80:81], off
	v_lshl_add_u64 v[80:81], v[92:93], 2, s[14:15]
	s_waitcnt vmcnt(2)
	v_fmamk_f32 v93, v90, 0x3a800000, v158
	s_waitcnt vmcnt(1)
	v_lshlrev_b32_e32 v90, 16, v86
	v_and_b32_e32 v91, 0xffff0000, v86
	v_mul_f32_e32 v86, 0x4b800000, v93
	v_cmp_gt_f32_e32 vcc, s44, v93
	v_lshlrev_b32_e32 v92, 16, v87
	s_waitcnt vmcnt(0)
	v_lshlrev_b32_e32 v94, 16, v88
	v_cndmask_b32_e32 v86, v93, v86, vcc
	v_rsq_f32_e32 v86, v86
	v_and_b32_e32 v93, 0xffff0000, v87
	v_and_b32_e32 v95, 0xffff0000, v88
	v_lshlrev_b32_e32 v88, 16, v89
	v_mul_f32_e32 v87, 0x45800000, v86
	v_cndmask_b32_e32 v86, v86, v87, vcc
	v_mul_f32_e64 v76, v76, -v86
	v_mul_f32_e64 v77, v77, -v86
	v_mul_f32_e32 v76, 0x3fb8aa3b, v76
	v_mul_f32_e32 v77, 0x3fb8aa3b, v77
	v_mul_f32_e64 v78, v78, -v86
	v_mul_f32_e64 v79, v79, -v86
	v_exp_f32_e32 v76, v76
	v_exp_f32_e32 v77, v77
	v_mul_f32_e32 v78, 0x3fb8aa3b, v78
	v_mul_f32_e32 v79, 0x3fb8aa3b, v79
	v_exp_f32_e32 v78, v78
	v_exp_f32_e32 v79, v79
	v_pk_add_f32 v[76:77], v[76:77], 1.0 op_sel_hi:[1,0]
	v_and_b32_e32 v89, 0xffff0000, v89
	v_pk_add_f32 v[78:79], v[78:79], 1.0 op_sel_hi:[1,0]
	v_div_scale_f32 v98, s[4:5], 1.0, v76, 1.0
	v_div_scale_f32 v100, s[6:7], 1.0, v79, 1.0
	v_div_scale_f32 v102, s[8:9], 1.0, v78, 1.0
	s_mov_b64 vcc, s[4:5]
	v_rcp_f32_e32 v77, v77
	s_mov_b64 vcc, s[6:7]
	v_rcp_f32_e32 v76, v76
	s_mov_b64 vcc, s[8:9]
	v_rcp_f32_e32 v79, v79
	v_rcp_f32_e32 v78, v78
	v_pk_fma_f32 v[76:77], v[76:77], v[90:91], v[94:95]
	v_pk_fma_f32 v[78:79], v[78:79], v[92:93], v[88:89]
	global_store_dwordx4 v[80:81], v[76:79], off
	global_load_dwordx2 v[76:77], v[82:83], off offset:32
	v_mul_f32_e64 v72, v72, -v86
	v_lshl_add_u64 v[78:79], v[84:85], 0, v[140:141]
	v_lshl_add_u64 v[78:79], v[78:79], 1, s[12:13]
	global_load_dwordx2 v[78:79], v[78:79], off
	v_mul_f32_e64 v73, v73, -v86
	v_mul_f32_e32 v72, 0x3fb8aa3b, v72
	v_mul_f32_e32 v73, 0x3fb8aa3b, v73
	v_mul_f32_e64 v74, v74, -v86
	v_mul_f32_e64 v75, v75, -v86
	v_exp_f32_e32 v72, v72
	v_exp_f32_e32 v73, v73
	v_mul_f32_e32 v74, 0x3fb8aa3b, v74
	v_mul_f32_e32 v75, 0x3fb8aa3b, v75
	v_exp_f32_e32 v74, v74
	v_exp_f32_e32 v75, v75
	v_pk_add_f32 v[72:73], v[72:73], 1.0 op_sel_hi:[1,0]
	v_mul_f32_e64 v68, v68, -v86
	v_pk_add_f32 v[74:75], v[74:75], 1.0 op_sel_hi:[1,0]
	v_div_scale_f32 v90, s[4:5], 1.0, v72, 1.0
	v_div_scale_f32 v92, s[6:7], 1.0, v75, 1.0
	v_div_scale_f32 v94, s[8:9], 1.0, v74, 1.0
	s_mov_b64 vcc, s[4:5]
	v_rcp_f32_e32 v73, v73
	s_mov_b64 vcc, s[6:7]
	v_rcp_f32_e32 v72, v72
	s_mov_b64 vcc, s[8:9]
	v_rcp_f32_e32 v75, v75
	v_rcp_f32_e32 v74, v74
	v_mul_f32_e64 v69, v69, -v86
	v_mul_f32_e32 v68, 0x3fb8aa3b, v68
	v_mul_f32_e32 v69, 0x3fb8aa3b, v69
	v_mul_f32_e64 v70, v70, -v86
	v_mul_f32_e64 v71, v71, -v86
	v_exp_f32_e32 v68, v68
	s_waitcnt vmcnt(1)
;   DI void operator()(const f32x4 (&acc)[2][2][4][2], const pg8::Unit& u, int wr, int wc, int fr, int fq) const {
;     ...
;         const int row = u.pm * 256 + ai * 128 + wr * 64 + m * 16 + fr; float rs = 0.f;
;         const float rstd = rsqrtf(ssx[row] * (1.f / DM) + EPS);
; #pragma unroll
;         for (int bj = 0; bj < 2; ++bj)
; #pragma unroll
;           for (int n = 0; n < 2; ++n) {
;             const int col = u.pn * 256 + bj * 128 + wc * 32 + n * 16 + fq * 4; const size_t off = (size_t)row * DM + col;
;             f32x4 g;
; #pragma unroll
;             for (int j = 0; j < 4; ++j) g[j] = 1.f / (1.f + __expf(-rstd * acc[ai][bj][m][n][j]));
;             const u32x2 pw = *(const u32x2*)(PT + off); f32x4 pp; pp.x = __uint_as_float(pw.x << 16); pp.y = __uint_as_float(pw.x & 0xffff0000u); pp.z = __uint_as_float(pw.y << 16); pp.w = __uint_as_float(pw.y & 0xffff0000u);
;             const u32x2 xw = *(const u32x2*)(X1B + off); f32x4 x1; x1.x = __uint_as_float(xw.x << 16); x1.y = __uint_as_float(xw.x & 0xffff0000u); x1.z = __uint_as_float(xw.y << 16); x1.w = __uint_as_float(xw.y & 0xffff0000u);
;             const f32x4 xn = x1 + pp * g;
;             if (layer != 0) *(f32x4*)(out + off) = xn;
	v_lshlrev_b32_e32 v88, 16, v76
	v_and_b32_e32 v89, 0xffff0000, v76
	v_lshlrev_b32_e32 v76, 16, v77
	v_and_b32_e32 v77, 0xffff0000, v77
	s_waitcnt vmcnt(0)
	v_lshlrev_b32_e32 v90, 16, v78
	v_and_b32_e32 v91, 0xffff0000, v78
	v_lshlrev_b32_e32 v78, 16, v79
	v_and_b32_e32 v79, 0xffff0000, v79
	v_pk_fma_f32 v[74:75], v[74:75], v[76:77], v[78:79]
	v_pk_fma_f32 v[72:73], v[72:73], v[88:89], v[90:91]
	global_store_dwordx4 v[80:81], v[72:75], off offset:64
	global_load_dwordx2 v[72:73], v[82:83], off offset:256
	v_exp_f32_e32 v69, v69
	v_lshl_add_u64 v[74:75], v[84:85], 0, v[120:121]
	v_lshl_add_u64 v[74:75], v[74:75], 1, s[12:13]
	global_load_dwordx2 v[74:75], v[74:75], off
	v_mul_f32_e32 v70, 0x3fb8aa3b, v70
	v_mul_f32_e32 v71, 0x3fb8aa3b, v71
	v_exp_f32_e32 v70, v70
	v_exp_f32_e32 v71, v71
	v_pk_add_f32 v[68:69], v[68:69], 1.0 op_sel_hi:[1,0]
	v_mul_f32_e64 v64, v64, -v86
	v_pk_add_f32 v[70:71], v[70:71], 1.0 op_sel_hi:[1,0]
	v_div_scale_f32 v87, s[4:5], 1.0, v68, 1.0
	v_div_scale_f32 v89, s[6:7], 1.0, v71, 1.0
	v_div_scale_f32 v91, s[8:9], 1.0, v70, 1.0
	s_mov_b64 vcc, s[4:5]
	v_rcp_f32_e32 v69, v69
	s_mov_b64 vcc, s[6:7]
	v_rcp_f32_e32 v68, v68
	s_mov_b64 vcc, s[8:9]
	v_rcp_f32_e32 v71, v71
	v_rcp_f32_e32 v70, v70
	v_mul_f32_e64 v65, v65, -v86
	v_mul_f32_e32 v64, 0x3fb8aa3b, v64
	v_mul_f32_e32 v65, 0x3fb8aa3b, v65
	v_mul_f32_e64 v66, v66, -v86
	v_mul_f32_e64 v67, v67, -v86
	v_exp_f32_e32 v64, v64
	v_exp_f32_e32 v65, v65
	v_mul_f32_e32 v66, 0x3fb8aa3b, v66
	v_mul_f32_e32 v67, 0x3fb8aa3b, v67
	v_add_u32_e32 v76, 0x80, v144
	v_pk_add_f32 v[64:65], v[64:65], 1.0 op_sel_hi:[1,0]
	v_ashrrev_i32_e32 v77, 31, v76
	s_waitcnt vmcnt(1)
	v_lshlrev_b32_e32 v78, 16, v72
	v_and_b32_e32 v79, 0xffff0000, v72
	v_lshlrev_b32_e32 v72, 16, v73
	v_and_b32_e32 v73, 0xffff0000, v73
	s_waitcnt vmcnt(0)
	v_lshlrev_b32_e32 v88, 16, v74
	v_and_b32_e32 v89, 0xffff0000, v74
	v_lshlrev_b32_e32 v74, 16, v75
	v_and_b32_e32 v75, 0xffff0000, v75
	v_pk_fma_f32 v[70:71], v[70:71], v[72:73], v[74:75]
	v_pk_fma_f32 v[68:69], v[68:69], v[78:79], v[88:89]
	global_store_dwordx4 v[80:81], v[68:71], off offset:512
	global_load_dwordx2 v[70:71], v[82:83], off offset:288
	v_exp_f32_e32 v78, v66
	v_lshl_add_u64 v[68:69], v[84:85], 0, v[116:117]
	v_lshl_add_u64 v[68:69], v[68:69], 1, s[12:13]
	global_load_dwordx2 v[72:73], v[68:69], off
	v_exp_f32_e32 v79, v67
	s_nop 0
	v_pk_add_f32 v[78:79], v[78:79], 1.0 op_sel_hi:[1,0]
	v_div_scale_f32 v87, s[4:5], 1.0, v64, 1.0
	v_div_scale_f32 v89, s[6:7], 1.0, v79, 1.0
	v_div_scale_f32 v91, s[8:9], 1.0, v78, 1.0
	s_mov_b64 vcc, s[4:5]
	v_rcp_f32_e32 v65, v65
	s_mov_b64 vcc, s[6:7]
	v_rcp_f32_e32 v64, v64
	s_mov_b64 vcc, s[8:9]
	v_rcp_f32_e32 v79, v79
	v_rcp_f32_e32 v78, v78
	v_lshlrev_b64 v[68:69], 10, v[76:77]
	v_lshl_add_u64 v[74:75], v[76:77], 2, s[18:19]
	v_lshl_add_u64 v[76:77], v[68:69], 0, v[142:143]
	v_lshlrev_b64 v[82:83], 1, v[76:77]
	v_lshl_add_u64 v[66:67], s[10:11], 0, v[82:83]
	s_waitcnt vmcnt(1)
	v_lshlrev_b32_e32 v84, 16, v70
	v_and_b32_e32 v85, 0xffff0000, v70
	v_lshlrev_b32_e32 v70, 16, v71
	v_and_b32_e32 v71, 0xffff0000, v71
	s_waitcnt vmcnt(0)
	v_lshlrev_b32_e32 v86, 16, v72
	v_and_b32_e32 v87, 0xffff0000, v72
	v_lshlrev_b32_e32 v72, 16, v73
	v_and_b32_e32 v73, 0xffff0000, v73
	v_pk_fma_f32 v[72:73], v[78:79], v[70:71], v[72:73]
	v_pk_fma_f32 v[70:71], v[64:65], v[84:85], v[86:87]
	global_store_dwordx4 v[80:81], v[70:73], off offset:576
	global_load_dword v74, v[74:75], off
	s_nop 0
	global_load_dwordx2 v[70:71], v[66:67], off
	v_lshl_add_u64 v[64:65], s[12:13], 0, v[82:83]
	global_load_dwordx2 v[72:73], v[64:65], off
	v_lshl_add_u64 v[64:65], v[76:77], 2, s[14:15]
	s_waitcnt vmcnt(2)
	v_fmamk_f32 v77, v74, 0x3a800000, v158
	s_waitcnt vmcnt(1)
	v_lshlrev_b32_e32 v74, 16, v70
	v_and_b32_e32 v75, 0xffff0000, v70
	v_mul_f32_e32 v70, 0x4b800000, v77
	v_cmp_gt_f32_e32 vcc, s44, v77
	v_lshlrev_b32_e32 v76, 16, v71
	s_waitcnt vmcnt(0)
	v_lshlrev_b32_e32 v78, 16, v72
	v_cndmask_b32_e32 v70, v77, v70, vcc
	v_rsq_f32_e32 v70, v70
	v_and_b32_e32 v77, 0xffff0000, v71
	v_and_b32_e32 v79, 0xffff0000, v72
	v_lshlrev_b32_e32 v72, 16, v73
	v_mul_f32_e32 v71, 0x45800000, v70
	v_cndmask_b32_e32 v70, v70, v71, vcc
	v_mul_f32_e64 v60, v60, -v70
	v_mul_f32_e64 v61, v61, -v70
	v_mul_f32_e32 v60, 0x3fb8aa3b, v60
	v_mul_f32_e32 v61, 0x3fb8aa3b, v61
	v_mul_f32_e64 v62, v62, -v70
	v_mul_f32_e64 v63, v63, -v70
	v_exp_f32_e32 v60, v60
	v_exp_f32_e32 v61, v61
	v_mul_f32_e32 v62, 0x3fb8aa3b, v62
	v_mul_f32_e32 v63, 0x3fb8aa3b, v63
	v_exp_f32_e32 v62, v62
	v_exp_f32_e32 v63, v63
	v_pk_add_f32 v[60:61], v[60:61], 1.0 op_sel_hi:[1,0]
	v_and_b32_e32 v73, 0xffff0000, v73
	v_pk_add_f32 v[62:63], v[62:63], 1.0 op_sel_hi:[1,0]
	v_div_scale_f32 v82, s[4:5], 1.0, v60, 1.0
	v_div_scale_f32 v84, s[6:7], 1.0, v63, 1.0
	v_div_scale_f32 v86, s[8:9], 1.0, v62, 1.0
	s_mov_b64 vcc, s[4:5]
	v_rcp_f32_e32 v61, v61
	s_mov_b64 vcc, s[6:7]
	v_rcp_f32_e32 v60, v60
	s_mov_b64 vcc, s[8:9]
	v_rcp_f32_e32 v63, v63
	v_rcp_f32_e32 v62, v62
	v_pk_fma_f32 v[60:61], v[60:61], v[74:75], v[78:79]
	v_pk_fma_f32 v[62:63], v[62:63], v[76:77], v[72:73]
	global_store_dwordx4 v[64:65], v[60:63], off
	global_load_dwordx2 v[60:61], v[66:67], off offset:32
	v_mul_f32_e64 v56, v56, -v70
	v_lshl_add_u64 v[62:63], v[68:69], 0, v[140:141]
	v_lshl_add_u64 v[62:63], v[62:63], 1, s[12:13]
	global_load_dwordx2 v[62:63], v[62:63], off
	v_mul_f32_e64 v57, v57, -v70
	v_mul_f32_e32 v56, 0x3fb8aa3b, v56
	v_mul_f32_e32 v57, 0x3fb8aa3b, v57
	v_mul_f32_e64 v58, v58, -v70
	v_mul_f32_e64 v59, v59, -v70
	v_exp_f32_e32 v56, v56
	v_exp_f32_e32 v57, v57
	v_mul_f32_e32 v58, 0x3fb8aa3b, v58
	v_mul_f32_e32 v59, 0x3fb8aa3b, v59
	v_exp_f32_e32 v58, v58
	v_exp_f32_e32 v59, v59
	v_pk_add_f32 v[56:57], v[56:57], 1.0 op_sel_hi:[1,0]
	v_mul_f32_e64 v52, v52, -v70
	v_pk_add_f32 v[58:59], v[58:59], 1.0 op_sel_hi:[1,0]
	v_div_scale_f32 v74, s[4:5], 1.0, v56, 1.0
	v_div_scale_f32 v76, s[6:7], 1.0, v59, 1.0
	v_div_scale_f32 v78, s[8:9], 1.0, v58, 1.0
	s_mov_b64 vcc, s[4:5]
	v_rcp_f32_e32 v57, v57
	s_mov_b64 vcc, s[6:7]
	v_rcp_f32_e32 v56, v56
	s_mov_b64 vcc, s[8:9]
	v_rcp_f32_e32 v59, v59
	v_rcp_f32_e32 v58, v58
	v_mul_f32_e64 v53, v53, -v70
	v_mul_f32_e32 v52, 0x3fb8aa3b, v52
	v_mul_f32_e32 v53, 0x3fb8aa3b, v53
	v_mul_f32_e64 v54, v54, -v70
	v_mul_f32_e64 v55, v55, -v70
	v_exp_f32_e32 v52, v52
	s_waitcnt vmcnt(1)
;   DI void operator()(const f32x4 (&acc)[2][2][4][2], const pg8::Unit& u, int wr, int wc, int fr, int fq) const {
;     ...
;         const int row = u.pm * 256 + ai * 128 + wr * 64 + m * 16 + fr; float rs = 0.f;
;         const float rstd = rsqrtf(ssx[row] * (1.f / DM) + EPS);
; #pragma unroll
;         for (int bj = 0; bj < 2; ++bj)
; #pragma unroll
;           for (int n = 0; n < 2; ++n) {
;             const int col = u.pn * 256 + bj * 128 + wc * 32 + n * 16 + fq * 4; const size_t off = (size_t)row * DM + col;
;             f32x4 g;
; #pragma unroll
;             for (int j = 0; j < 4; ++j) g[j] = 1.f / (1.f + __expf(-rstd * acc[ai][bj][m][n][j]));
;             const u32x2 pw = *(const u32x2*)(PT + off); f32x4 pp; pp.x = __uint_as_float(pw.x << 16); pp.y = __uint_as_float(pw.x & 0xffff0000u); pp.z = __uint_as_float(pw.y << 16); pp.w = __uint_as_float(pw.y & 0xffff0000u);
;             const u32x2 xw = *(const u32x2*)(X1B + off); f32x4 x1; x1.x = __uint_as_float(xw.x << 16); x1.y = __uint_as_float(xw.x & 0xffff0000u); x1.z = __uint_as_float(xw.y << 16); x1.w = __uint_as_float(xw.y & 0xffff0000u);
;             const f32x4 xn = x1 + pp * g;
;             if (layer != 0) *(f32x4*)(out + off) = xn;
	v_lshlrev_b32_e32 v72, 16, v60
	v_and_b32_e32 v73, 0xffff0000, v60
	v_lshlrev_b32_e32 v60, 16, v61
	v_and_b32_e32 v61, 0xffff0000, v61
	s_waitcnt vmcnt(0)
	v_lshlrev_b32_e32 v74, 16, v62
	v_and_b32_e32 v75, 0xffff0000, v62
	v_lshlrev_b32_e32 v62, 16, v63
	v_and_b32_e32 v63, 0xffff0000, v63
	v_pk_fma_f32 v[58:59], v[58:59], v[60:61], v[62:63]
	v_pk_fma_f32 v[56:57], v[56:57], v[72:73], v[74:75]
	global_store_dwordx4 v[64:65], v[56:59], off offset:64
	global_load_dwordx2 v[56:57], v[66:67], off offset:256
	v_exp_f32_e32 v53, v53
	v_lshl_add_u64 v[58:59], v[68:69], 0, v[120:121]
	v_lshl_add_u64 v[58:59], v[58:59], 1, s[12:13]
	global_load_dwordx2 v[58:59], v[58:59], off
	v_mul_f32_e32 v54, 0x3fb8aa3b, v54
	v_mul_f32_e32 v55, 0x3fb8aa3b, v55
	v_exp_f32_e32 v54, v54
	v_exp_f32_e32 v55, v55
	v_pk_add_f32 v[52:53], v[52:53], 1.0 op_sel_hi:[1,0]
	v_mul_f32_e64 v48, v48, -v70
	v_pk_add_f32 v[54:55], v[54:55], 1.0 op_sel_hi:[1,0]
	v_div_scale_f32 v71, s[4:5], 1.0, v52, 1.0
	v_div_scale_f32 v73, s[6:7], 1.0, v55, 1.0
	v_div_scale_f32 v75, s[8:9], 1.0, v54, 1.0
	s_mov_b64 vcc, s[4:5]
	v_rcp_f32_e32 v53, v53
	s_mov_b64 vcc, s[6:7]
	v_rcp_f32_e32 v52, v52
	s_mov_b64 vcc, s[8:9]
	v_rcp_f32_e32 v55, v55
	v_rcp_f32_e32 v54, v54
	v_mul_f32_e64 v49, v49, -v70
	v_mul_f32_e32 v48, 0x3fb8aa3b, v48
	v_mul_f32_e32 v49, 0x3fb8aa3b, v49
	v_mul_f32_e64 v50, v50, -v70
	v_mul_f32_e64 v51, v51, -v70
	v_exp_f32_e32 v48, v48
	v_exp_f32_e32 v49, v49
	v_mul_f32_e32 v50, 0x3fb8aa3b, v50
	v_mul_f32_e32 v51, 0x3fb8aa3b, v51
	v_add_u32_e32 v60, 0x90, v144
	v_pk_add_f32 v[48:49], v[48:49], 1.0 op_sel_hi:[1,0]
	v_ashrrev_i32_e32 v61, 31, v60
	s_waitcnt vmcnt(1)
	v_lshlrev_b32_e32 v62, 16, v56
	v_and_b32_e32 v63, 0xffff0000, v56
	v_lshlrev_b32_e32 v56, 16, v57
	v_and_b32_e32 v57, 0xffff0000, v57
	s_waitcnt vmcnt(0)
	v_lshlrev_b32_e32 v72, 16, v58
	v_and_b32_e32 v73, 0xffff0000, v58
	v_lshlrev_b32_e32 v58, 16, v59
	v_and_b32_e32 v59, 0xffff0000, v59
	v_pk_fma_f32 v[54:55], v[54:55], v[56:57], v[58:59]
	v_pk_fma_f32 v[52:53], v[52:53], v[62:63], v[72:73]
	global_store_dwordx4 v[64:65], v[52:55], off offset:512
	global_load_dwordx2 v[54:55], v[66:67], off offset:288
	v_exp_f32_e32 v62, v50
	v_lshl_add_u64 v[52:53], v[68:69], 0, v[116:117]
	v_lshl_add_u64 v[52:53], v[52:53], 1, s[12:13]
	global_load_dwordx2 v[56:57], v[52:53], off
	v_exp_f32_e32 v63, v51
	s_nop 0
	v_pk_add_f32 v[62:63], v[62:63], 1.0 op_sel_hi:[1,0]
	v_div_scale_f32 v71, s[4:5], 1.0, v48, 1.0
	v_div_scale_f32 v73, s[6:7], 1.0, v63, 1.0
	v_div_scale_f32 v75, s[8:9], 1.0, v62, 1.0
	s_mov_b64 vcc, s[4:5]
	v_rcp_f32_e32 v49, v49
	s_mov_b64 vcc, s[6:7]
	v_rcp_f32_e32 v48, v48
	s_mov_b64 vcc, s[8:9]
	v_rcp_f32_e32 v63, v63
	v_rcp_f32_e32 v62, v62
	v_lshlrev_b64 v[52:53], 10, v[60:61]
	v_lshl_add_u64 v[58:59], v[60:61], 2, s[18:19]
	v_lshl_add_u64 v[60:61], v[52:53], 0, v[142:143]
	v_lshlrev_b64 v[66:67], 1, v[60:61]
	v_lshl_add_u64 v[50:51], s[10:11], 0, v[66:67]
	s_waitcnt vmcnt(1)
	v_lshlrev_b32_e32 v68, 16, v54
	v_and_b32_e32 v69, 0xffff0000, v54
	v_lshlrev_b32_e32 v54, 16, v55
	v_and_b32_e32 v55, 0xffff0000, v55
	s_waitcnt vmcnt(0)
	v_lshlrev_b32_e32 v70, 16, v56
	v_and_b32_e32 v71, 0xffff0000, v56
	v_lshlrev_b32_e32 v56, 16, v57
	v_and_b32_e32 v57, 0xffff0000, v57
	v_pk_fma_f32 v[56:57], v[62:63], v[54:55], v[56:57]
	v_pk_fma_f32 v[54:55], v[48:49], v[68:69], v[70:71]
	global_store_dwordx4 v[64:65], v[54:57], off offset:576
	global_load_dword v62, v[58:59], off
	global_load_dwordx2 v[54:55], v[50:51], off
	v_lshl_add_u64 v[48:49], s[12:13], 0, v[66:67]
	global_load_dwordx2 v[56:57], v[48:49], off
	v_lshl_add_u64 v[48:49], v[60:61], 2, s[14:15]
	s_waitcnt vmcnt(2)
	v_fmamk_f32 v61, v62, 0x3a800000, v158
	s_waitcnt vmcnt(1)
	v_lshlrev_b32_e32 v58, 16, v54
	v_and_b32_e32 v59, 0xffff0000, v54
	v_mul_f32_e32 v54, 0x4b800000, v61
	v_cmp_gt_f32_e32 vcc, s44, v61
	v_lshlrev_b32_e32 v60, 16, v55
	s_waitcnt vmcnt(0)
	v_lshlrev_b32_e32 v62, 16, v56
	v_cndmask_b32_e32 v54, v61, v54, vcc
	v_rsq_f32_e32 v54, v54
	v_and_b32_e32 v61, 0xffff0000, v55
	v_and_b32_e32 v63, 0xffff0000, v56
	v_lshlrev_b32_e32 v56, 16, v57
	v_mul_f32_e32 v55, 0x45800000, v54
	v_cndmask_b32_e32 v54, v54, v55, vcc
	v_mul_f32_e64 v44, v44, -v54
	v_mul_f32_e64 v45, v45, -v54
	v_mul_f32_e32 v44, 0x3fb8aa3b, v44
	v_mul_f32_e32 v45, 0x3fb8aa3b, v45
	v_mul_f32_e64 v46, v46, -v54
	v_mul_f32_e64 v47, v47, -v54
	v_exp_f32_e32 v44, v44
	v_exp_f32_e32 v45, v45
	v_mul_f32_e32 v46, 0x3fb8aa3b, v46
	v_mul_f32_e32 v47, 0x3fb8aa3b, v47
	v_exp_f32_e32 v46, v46
	v_exp_f32_e32 v47, v47
	v_pk_add_f32 v[44:45], v[44:45], 1.0 op_sel_hi:[1,0]
	v_and_b32_e32 v57, 0xffff0000, v57
	v_pk_add_f32 v[46:47], v[46:47], 1.0 op_sel_hi:[1,0]
	v_div_scale_f32 v66, s[4:5], 1.0, v44, 1.0
	v_div_scale_f32 v68, s[6:7], 1.0, v47, 1.0
	v_div_scale_f32 v70, s[8:9], 1.0, v46, 1.0
	s_mov_b64 vcc, s[4:5]
	v_rcp_f32_e32 v45, v45
	s_mov_b64 vcc, s[6:7]
	v_rcp_f32_e32 v44, v44
	s_mov_b64 vcc, s[8:9]
	v_rcp_f32_e32 v47, v47
	v_rcp_f32_e32 v46, v46
	v_pk_fma_f32 v[44:45], v[44:45], v[58:59], v[62:63]
	v_pk_fma_f32 v[46:47], v[46:47], v[60:61], v[56:57]
	global_store_dwordx4 v[48:49], v[44:47], off
	global_load_dwordx2 v[44:45], v[50:51], off offset:32
	v_mul_f32_e64 v40, v40, -v54
	v_lshl_add_u64 v[46:47], v[52:53], 0, v[140:141]
	v_lshl_add_u64 v[46:47], v[46:47], 1, s[12:13]
	global_load_dwordx2 v[46:47], v[46:47], off
	v_mul_f32_e64 v41, v41, -v54
	v_mul_f32_e32 v40, 0x3fb8aa3b, v40
	v_mul_f32_e32 v41, 0x3fb8aa3b, v41
	v_mul_f32_e64 v42, v42, -v54
	v_mul_f32_e64 v43, v43, -v54
	v_exp_f32_e32 v40, v40
	v_exp_f32_e32 v41, v41
	v_mul_f32_e32 v42, 0x3fb8aa3b, v42
	v_mul_f32_e32 v43, 0x3fb8aa3b, v43
	v_exp_f32_e32 v42, v42
	v_exp_f32_e32 v43, v43
	v_pk_add_f32 v[40:41], v[40:41], 1.0 op_sel_hi:[1,0]
	v_mul_f32_e64 v36, v36, -v54
	v_pk_add_f32 v[42:43], v[42:43], 1.0 op_sel_hi:[1,0]
	v_div_scale_f32 v58, s[4:5], 1.0, v40, 1.0
	v_div_scale_f32 v60, s[6:7], 1.0, v43, 1.0
	v_div_scale_f32 v62, s[8:9], 1.0, v42, 1.0
	s_mov_b64 vcc, s[4:5]
	v_rcp_f32_e32 v41, v41
	s_mov_b64 vcc, s[6:7]
	v_rcp_f32_e32 v40, v40
	s_mov_b64 vcc, s[8:9]
	v_rcp_f32_e32 v43, v43
	v_rcp_f32_e32 v42, v42
	v_mul_f32_e64 v37, v37, -v54
	v_mul_f32_e32 v36, 0x3fb8aa3b, v36
	v_mul_f32_e32 v37, 0x3fb8aa3b, v37
	v_mul_f32_e64 v38, v38, -v54
	v_mul_f32_e64 v39, v39, -v54
	v_exp_f32_e32 v36, v36
	s_waitcnt vmcnt(1)
;   DI void operator()(const f32x4 (&acc)[2][2][4][2], const pg8::Unit& u, int wr, int wc, int fr, int fq) const {
;     ...
;         const int row = u.pm * 256 + ai * 128 + wr * 64 + m * 16 + fr; float rs = 0.f;
;         const float rstd = rsqrtf(ssx[row] * (1.f / DM) + EPS);
; #pragma unroll
;         for (int bj = 0; bj < 2; ++bj)
; #pragma unroll
;           for (int n = 0; n < 2; ++n) {
;             const int col = u.pn * 256 + bj * 128 + wc * 32 + n * 16 + fq * 4; const size_t off = (size_t)row * DM + col;
;             f32x4 g;
; #pragma unroll
;             for (int j = 0; j < 4; ++j) g[j] = 1.f / (1.f + __expf(-rstd * acc[ai][bj][m][n][j]));
;             const u32x2 pw = *(const u32x2*)(PT + off); f32x4 pp; pp.x = __uint_as_float(pw.x << 16); pp.y = __uint_as_float(pw.x & 0xffff0000u); pp.z = __uint_as_float(pw.y << 16); pp.w = __uint_as_float(pw.y & 0xffff0000u);
;             const u32x2 xw = *(const u32x2*)(X1B + off); f32x4 x1; x1.x = __uint_as_float(xw.x << 16); x1.y = __uint_as_float(xw.x & 0xffff0000u); x1.z = __uint_as_float(xw.y << 16); x1.w = __uint_as_float(xw.y & 0xffff0000u);
;             const f32x4 xn = x1 + pp * g;
;             if (layer != 0) *(f32x4*)(out + off) = xn;
	v_lshlrev_b32_e32 v56, 16, v44
	v_and_b32_e32 v57, 0xffff0000, v44
	v_lshlrev_b32_e32 v44, 16, v45
	v_and_b32_e32 v45, 0xffff0000, v45
	s_waitcnt vmcnt(0)
	v_lshlrev_b32_e32 v58, 16, v46
	v_and_b32_e32 v59, 0xffff0000, v46
	v_lshlrev_b32_e32 v46, 16, v47
	v_and_b32_e32 v47, 0xffff0000, v47
	v_pk_fma_f32 v[42:43], v[42:43], v[44:45], v[46:47]
	v_pk_fma_f32 v[40:41], v[40:41], v[56:57], v[58:59]
	global_store_dwordx4 v[48:49], v[40:43], off offset:64
	global_load_dwordx2 v[40:41], v[50:51], off offset:256
	v_exp_f32_e32 v37, v37
	v_lshl_add_u64 v[42:43], v[52:53], 0, v[120:121]
	v_lshl_add_u64 v[42:43], v[42:43], 1, s[12:13]
	global_load_dwordx2 v[42:43], v[42:43], off
	v_mul_f32_e32 v38, 0x3fb8aa3b, v38
	v_mul_f32_e32 v39, 0x3fb8aa3b, v39
	v_exp_f32_e32 v38, v38
	v_exp_f32_e32 v39, v39
	v_pk_add_f32 v[36:37], v[36:37], 1.0 op_sel_hi:[1,0]
	v_mul_f32_e64 v32, v32, -v54
	v_pk_add_f32 v[38:39], v[38:39], 1.0 op_sel_hi:[1,0]
	v_div_scale_f32 v55, s[4:5], 1.0, v36, 1.0
	v_div_scale_f32 v57, s[6:7], 1.0, v39, 1.0
	v_div_scale_f32 v59, s[8:9], 1.0, v38, 1.0
	s_mov_b64 vcc, s[4:5]
	v_rcp_f32_e32 v37, v37
	s_mov_b64 vcc, s[6:7]
	v_rcp_f32_e32 v36, v36
	s_mov_b64 vcc, s[8:9]
	v_rcp_f32_e32 v39, v39
	v_rcp_f32_e32 v38, v38
	v_mul_f32_e64 v33, v33, -v54
	v_mul_f32_e32 v32, 0x3fb8aa3b, v32
	v_mul_f32_e32 v33, 0x3fb8aa3b, v33
	v_mul_f32_e64 v34, v34, -v54
	v_mul_f32_e64 v35, v35, -v54
	v_exp_f32_e32 v32, v32
	v_exp_f32_e32 v33, v33
	v_mul_f32_e32 v34, 0x3fb8aa3b, v34
	v_mul_f32_e32 v35, 0x3fb8aa3b, v35
	v_add_u32_e32 v44, 0xa0, v144
	v_pk_add_f32 v[32:33], v[32:33], 1.0 op_sel_hi:[1,0]
	v_ashrrev_i32_e32 v45, 31, v44
	s_waitcnt vmcnt(1)
	v_lshlrev_b32_e32 v46, 16, v40
	v_and_b32_e32 v47, 0xffff0000, v40
	v_lshlrev_b32_e32 v40, 16, v41
	v_and_b32_e32 v41, 0xffff0000, v41
	s_waitcnt vmcnt(0)
	v_lshlrev_b32_e32 v56, 16, v42
	v_and_b32_e32 v57, 0xffff0000, v42
	v_lshlrev_b32_e32 v42, 16, v43
	v_and_b32_e32 v43, 0xffff0000, v43
	v_pk_fma_f32 v[38:39], v[38:39], v[40:41], v[42:43]
	v_pk_fma_f32 v[36:37], v[36:37], v[46:47], v[56:57]
	global_store_dwordx4 v[48:49], v[36:39], off offset:512
	global_load_dwordx2 v[38:39], v[50:51], off offset:288
	v_exp_f32_e32 v46, v34
	v_lshl_add_u64 v[36:37], v[52:53], 0, v[116:117]
	v_lshl_add_u64 v[36:37], v[36:37], 1, s[12:13]
	global_load_dwordx2 v[40:41], v[36:37], off
	v_exp_f32_e32 v47, v35
	s_nop 0
	v_pk_add_f32 v[46:47], v[46:47], 1.0 op_sel_hi:[1,0]
	v_div_scale_f32 v55, s[4:5], 1.0, v32, 1.0
	v_div_scale_f32 v57, s[6:7], 1.0, v47, 1.0
	v_div_scale_f32 v59, s[8:9], 1.0, v46, 1.0
	s_mov_b64 vcc, s[4:5]
	v_rcp_f32_e32 v33, v33
	s_mov_b64 vcc, s[6:7]
	v_rcp_f32_e32 v32, v32
	s_mov_b64 vcc, s[8:9]
	v_rcp_f32_e32 v47, v47
	v_rcp_f32_e32 v46, v46
	v_lshlrev_b64 v[36:37], 10, v[44:45]
	v_lshl_add_u64 v[42:43], v[44:45], 2, s[18:19]
	v_lshl_add_u64 v[44:45], v[36:37], 0, v[142:143]
	v_lshlrev_b64 v[50:51], 1, v[44:45]
	v_lshl_add_u64 v[34:35], s[10:11], 0, v[50:51]
	s_waitcnt vmcnt(1)
	v_lshlrev_b32_e32 v52, 16, v38
	v_and_b32_e32 v53, 0xffff0000, v38
	v_lshlrev_b32_e32 v38, 16, v39
	v_and_b32_e32 v39, 0xffff0000, v39
	s_waitcnt vmcnt(0)
	v_lshlrev_b32_e32 v54, 16, v40
	v_and_b32_e32 v55, 0xffff0000, v40
	v_lshlrev_b32_e32 v40, 16, v41
	v_and_b32_e32 v41, 0xffff0000, v41
	v_pk_fma_f32 v[40:41], v[46:47], v[38:39], v[40:41]
	v_pk_fma_f32 v[38:39], v[32:33], v[52:53], v[54:55]
	global_store_dwordx4 v[48:49], v[38:41], off offset:576
	global_load_dword v46, v[42:43], off
	global_load_dwordx2 v[38:39], v[34:35], off
	v_lshl_add_u64 v[32:33], s[12:13], 0, v[50:51]
	global_load_dwordx2 v[40:41], v[32:33], off
	v_lshl_add_u64 v[32:33], v[44:45], 2, s[14:15]
	s_waitcnt vmcnt(2)
	v_fmamk_f32 v45, v46, 0x3a800000, v158
	s_waitcnt vmcnt(1)
	v_lshlrev_b32_e32 v42, 16, v38
	v_and_b32_e32 v43, 0xffff0000, v38
	v_mul_f32_e32 v38, 0x4b800000, v45
	v_cmp_gt_f32_e32 vcc, s44, v45
	v_lshlrev_b32_e32 v44, 16, v39
	s_waitcnt vmcnt(0)
	v_lshlrev_b32_e32 v46, 16, v40
	v_cndmask_b32_e32 v38, v45, v38, vcc
	v_rsq_f32_e32 v38, v38
	v_and_b32_e32 v45, 0xffff0000, v39
	v_and_b32_e32 v47, 0xffff0000, v40
	v_lshlrev_b32_e32 v40, 16, v41
	v_mul_f32_e32 v39, 0x45800000, v38
	v_cndmask_b32_e32 v38, v38, v39, vcc
	v_mul_f32_e64 v28, v28, -v38
	v_mul_f32_e64 v29, v29, -v38
	v_mul_f32_e32 v28, 0x3fb8aa3b, v28
	v_mul_f32_e32 v29, 0x3fb8aa3b, v29
	v_mul_f32_e64 v30, v30, -v38
	v_mul_f32_e64 v31, v31, -v38
	v_exp_f32_e32 v28, v28
	v_exp_f32_e32 v29, v29
	v_mul_f32_e32 v30, 0x3fb8aa3b, v30
	v_mul_f32_e32 v31, 0x3fb8aa3b, v31
	v_exp_f32_e32 v30, v30
	v_exp_f32_e32 v31, v31
	v_pk_add_f32 v[28:29], v[28:29], 1.0 op_sel_hi:[1,0]
	v_and_b32_e32 v41, 0xffff0000, v41
	v_pk_add_f32 v[30:31], v[30:31], 1.0 op_sel_hi:[1,0]
	v_div_scale_f32 v50, s[4:5], 1.0, v28, 1.0
	v_div_scale_f32 v52, s[6:7], 1.0, v31, 1.0
	v_div_scale_f32 v54, s[8:9], 1.0, v30, 1.0
	s_mov_b64 vcc, s[4:5]
	v_rcp_f32_e32 v29, v29
	s_mov_b64 vcc, s[6:7]
	v_rcp_f32_e32 v28, v28
	s_mov_b64 vcc, s[8:9]
	v_rcp_f32_e32 v31, v31
	v_rcp_f32_e32 v30, v30
	v_pk_fma_f32 v[28:29], v[28:29], v[42:43], v[46:47]
	v_pk_fma_f32 v[30:31], v[30:31], v[44:45], v[40:41]
	global_store_dwordx4 v[32:33], v[28:31], off
	global_load_dwordx2 v[28:29], v[34:35], off offset:32
	v_mul_f32_e64 v24, v24, -v38
	v_lshl_add_u64 v[30:31], v[36:37], 0, v[140:141]
	v_lshl_add_u64 v[30:31], v[30:31], 1, s[12:13]
	global_load_dwordx2 v[30:31], v[30:31], off
	v_mul_f32_e64 v25, v25, -v38
	v_mul_f32_e32 v24, 0x3fb8aa3b, v24
	v_mul_f32_e32 v25, 0x3fb8aa3b, v25
	v_mul_f32_e64 v26, v26, -v38
	v_mul_f32_e64 v27, v27, -v38
	v_exp_f32_e32 v24, v24
	v_exp_f32_e32 v25, v25
	v_mul_f32_e32 v26, 0x3fb8aa3b, v26
	v_mul_f32_e32 v27, 0x3fb8aa3b, v27
	v_exp_f32_e32 v26, v26
	v_exp_f32_e32 v27, v27
	v_pk_add_f32 v[24:25], v[24:25], 1.0 op_sel_hi:[1,0]
	v_mul_f32_e64 v20, v20, -v38
	v_pk_add_f32 v[26:27], v[26:27], 1.0 op_sel_hi:[1,0]
	v_div_scale_f32 v42, s[4:5], 1.0, v24, 1.0
	v_div_scale_f32 v44, s[6:7], 1.0, v27, 1.0
	v_div_scale_f32 v46, s[8:9], 1.0, v26, 1.0
	s_mov_b64 vcc, s[4:5]
	v_rcp_f32_e32 v25, v25
	s_mov_b64 vcc, s[6:7]
	v_rcp_f32_e32 v24, v24
	s_mov_b64 vcc, s[8:9]
	v_rcp_f32_e32 v27, v27
	v_rcp_f32_e32 v26, v26
	v_mul_f32_e64 v21, v21, -v38
	v_mul_f32_e32 v20, 0x3fb8aa3b, v20
	v_mul_f32_e32 v21, 0x3fb8aa3b, v21
	v_mul_f32_e64 v22, v22, -v38
	v_mul_f32_e64 v23, v23, -v38
	v_exp_f32_e32 v20, v20
	s_waitcnt vmcnt(1)
;   DI void operator()(const f32x4 (&acc)[2][2][4][2], const pg8::Unit& u, int wr, int wc, int fr, int fq) const {
;     ...
;         const int row = u.pm * 256 + ai * 128 + wr * 64 + m * 16 + fr; float rs = 0.f;
;         const float rstd = rsqrtf(ssx[row] * (1.f / DM) + EPS);
; #pragma unroll
;         for (int bj = 0; bj < 2; ++bj)
; #pragma unroll
;           for (int n = 0; n < 2; ++n) {
;             const int col = u.pn * 256 + bj * 128 + wc * 32 + n * 16 + fq * 4; const size_t off = (size_t)row * DM + col;
;             f32x4 g;
; #pragma unroll
;             for (int j = 0; j < 4; ++j) g[j] = 1.f / (1.f + __expf(-rstd * acc[ai][bj][m][n][j]));
;             const u32x2 pw = *(const u32x2*)(PT + off); f32x4 pp; pp.x = __uint_as_float(pw.x << 16); pp.y = __uint_as_float(pw.x & 0xffff0000u); pp.z = __uint_as_float(pw.y << 16); pp.w = __uint_as_float(pw.y & 0xffff0000u);
;             const u32x2 xw = *(const u32x2*)(X1B + off); f32x4 x1; x1.x = __uint_as_float(xw.x << 16); x1.y = __uint_as_float(xw.x & 0xffff0000u); x1.z = __uint_as_float(xw.y << 16); x1.w = __uint_as_float(xw.y & 0xffff0000u);
;             const f32x4 xn = x1 + pp * g;
;             if (layer != 0) *(f32x4*)(out + off) = xn;
	v_lshlrev_b32_e32 v40, 16, v28
	v_and_b32_e32 v41, 0xffff0000, v28
	v_lshlrev_b32_e32 v28, 16, v29
	v_and_b32_e32 v29, 0xffff0000, v29
	s_waitcnt vmcnt(0)
	v_lshlrev_b32_e32 v42, 16, v30
	v_and_b32_e32 v43, 0xffff0000, v30
	v_lshlrev_b32_e32 v30, 16, v31
	v_and_b32_e32 v31, 0xffff0000, v31
	v_pk_fma_f32 v[26:27], v[26:27], v[28:29], v[30:31]
	v_pk_fma_f32 v[24:25], v[24:25], v[40:41], v[42:43]
	global_store_dwordx4 v[32:33], v[24:27], off offset:64
	global_load_dwordx2 v[24:25], v[34:35], off offset:256
	v_exp_f32_e32 v21, v21
	v_lshl_add_u64 v[26:27], v[36:37], 0, v[120:121]
	v_lshl_add_u64 v[26:27], v[26:27], 1, s[12:13]
	global_load_dwordx2 v[26:27], v[26:27], off
	v_mul_f32_e32 v22, 0x3fb8aa3b, v22
	v_mul_f32_e32 v23, 0x3fb8aa3b, v23
	v_exp_f32_e32 v22, v22
	v_exp_f32_e32 v23, v23
	v_pk_add_f32 v[20:21], v[20:21], 1.0 op_sel_hi:[1,0]
	v_mul_f32_e64 v16, v16, -v38
	v_pk_add_f32 v[22:23], v[22:23], 1.0 op_sel_hi:[1,0]
	v_div_scale_f32 v39, s[4:5], 1.0, v20, 1.0
	v_div_scale_f32 v41, s[6:7], 1.0, v23, 1.0
	v_div_scale_f32 v43, s[8:9], 1.0, v22, 1.0
	s_mov_b64 vcc, s[4:5]
	v_rcp_f32_e32 v21, v21
	s_mov_b64 vcc, s[6:7]
	v_rcp_f32_e32 v20, v20
	s_mov_b64 vcc, s[8:9]
	v_rcp_f32_e32 v23, v23
	v_rcp_f32_e32 v22, v22
	v_mul_f32_e64 v17, v17, -v38
	v_mul_f32_e32 v16, 0x3fb8aa3b, v16
	v_mul_f32_e32 v17, 0x3fb8aa3b, v17
	v_mul_f32_e64 v18, v18, -v38
	v_mul_f32_e64 v19, v19, -v38
	v_exp_f32_e32 v16, v16
	v_exp_f32_e32 v17, v17
	v_mul_f32_e32 v18, 0x3fb8aa3b, v18
	v_mul_f32_e32 v19, 0x3fb8aa3b, v19
	v_add_u32_e32 v28, 0xb0, v144
	v_pk_add_f32 v[16:17], v[16:17], 1.0 op_sel_hi:[1,0]
	v_ashrrev_i32_e32 v29, 31, v28
	s_waitcnt vmcnt(1)
	v_lshlrev_b32_e32 v30, 16, v24
	v_and_b32_e32 v31, 0xffff0000, v24
	v_lshlrev_b32_e32 v24, 16, v25
	v_and_b32_e32 v25, 0xffff0000, v25
	s_waitcnt vmcnt(0)
	v_lshlrev_b32_e32 v40, 16, v26
	v_and_b32_e32 v41, 0xffff0000, v26
	v_lshlrev_b32_e32 v26, 16, v27
	v_and_b32_e32 v27, 0xffff0000, v27
	v_pk_fma_f32 v[22:23], v[22:23], v[24:25], v[26:27]
	v_pk_fma_f32 v[20:21], v[20:21], v[30:31], v[40:41]
	global_store_dwordx4 v[32:33], v[20:23], off offset:512
	global_load_dwordx2 v[22:23], v[34:35], off offset:288
	v_exp_f32_e32 v30, v18
	v_lshl_add_u64 v[20:21], v[36:37], 0, v[116:117]
	v_lshl_add_u64 v[20:21], v[20:21], 1, s[12:13]
	global_load_dwordx2 v[24:25], v[20:21], off
	v_exp_f32_e32 v31, v19
	s_nop 0
	v_pk_add_f32 v[30:31], v[30:31], 1.0 op_sel_hi:[1,0]
	v_div_scale_f32 v39, s[4:5], 1.0, v16, 1.0
	v_div_scale_f32 v41, s[6:7], 1.0, v31, 1.0
	v_div_scale_f32 v43, s[8:9], 1.0, v30, 1.0
	s_mov_b64 vcc, s[4:5]
	v_rcp_f32_e32 v17, v17
	s_mov_b64 vcc, s[6:7]
	v_rcp_f32_e32 v16, v16
	s_mov_b64 vcc, s[8:9]
	v_rcp_f32_e32 v31, v31
	v_rcp_f32_e32 v30, v30
	v_lshlrev_b64 v[20:21], 10, v[28:29]
	v_lshl_add_u64 v[26:27], v[28:29], 2, s[18:19]
	v_lshl_add_u64 v[28:29], v[20:21], 0, v[142:143]
	v_lshlrev_b64 v[34:35], 1, v[28:29]
	v_lshl_add_u64 v[18:19], s[10:11], 0, v[34:35]
	s_waitcnt vmcnt(1)
	v_lshlrev_b32_e32 v36, 16, v22
	v_and_b32_e32 v37, 0xffff0000, v22
	v_lshlrev_b32_e32 v22, 16, v23
	v_and_b32_e32 v23, 0xffff0000, v23
	s_waitcnt vmcnt(0)
	v_lshlrev_b32_e32 v38, 16, v24
	v_and_b32_e32 v39, 0xffff0000, v24
	v_lshlrev_b32_e32 v24, 16, v25
	v_and_b32_e32 v25, 0xffff0000, v25
	v_pk_fma_f32 v[24:25], v[30:31], v[22:23], v[24:25]
	v_pk_fma_f32 v[22:23], v[16:17], v[36:37], v[38:39]
	global_store_dwordx4 v[32:33], v[22:25], off offset:576
	global_load_dword v30, v[26:27], off
	global_load_dwordx2 v[22:23], v[18:19], off
	v_lshl_add_u64 v[16:17], s[12:13], 0, v[34:35]
	global_load_dwordx2 v[24:25], v[16:17], off
	v_lshl_add_u64 v[16:17], v[28:29], 2, s[14:15]
	s_waitcnt vmcnt(2)
	v_fmamk_f32 v28, v30, 0x3a800000, v158
	v_mul_f32_e32 v29, 0x4b800000, v28
	v_cmp_gt_f32_e32 vcc, s44, v28
	s_waitcnt vmcnt(1)
	v_lshlrev_b32_e32 v26, 16, v22
	v_and_b32_e32 v27, 0xffff0000, v22
	v_cndmask_b32_e32 v28, v28, v29, vcc
	v_rsq_f32_e32 v30, v28
	s_waitcnt vmcnt(0)
; #define PG8_BAR __builtin_amdgcn_s_barrier()
; template <class Epi, class Sched, bool ALIGN_EPI = false, bool SP2 = false>
; __device__ __forceinline__ void gemm_phase(PG8_LAS unsigned char* lds, const Gemm g, const Sched& S, const Epi& E) {
;     ...
;         if constexpr (!Epi::AFTER_DRAIN) { E(acc, cur, wr, wc, fr, fq); S.done(cur); }
;         if (!has_next) break;
; #pragma unroll
;         for (int a = 0; a < 2; ++a)
; #pragma unroll
;             for (int b = 0; b < 2; ++b)
; #pragma unroll
;                 for (int m = 0; m < 4; ++m)
; #pragma unroll
;                     for (int n = 0; n < 2; ++n) acc[a][b][m][n] = (f32x4){0.f, 0.f, 0.f, 0.f};
;         cur = nxt; cA = nA; cB = nB; ++ui;
;         if constexpr (ALIGN_EPI) { if (wr == 1) PG8_BAR; }
;   DI void operator()(const f32x4 (&acc)[2][2][4][2], const pg8::Unit& u, int wr, int wc, int fr, int fq) const {
;     ...
;         const int row = u.pm * 256 + ai * 128 + wr * 64 + m * 16 + fr; float rs = 0.f;
;         const float rstd = rsqrtf(ssx[row] * (1.f / DM) + EPS);
; #pragma unroll
;         for (int bj = 0; bj < 2; ++bj)
; #pragma unroll
;           for (int n = 0; n < 2; ++n) {
;             const int col = u.pn * 256 + bj * 128 + wc * 32 + n * 16 + fq * 4; const size_t off = (size_t)row * DM + col;
;             f32x4 g;
; #pragma unroll
;             for (int j = 0; j < 4; ++j) g[j] = 1.f / (1.f + __expf(-rstd * acc[ai][bj][m][n][j]));
;             const u32x2 pw = *(const u32x2*)(PT + off); f32x4 pp; pp.x = __uint_as_float(pw.x << 16); pp.y = __uint_as_float(pw.x & 0xffff0000u); pp.z = __uint_as_float(pw.y << 16); pp.w = __uint_as_float(pw.y & 0xffff0000u);
;             const u32x2 xw = *(const u32x2*)(X1B + off); f32x4 x1; x1.x = __uint_as_float(xw.x << 16); x1.y = __uint_as_float(xw.x & 0xffff0000u); x1.z = __uint_as_float(xw.y << 16); x1.w = __uint_as_float(xw.y & 0xffff0000u);
;             const f32x4 xn = x1 + pp * g;
;             if (layer != 0) *(f32x4*)(out + off) = xn;
	v_lshlrev_b32_e32 v28, 16, v24
	v_and_b32_e32 v29, 0xffff0000, v24
	v_lshlrev_b32_e32 v22, 16, v23
	v_mul_f32_e32 v24, 0x45800000, v30
	v_cndmask_b32_e32 v30, v30, v24, vcc
	v_mul_f32_e64 v12, v12, -v30
	v_mul_f32_e64 v13, v13, -v30
	v_mul_f32_e32 v12, 0x3fb8aa3b, v12
	v_mul_f32_e32 v13, 0x3fb8aa3b, v13
	v_mul_f32_e64 v14, v14, -v30
	v_mul_f32_e64 v15, v15, -v30
	v_exp_f32_e32 v12, v12
	v_exp_f32_e32 v13, v13
	v_mul_f32_e32 v14, 0x3fb8aa3b, v14
	v_mul_f32_e32 v15, 0x3fb8aa3b, v15
	v_exp_f32_e32 v14, v14
	v_exp_f32_e32 v15, v15
	v_pk_add_f32 v[12:13], v[12:13], 1.0 op_sel_hi:[1,0]
	v_and_b32_e32 v23, 0xffff0000, v23
	v_pk_add_f32 v[14:15], v[14:15], 1.0 op_sel_hi:[1,0]
	v_div_scale_f32 v34, s[4:5], 1.0, v12, 1.0
	v_div_scale_f32 v36, s[6:7], 1.0, v15, 1.0
	v_div_scale_f32 v38, s[8:9], 1.0, v14, 1.0
	s_mov_b64 vcc, s[4:5]
	v_rcp_f32_e32 v13, v13
	s_mov_b64 vcc, s[6:7]
	v_rcp_f32_e32 v12, v12
	s_mov_b64 vcc, s[8:9]
	v_rcp_f32_e32 v15, v15
	v_lshlrev_b32_e32 v24, 16, v25
	v_and_b32_e32 v25, 0xffff0000, v25
	v_rcp_f32_e32 v14, v14
	v_pk_fma_f32 v[12:13], v[12:13], v[26:27], v[28:29]
	v_pk_fma_f32 v[14:15], v[14:15], v[22:23], v[24:25]
	global_store_dwordx4 v[16:17], v[12:15], off
	global_load_dwordx2 v[12:13], v[18:19], off offset:32
	v_mul_f32_e64 v8, v8, -v30
	v_lshl_add_u64 v[14:15], v[20:21], 0, v[140:141]
	v_lshl_add_u64 v[14:15], v[14:15], 1, s[12:13]
	global_load_dwordx2 v[14:15], v[14:15], off
	v_mul_f32_e64 v9, v9, -v30
	v_mul_f32_e32 v8, 0x3fb8aa3b, v8
	v_mul_f32_e32 v9, 0x3fb8aa3b, v9
	v_mul_f32_e64 v10, v10, -v30
	v_mul_f32_e64 v11, v11, -v30
	v_exp_f32_e32 v8, v8
	v_exp_f32_e32 v9, v9
	v_mul_f32_e32 v10, 0x3fb8aa3b, v10
	v_mul_f32_e32 v11, 0x3fb8aa3b, v11
	v_exp_f32_e32 v10, v10
	v_exp_f32_e32 v11, v11
	v_pk_add_f32 v[8:9], v[8:9], 1.0 op_sel_hi:[1,0]
	v_mul_f32_e64 v4, v4, -v30
	v_pk_add_f32 v[10:11], v[10:11], 1.0 op_sel_hi:[1,0]
	v_div_scale_f32 v25, s[4:5], 1.0, v8, 1.0
	v_div_scale_f32 v27, s[6:7], 1.0, v11, 1.0
	v_div_scale_f32 v29, s[8:9], 1.0, v10, 1.0
	s_mov_b64 vcc, s[4:5]
	v_rcp_f32_e32 v9, v9
	s_mov_b64 vcc, s[6:7]
	v_rcp_f32_e32 v8, v8
	s_mov_b64 vcc, s[8:9]
	v_rcp_f32_e32 v11, v11
	v_rcp_f32_e32 v10, v10
	v_mul_f32_e64 v5, v5, -v30
	v_mul_f32_e32 v4, 0x3fb8aa3b, v4
	v_mul_f32_e32 v5, 0x3fb8aa3b, v5
	v_mul_f32_e64 v6, v6, -v30
	v_mul_f32_e64 v7, v7, -v30
	v_exp_f32_e32 v4, v4
	s_waitcnt vmcnt(1)
	v_lshlrev_b32_e32 v22, 16, v12
	v_and_b32_e32 v23, 0xffff0000, v12
	v_lshlrev_b32_e32 v12, 16, v13
	v_and_b32_e32 v13, 0xffff0000, v13
	s_waitcnt vmcnt(0)
	v_lshlrev_b32_e32 v24, 16, v14
	v_and_b32_e32 v25, 0xffff0000, v14
	v_lshlrev_b32_e32 v14, 16, v15
	v_and_b32_e32 v15, 0xffff0000, v15
	v_pk_fma_f32 v[10:11], v[10:11], v[12:13], v[14:15]
	v_pk_fma_f32 v[8:9], v[8:9], v[22:23], v[24:25]
	global_store_dwordx4 v[16:17], v[8:11], off offset:64
	global_load_dwordx2 v[8:9], v[18:19], off offset:256
	v_exp_f32_e32 v5, v5
	v_lshl_add_u64 v[10:11], v[20:21], 0, v[120:121]
	v_lshl_add_u64 v[10:11], v[10:11], 1, s[12:13]
	global_load_dwordx2 v[10:11], v[10:11], off
	v_mul_f32_e32 v6, 0x3fb8aa3b, v6
	v_mul_f32_e32 v7, 0x3fb8aa3b, v7
	v_exp_f32_e32 v6, v6
	v_exp_f32_e32 v7, v7
	v_pk_add_f32 v[4:5], v[4:5], 1.0 op_sel_hi:[1,0]
	v_mul_f32_e64 v0, v0, -v30
	v_pk_add_f32 v[6:7], v[6:7], 1.0 op_sel_hi:[1,0]
	v_div_scale_f32 v15, s[4:5], 1.0, v4, 1.0
	v_div_scale_f32 v23, s[6:7], 1.0, v7, 1.0
	v_div_scale_f32 v25, s[8:9], 1.0, v6, 1.0
	s_mov_b64 vcc, s[4:5]
	v_rcp_f32_e32 v5, v5
	s_mov_b64 vcc, s[6:7]
	v_rcp_f32_e32 v4, v4
	s_mov_b64 vcc, s[8:9]
	v_rcp_f32_e32 v7, v7
	v_rcp_f32_e32 v6, v6
	v_mul_f32_e64 v1, v1, -v30
	v_mul_f32_e32 v0, 0x3fb8aa3b, v0
	v_mul_f32_e32 v1, 0x3fb8aa3b, v1
	v_mul_f32_e64 v2, v2, -v30
	v_mul_f32_e64 v3, v3, -v30
	v_exp_f32_e32 v0, v0
	v_exp_f32_e32 v1, v1
	v_mul_f32_e32 v2, 0x3fb8aa3b, v2
	v_mul_f32_e32 v3, 0x3fb8aa3b, v3
	v_exp_f32_e32 v2, v2
	v_exp_f32_e32 v3, v3
	v_pk_add_f32 v[0:1], v[0:1], 1.0 op_sel_hi:[1,0]
	s_waitcnt vmcnt(1)
	v_lshlrev_b32_e32 v12, 16, v8
	v_and_b32_e32 v13, 0xffff0000, v8
	v_lshlrev_b32_e32 v8, 16, v9
	v_and_b32_e32 v9, 0xffff0000, v9
	s_waitcnt vmcnt(0)
	v_lshlrev_b32_e32 v14, 16, v10
	v_and_b32_e32 v15, 0xffff0000, v10
	v_lshlrev_b32_e32 v10, 16, v11
	v_and_b32_e32 v11, 0xffff0000, v11
	v_pk_fma_f32 v[6:7], v[6:7], v[8:9], v[10:11]
	v_pk_fma_f32 v[4:5], v[4:5], v[12:13], v[14:15]
	global_store_dwordx4 v[16:17], v[4:7], off offset:512
	global_load_dwordx2 v[4:5], v[18:19], off offset:288
	v_lshl_add_u64 v[6:7], v[20:21], 0, v[116:117]
	v_lshl_add_u64 v[6:7], v[6:7], 1, s[12:13]
	global_load_dwordx2 v[6:7], v[6:7], off
	v_pk_add_f32 v[2:3], v[2:3], 1.0 op_sel_hi:[1,0]
	v_div_scale_f32 v11, s[4:5], 1.0, v0, 1.0
	v_div_scale_f32 v13, s[6:7], 1.0, v3, 1.0
	v_div_scale_f32 v15, s[8:9], 1.0, v2, 1.0
	s_mov_b64 vcc, s[4:5]
	v_rcp_f32_e32 v1, v1
	s_mov_b64 vcc, s[6:7]
	v_rcp_f32_e32 v0, v0
	s_mov_b64 vcc, s[8:9]
	v_rcp_f32_e32 v3, v3
	v_rcp_f32_e32 v2, v2
	s_andn2_b64 vcc, exec, s[0:1]
	s_mov_b64 s[0:1], -1
	s_waitcnt vmcnt(1)
	v_lshlrev_b32_e32 v8, 16, v4
	v_and_b32_e32 v9, 0xffff0000, v4
	v_lshlrev_b32_e32 v4, 16, v5
	v_and_b32_e32 v5, 0xffff0000, v5
	s_waitcnt vmcnt(0)
	v_lshlrev_b32_e32 v10, 16, v6
	v_and_b32_e32 v11, 0xffff0000, v6
	v_lshlrev_b32_e32 v6, 16, v7
	v_and_b32_e32 v7, 0xffff0000, v7
	v_pk_fma_f32 v[2:3], v[2:3], v[4:5], v[6:7]
	v_pk_fma_f32 v[0:1], v[0:1], v[8:9], v[10:11]
	global_store_dwordx4 v[16:17], v[0:3], off offset:576
	s_cbranch_vccnz .LBB0_2815
	s_andn2_b64 vcc, exec, s[16:17]
	s_cbranch_vccnz .LBB0_2814
	s_barrier
	s_branch .LBB0_2814
